# merged super-phases + handoff trim: tail SALU hoisted into MFMA shadow, setprio moved off the barrier-to-MFMA path
# speedup vs baseline: 1.0416x; 1.0105x over previous
; #define PG8_STAGE(bufoff, gbase, voff) do { _Pragma("unroll") for (int _i = 0; _i < 2; ++_i) \
;         __builtin_amdgcn_global_load_lds((const unsigned*)((const char*)(gbase) + (voff)[_i]), (PG8_LAS unsigned*)(lds + (bufoff) + ldsw + _i * 8192), 16, 0, 0); } while (0)
; #define PG8_LDA(dst, b, h) do { _Pragma("unroll") for (int m = 0; m < 4; ++m) _Pragma("unroll") for (int k = 0; k < 2; ++k) dst[m][k] = *(const PG8_LAS bf16x8*)(lds + PG8_SA(b, h) + aoff + m * 2048 + k * 1024); } while (0)
; #define PG8_LDB(dst, b, h) do { _Pragma("unroll") for (int n = 0; n < 2; ++n) _Pragma("unroll") for (int k = 0; k < 2; ++k) dst[n][k] = *(const PG8_LAS bf16x8*)(lds + PG8_SB(b, h) + boff + n * 2048 + k * 1024); } while (0)
; #define PG8_WAIT_V(n) asm volatile("s_waitcnt vmcnt(" #n ")" ::: "memory")
; #define PG8_WAIT_L(n) asm volatile("s_waitcnt lgkmcnt(" #n ")" ::: "memory")
; #define PG8_BAR __builtin_amdgcn_s_barrier()
; #define PG8_SCHED __builtin_amdgcn_sched_barrier(0)
; template <class Epi, class Sched>
; __device__ __forceinline__ void gemm_phase(PG8_LAS unsigned char* lds, const Gemm g, const Sched& S, const Epi& E) {
;     ...
;         for (int t = 0; t < nt; t += 2) {
;             const bool last = (t == nt - 2);
;             const char* a1 = cA + (size_t)(t + 1) * kstep;
;             const char* a2 = last ? nA : cA + (size_t)(t + 2) * kstep; const char* b2 = last ? nB : cB + (size_t)(t + 2) * kstep;
;             const char* a3 = a2 + kstep; const char* b3 = b2 + kstep;
;             if (last && has_next) S.a_ready(nxt);
;             PG8_LDB(B0, 0, 0); PG8_SCHED; PG8_LDA(At, 0, 0); PG8_STAGE(PG8_SA(1, 1), a1 + hstep, voffA);
;             PG8_WAIT_L(8); PG8_BAR; PG8_WAIT_L(0); PG8_MMA(0, 0, At, B0); PG8_BAR; PG8_SCHED;
;             PG8_LDB(B1, 0, 1); PG8_STAGE(PG8_SB(0, 0), b2, voffB);
;             PG8_BAR; PG8_WAIT_L(0); PG8_MMA(0, 1, At, B1); PG8_BAR;
;             PG8_LDA(At, 0, 1); PG8_STAGE(PG8_SA(0, 0), a2, voffA);
;             PG8_BAR; PG8_WAIT_L(0); PG8_MMA(1, 0, At, B0); PG8_BAR; PG8_SCHED;
;             PG8_STAGE(PG8_SB(0, 1), b2 + hstep, voffB);
;             PG8_WAIT_V(6); PG8_BAR; PG8_MMA(1, 1, At, B1); PG8_BAR;
;             PG8_LDB(B0, 1, 0); PG8_SCHED; PG8_LDA(At, 1, 0); PG8_STAGE(PG8_SA(0, 1), a2 + hstep, voffA);
;             PG8_WAIT_L(8); PG8_BAR; PG8_WAIT_L(0); PG8_MMA(0, 0, At, B0); PG8_BAR; PG8_SCHED;
.LBB0_235:
	s_setprio 0
	ds_read_b128 v[128:131], v162
	ds_read_b128 v[132:135], v162 offset:1024
	ds_read_b128 v[154:157], v162 offset:2048
	ds_read_b128 v[166:169], v162 offset:3072
	ds_read_b128 v[170:173], v163
	ds_read_b128 v[174:177], v163 offset:1024
	ds_read_b128 v[178:181], v163 offset:2048
	ds_read_b128 v[182:185], v163 offset:3072
	ds_read_b128 v[186:189], v163 offset:4096
	ds_read_b128 v[190:193], v163 offset:5120
	ds_read_b128 v[194:197], v163 offset:6144
	ds_read_b128 v[198:201], v163 offset:7168
	ds_read_b128 v[202:205], v164
	ds_read_b128 v[206:209], v164 offset:1024
	ds_read_b128 v[210:213], v164 offset:2048
	ds_read_b128 v[214:217], v164 offset:3072
	s_add_u32 s10, s68, 0xfff80080
	s_addc_u32 s11, s69, -1
	s_cmp_eq_u32 vcc_hi, 28
	s_cselect_b32 s73, s0, s11
	s_cselect_b32 s72, s5, s10
	s_cselect_b32 s71, s47, vcc_lo
	s_cselect_b32 s70, s49, s97
	v_lshl_add_u64 v[158:159], s[68:69], 0, v[148:149]
	s_add_i32 m0, s67, 0xc000
	s_nop 0
	global_load_lds_dwordx4 v[158:159], off
	v_lshl_add_u64 v[158:159], s[68:69], 0, v[150:151]
	s_add_i32 m0, s67, 0xe000
	s_nop 0
	global_load_lds_dwordx4 v[158:159], off
	s_waitcnt vmcnt(8)
	s_waitcnt lgkmcnt(0)
	s_setprio 1
	s_barrier
	v_mfma_f32_16x16x32_bf16 v[124:127], v[128:131], v[170:173], v[124:127]
	v_mfma_f32_16x16x32_bf16 v[120:123], v[154:157], v[170:173], v[120:123]
	v_mfma_f32_16x16x32_bf16 v[116:119], v[128:131], v[178:181], v[116:119]
	v_mfma_f32_16x16x32_bf16 v[112:115], v[154:157], v[178:181], v[112:115]
	v_mfma_f32_16x16x32_bf16 v[108:111], v[128:131], v[186:189], v[108:111]
	v_mfma_f32_16x16x32_bf16 v[104:107], v[154:157], v[186:189], v[104:107]
	v_mfma_f32_16x16x32_bf16 v[100:103], v[128:131], v[194:197], v[100:103]
	v_mfma_f32_16x16x32_bf16 v[96:99], v[154:157], v[194:197], v[96:99]
	v_mfma_f32_16x16x32_bf16 v[124:127], v[132:135], v[174:177], v[124:127]
	v_mfma_f32_16x16x32_bf16 v[120:123], v[166:169], v[174:177], v[120:123]
	v_mfma_f32_16x16x32_bf16 v[116:119], v[132:135], v[182:185], v[116:119]
	v_mfma_f32_16x16x32_bf16 v[112:115], v[166:169], v[182:185], v[112:115]
	v_mfma_f32_16x16x32_bf16 v[108:111], v[132:135], v[190:193], v[108:111]
	v_mfma_f32_16x16x32_bf16 v[104:107], v[166:169], v[190:193], v[104:107]
	v_mfma_f32_16x16x32_bf16 v[100:103], v[132:135], v[198:201], v[100:103]
	v_mfma_f32_16x16x32_bf16 v[96:99], v[166:169], v[198:201], v[96:99]
	v_mfma_f32_16x16x32_bf16 v[60:63], v[202:205], v[170:173], v[60:63]
	v_mfma_f32_16x16x32_bf16 v[56:59], v[210:213], v[170:173], v[56:59]
	v_mfma_f32_16x16x32_bf16 v[52:55], v[202:205], v[178:181], v[52:55]
	v_mfma_f32_16x16x32_bf16 v[48:51], v[210:213], v[178:181], v[48:51]
	v_mfma_f32_16x16x32_bf16 v[44:47], v[202:205], v[186:189], v[44:47]
	v_mfma_f32_16x16x32_bf16 v[40:43], v[210:213], v[186:189], v[40:43]
	v_mfma_f32_16x16x32_bf16 v[36:39], v[202:205], v[194:197], v[36:39]
	v_mfma_f32_16x16x32_bf16 v[32:35], v[210:213], v[194:197], v[32:35]
	v_mfma_f32_16x16x32_bf16 v[60:63], v[206:209], v[174:177], v[60:63]
	v_mfma_f32_16x16x32_bf16 v[56:59], v[214:217], v[174:177], v[56:59]
	v_mfma_f32_16x16x32_bf16 v[52:55], v[206:209], v[182:185], v[52:55]
	v_mfma_f32_16x16x32_bf16 v[48:51], v[214:217], v[182:185], v[48:51]
	v_mfma_f32_16x16x32_bf16 v[44:47], v[206:209], v[190:193], v[44:47]
	v_mfma_f32_16x16x32_bf16 v[40:43], v[214:217], v[190:193], v[40:43]
	v_mfma_f32_16x16x32_bf16 v[36:39], v[206:209], v[198:201], v[36:39]
	v_mfma_f32_16x16x32_bf16 v[32:35], v[214:217], v[198:201], v[32:35]
	s_barrier
	s_setprio 0
	ds_read_b128 v[170:173], v163 offset:16384
	ds_read_b128 v[174:177], v163 offset:17408
	ds_read_b128 v[178:181], v163 offset:18432
	ds_read_b128 v[182:185], v163 offset:19456
	ds_read_b128 v[186:189], v163 offset:20480
	ds_read_b128 v[190:193], v163 offset:21504
	ds_read_b128 v[194:197], v163 offset:22528
	ds_read_b128 v[198:201], v163 offset:23552
	s_add_i32 s10, s90, s78
	v_lshl_add_u64 v[158:159], s[70:71], 0, v[138:139]
	s_mov_b32 m0, s10
	s_nop 0
	global_load_lds_dwordx4 v[158:159], off
	v_lshl_add_u64 v[218:219], s[70:71], 0, v[142:143]
	s_add_i32 m0, s10, 0x2000
	s_nop 0
	global_load_lds_dwordx4 v[218:219], off
	s_mov_b32 m0, s67
	v_lshl_add_u64 v[220:221], s[72:73], 0, v[136:137]
	global_load_lds_dwordx4 v[220:221], off
	v_lshl_add_u64 v[222:223], s[72:73], 0, v[140:141]
	s_mov_b32 m0, s79
	s_nop 0
	global_load_lds_dwordx4 v[222:223], off
	s_add_u32 s10, s70, 0x80000
	s_addc_u32 s11, s71, 0
	s_add_i32 s33, s91, s78
	v_lshl_add_u64 v[224:225], s[10:11], 0, v[138:139]
	s_mov_b32 m0, s33
	s_nop 0
	global_load_lds_dwordx4 v[224:225], off
	v_lshl_add_u64 v[224:225], s[10:11], 0, v[142:143]
	s_add_i32 m0, s33, 0x2000
	s_nop 0
	global_load_lds_dwordx4 v[224:225], off
	s_waitcnt vmcnt(8)
	s_waitcnt lgkmcnt(0)
	s_setprio 1
	s_barrier
; #define PG8_STAGE(bufoff, gbase, voff) do { _Pragma("unroll") for (int _i = 0; _i < 2; ++_i) \
;         __builtin_amdgcn_global_load_lds((const unsigned*)((const char*)(gbase) + (voff)[_i]), (PG8_LAS unsigned*)(lds + (bufoff) + ldsw + _i * 8192), 16, 0, 0); } while (0)
; #define PG8_LDA(dst, b, h) do { _Pragma("unroll") for (int m = 0; m < 4; ++m) _Pragma("unroll") for (int k = 0; k < 2; ++k) dst[m][k] = *(const PG8_LAS bf16x8*)(lds + PG8_SA(b, h) + aoff + m * 2048 + k * 1024); } while (0)
; #define PG8_LDB(dst, b, h) do { _Pragma("unroll") for (int n = 0; n < 2; ++n) _Pragma("unroll") for (int k = 0; k < 2; ++k) dst[n][k] = *(const PG8_LAS bf16x8*)(lds + PG8_SB(b, h) + boff + n * 2048 + k * 1024); } while (0)
; #define PG8_MMA(ai, bj, At, Bt) do { __builtin_amdgcn_s_setprio(1); _Pragma("unroll") for (int m = 0; m < 4; ++m) _Pragma("unroll") for (int n = 0; n < 2; ++n) _Pragma("unroll") for (int k = 0; k < 2; ++k) \
;         acc[ai][bj][m][n] = __builtin_amdgcn_mfma_f32_16x16x32_bf16(Bt[n][k], At[m][k], acc[ai][bj][m][n], 0, 0, 0); __builtin_amdgcn_s_setprio(0); } while (0)
; template <class Epi, class Sched>
; __device__ __forceinline__ void gemm_phase(PG8_LAS unsigned char* lds, const Gemm g, const Sched& S, const Epi& E) {
;     ...
;             PG8_LDB(B0, 0, 0); PG8_SCHED; PG8_LDA(At, 0, 0); PG8_STAGE(PG8_SA(1, 1), a1 + hstep, voffA);
;             PG8_WAIT_L(8); PG8_BAR; PG8_WAIT_L(0); PG8_MMA(0, 0, At, B0); PG8_BAR; PG8_SCHED;
;             PG8_LDB(B1, 0, 1); PG8_STAGE(PG8_SB(0, 0), b2, voffB);
;             PG8_BAR; PG8_WAIT_L(0); PG8_MMA(0, 1, At, B1); PG8_BAR;
;             PG8_LDA(At, 0, 1); PG8_STAGE(PG8_SA(0, 0), a2, voffA);
;             PG8_BAR; PG8_WAIT_L(0); PG8_MMA(1, 0, At, B0); PG8_BAR; PG8_SCHED;
;             PG8_STAGE(PG8_SB(0, 1), b2 + hstep, voffB);
;             PG8_WAIT_V(6); PG8_BAR; PG8_MMA(1, 1, At, B1); PG8_BAR;
;             PG8_LDB(B0, 1, 0); PG8_SCHED; PG8_LDA(At, 1, 0); PG8_STAGE(PG8_SA(0, 1), a2 + hstep, voffA);
;             PG8_WAIT_L(8); PG8_BAR; PG8_WAIT_L(0); PG8_MMA(0, 0, At, B0); PG8_BAR; PG8_SCHED;
;             PG8_LDB(B1, 1, 1); PG8_STAGE(PG8_SB(1, 0), b3, voffB);
;             PG8_BAR; PG8_WAIT_L(0); PG8_MMA(0, 1, At, B1); PG8_BAR;
;             PG8_LDA(At, 1, 1); PG8_STAGE(PG8_SA(1, 0), a3, voffA);
;             PG8_BAR; PG8_WAIT_L(0); PG8_MMA(1, 0, At, B0); PG8_BAR; PG8_SCHED;
	v_mfma_f32_16x16x32_bf16 v[92:95], v[128:131], v[170:173], v[92:95]
	v_mfma_f32_16x16x32_bf16 v[88:91], v[154:157], v[170:173], v[88:91]
	v_mfma_f32_16x16x32_bf16 v[84:87], v[128:131], v[178:181], v[84:87]
	v_mfma_f32_16x16x32_bf16 v[80:83], v[154:157], v[178:181], v[80:83]
	v_mfma_f32_16x16x32_bf16 v[76:79], v[128:131], v[186:189], v[76:79]
	v_mfma_f32_16x16x32_bf16 v[72:75], v[154:157], v[186:189], v[72:75]
	v_mfma_f32_16x16x32_bf16 v[68:71], v[128:131], v[194:197], v[68:71]
	v_mfma_f32_16x16x32_bf16 v[64:67], v[154:157], v[194:197], v[64:67]
	s_add_i32 s33, 0, 0x18000
	v_add_u32_e32 v144, s33, v160
	v_mfma_f32_16x16x32_bf16 v[92:95], v[132:135], v[174:177], v[92:95]
	v_mfma_f32_16x16x32_bf16 v[88:91], v[166:169], v[174:177], v[88:91]
	v_mfma_f32_16x16x32_bf16 v[84:87], v[132:135], v[182:185], v[84:87]
	v_mfma_f32_16x16x32_bf16 v[80:83], v[166:169], v[182:185], v[80:83]
	v_mfma_f32_16x16x32_bf16 v[76:79], v[132:135], v[190:193], v[76:79]
	v_mfma_f32_16x16x32_bf16 v[72:75], v[166:169], v[190:193], v[72:75]
	v_mfma_f32_16x16x32_bf16 v[68:71], v[132:135], v[198:201], v[68:71]
	v_mfma_f32_16x16x32_bf16 v[64:67], v[166:169], v[198:201], v[64:67]
	v_mfma_f32_16x16x32_bf16 v[28:31], v[202:205], v[170:173], v[28:31]
	v_mfma_f32_16x16x32_bf16 v[24:27], v[210:213], v[170:173], v[24:27]
	v_mfma_f32_16x16x32_bf16 v[20:23], v[202:205], v[178:181], v[20:23]
	v_mfma_f32_16x16x32_bf16 v[16:19], v[210:213], v[178:181], v[16:19]
	v_mfma_f32_16x16x32_bf16 v[12:15], v[202:205], v[186:189], v[12:15]
	v_mfma_f32_16x16x32_bf16 v[8:11], v[210:213], v[186:189], v[8:11]
	v_mfma_f32_16x16x32_bf16 v[4:7], v[202:205], v[194:197], v[4:7]
	v_mfma_f32_16x16x32_bf16 v[0:3], v[210:213], v[194:197], v[0:3]
	v_mfma_f32_16x16x32_bf16 v[28:31], v[206:209], v[174:177], v[28:31]
	v_mfma_f32_16x16x32_bf16 v[24:27], v[214:217], v[174:177], v[24:27]
	v_mfma_f32_16x16x32_bf16 v[20:23], v[206:209], v[182:185], v[20:23]
	v_mfma_f32_16x16x32_bf16 v[16:19], v[214:217], v[182:185], v[16:19]
	v_mfma_f32_16x16x32_bf16 v[12:15], v[206:209], v[190:193], v[12:15]
	v_mfma_f32_16x16x32_bf16 v[8:11], v[214:217], v[190:193], v[8:11]
	v_mfma_f32_16x16x32_bf16 v[4:7], v[206:209], v[198:201], v[4:7]
	v_mfma_f32_16x16x32_bf16 v[0:3], v[214:217], v[198:201], v[0:3]
	s_barrier
	s_setprio 0
	ds_read_b128 v[128:131], v162 offset:32768
	ds_read_b128 v[132:135], v162 offset:33792
	ds_read_b128 v[154:157], v162 offset:34816
	ds_read_b128 v[166:169], v162 offset:35840
	ds_read_b128 v[170:173], v163 offset:32768
	ds_read_b128 v[174:177], v163 offset:33792
	ds_read_b128 v[178:181], v163 offset:34816
	ds_read_b128 v[182:185], v163 offset:35840
	ds_read_b128 v[186:189], v163 offset:36864
	ds_read_b128 v[190:193], v163 offset:37888
	ds_read_b128 v[194:197], v163 offset:38912
	ds_read_b128 v[198:201], v163 offset:39936
	ds_read_b128 v[202:205], v164 offset:32768
	ds_read_b128 v[206:209], v164 offset:33792
	ds_read_b128 v[210:213], v164 offset:34816
	ds_read_b128 v[214:217], v164 offset:35840
	s_add_u32 s10, s72, 0x80000
	s_addc_u32 s11, s73, 0
	s_mov_b32 m0, s80
	v_lshl_add_u64 v[224:225], s[10:11], 0, v[136:137]
	global_load_lds_dwordx4 v[224:225], off
	v_lshl_add_u64 v[224:225], s[10:11], 0, v[140:141]
	s_mov_b32 m0, s81
	s_nop 0
	global_load_lds_dwordx4 v[224:225], off
	s_waitcnt vmcnt(8)
	s_waitcnt lgkmcnt(0)
	s_setprio 1
	s_barrier
	v_mfma_f32_16x16x32_bf16 v[124:127], v[128:131], v[170:173], v[124:127]
	v_mfma_f32_16x16x32_bf16 v[120:123], v[154:157], v[170:173], v[120:123]
	v_mfma_f32_16x16x32_bf16 v[116:119], v[128:131], v[178:181], v[116:119]
	v_mfma_f32_16x16x32_bf16 v[112:115], v[154:157], v[178:181], v[112:115]
	v_mfma_f32_16x16x32_bf16 v[108:111], v[128:131], v[186:189], v[108:111]
	v_mfma_f32_16x16x32_bf16 v[104:107], v[154:157], v[186:189], v[104:107]
	v_mfma_f32_16x16x32_bf16 v[100:103], v[128:131], v[194:197], v[100:103]
	v_mfma_f32_16x16x32_bf16 v[96:99], v[154:157], v[194:197], v[96:99]
	v_mfma_f32_16x16x32_bf16 v[124:127], v[132:135], v[174:177], v[124:127]
	v_mfma_f32_16x16x32_bf16 v[120:123], v[166:169], v[174:177], v[120:123]
	v_mfma_f32_16x16x32_bf16 v[116:119], v[132:135], v[182:185], v[116:119]
	v_mfma_f32_16x16x32_bf16 v[112:115], v[166:169], v[182:185], v[112:115]
	v_mfma_f32_16x16x32_bf16 v[108:111], v[132:135], v[190:193], v[108:111]
	v_mfma_f32_16x16x32_bf16 v[104:107], v[166:169], v[190:193], v[104:107]
	v_mfma_f32_16x16x32_bf16 v[100:103], v[132:135], v[198:201], v[100:103]
	v_mfma_f32_16x16x32_bf16 v[96:99], v[166:169], v[198:201], v[96:99]
	v_mfma_f32_16x16x32_bf16 v[60:63], v[202:205], v[170:173], v[60:63]
	v_mfma_f32_16x16x32_bf16 v[56:59], v[210:213], v[170:173], v[56:59]
	v_mfma_f32_16x16x32_bf16 v[52:55], v[202:205], v[178:181], v[52:55]
	v_mfma_f32_16x16x32_bf16 v[48:51], v[210:213], v[178:181], v[48:51]
	v_mfma_f32_16x16x32_bf16 v[44:47], v[202:205], v[186:189], v[44:47]
	v_mfma_f32_16x16x32_bf16 v[40:43], v[210:213], v[186:189], v[40:43]
	v_mfma_f32_16x16x32_bf16 v[36:39], v[202:205], v[194:197], v[36:39]
	v_mfma_f32_16x16x32_bf16 v[32:35], v[210:213], v[194:197], v[32:35]
	v_mfma_f32_16x16x32_bf16 v[60:63], v[206:209], v[174:177], v[60:63]
	v_mfma_f32_16x16x32_bf16 v[56:59], v[214:217], v[174:177], v[56:59]
	v_mfma_f32_16x16x32_bf16 v[52:55], v[206:209], v[182:185], v[52:55]
	v_mfma_f32_16x16x32_bf16 v[48:51], v[214:217], v[182:185], v[48:51]
	v_mfma_f32_16x16x32_bf16 v[44:47], v[206:209], v[190:193], v[44:47]
	v_mfma_f32_16x16x32_bf16 v[40:43], v[214:217], v[190:193], v[40:43]
	v_mfma_f32_16x16x32_bf16 v[36:39], v[206:209], v[198:201], v[36:39]
	v_mfma_f32_16x16x32_bf16 v[32:35], v[214:217], v[198:201], v[32:35]
	s_barrier
; template <class Epi, class Sched>
; __device__ __forceinline__ void gemm_phase(PG8_LAS unsigned char* lds, const Gemm g, const Sched& S, const Epi& E) {
;     ...
;             PG8_WAIT_V(6); PG8_BAR; PG8_MMA(1, 1, At, B1); PG8_BAR;
;             PG8_LDB(B0, 1, 0); PG8_SCHED; PG8_LDA(At, 1, 0); PG8_STAGE(PG8_SA(0, 1), a2 + hstep, voffA);
;             PG8_WAIT_L(8); PG8_BAR; PG8_WAIT_L(0); PG8_MMA(0, 0, At, B0); PG8_BAR; PG8_SCHED;
;             PG8_LDB(B1, 1, 1); PG8_STAGE(PG8_SB(1, 0), b3, voffB);
;             PG8_BAR; PG8_WAIT_L(0); PG8_MMA(0, 1, At, B1); PG8_BAR;
;             PG8_LDA(At, 1, 1); PG8_STAGE(PG8_SA(1, 0), a3, voffA);
;             PG8_BAR; PG8_WAIT_L(0); PG8_MMA(1, 0, At, B0); PG8_BAR; PG8_SCHED;
;             PG8_STAGE(PG8_SB(1, 1), b3 + hstep, voffB);
;             PG8_WAIT_V(6); PG8_BAR; PG8_MMA(1, 1, At, B1); PG8_BAR;
;         }
;         E(acc, cur, wr, wc, fr, fq); S.done(cur);
;     __device__ __forceinline__ void operator()(const AccT& acc, const pg8::Unit& u, int wr, int wc, int fr, int fq) const {
;         const int row0 = u.pm * 256 + wr * 64 + fr, cl = wc * 32 + 8 * fq, pn = u.pn;
;         if (pn < 8) {
; #pragma unroll
;             for (int bj = 0; bj < 2; ++bj) {
;                 const int col = pn * 256 + bj * 128 + cl;
;                 const f32x4 l0 = *(const f32x4*)(lb + col), l1 = *(const f32x4*)(lb + col + 4);
; #pragma unroll
;                 for (int ai = 0; ai < 2; ++ai)
; #pragma unroll
;                     for (int m = 0; m < 4; ++m) {
;                         const f32x4 a = acc[ai][bj][m][0], b = acc[ai][bj][m][1]; float g[8];
; #pragma unroll
;                         for (int j = 0; j < 4; ++j) { g[j] = (1.f - l0[j]) * __builtin_amdgcn_rcpf(1.f + __expf(a[j])); g[4 + j] = (1.f - l1[j]) * __builtin_amdgcn_rcpf(1.f + __expf(b[j])); }
;                         u32x4 w; w.x = pk_h2(g[0], g[1]); w.y = pk_h2(g[2], g[3]); w.z = pk_h2(g[4], g[5]); w.w = pk_h2(g[6], g[7]);
;                         *(u32x4*)(G + (size_t)(row0 + ai * 128 + m * 16) * 2048 + col) = w;
;                     }
;             }
;         } else if (pn < 24) {
;             if (u.pm >= 128 && pn >= 12) return;
;             const int ty = (pn - 8) >> 2; bf16_t* base = V + (ty == 0 ? (size_t)0 : (size_t)TALL * HW + (size_t)(ty - 1) * T * HW);
;             const bool act = (ty == 1);
;             const int colt = (pn - 8 - 4 * ty) * 256;
	s_setprio 0
	ds_read_b128 v[170:173], v163 offset:49152
	ds_read_b128 v[174:177], v163 offset:50176
	ds_read_b128 v[178:181], v163 offset:51200
	ds_read_b128 v[182:185], v163 offset:52224
	ds_read_b128 v[186:189], v163 offset:53248
	ds_read_b128 v[190:193], v163 offset:54272
	ds_read_b128 v[194:197], v163 offset:55296
	ds_read_b128 v[198:201], v163 offset:56320
	s_add_i32 s72, 0, 0x1c000
	s_add_i32 s10, s33, s78
	v_add_u32_e32 v144, s72, v160
	v_lshl_add_u64 v[158:159], v[158:159], 0, s[26:27]
	s_mov_b32 m0, s10
	s_nop 0
	global_load_lds_dwordx4 v[158:159], off
	v_lshl_add_u64 v[158:159], v[218:219], 0, s[26:27]
	s_add_i32 m0, s10, 0x2000
	s_nop 0
	global_load_lds_dwordx4 v[158:159], off
	s_mov_b32 m0, s84
	v_lshl_add_u64 v[158:159], v[220:221], 0, s[26:27]
	global_load_lds_dwordx4 v[158:159], off
	v_lshl_add_u64 v[158:159], v[222:223], 0, s[26:27]
	s_mov_b32 m0, s85
	s_nop 0
	global_load_lds_dwordx4 v[158:159], off
	s_add_u32 s10, s70, 0x80080
	s_addc_u32 s11, s71, 0
	s_add_i32 s33, s72, s78
	v_lshl_add_u64 v[224:225], s[10:11], 0, v[138:139]
	s_mov_b32 m0, s33
	s_nop 0
	global_load_lds_dwordx4 v[224:225], off
	v_lshl_add_u64 v[224:225], s[10:11], 0, v[142:143]
	s_add_i32 m0, s33, 0x2000
	s_nop 0
	global_load_lds_dwordx4 v[224:225], off
	s_waitcnt vmcnt(8)
	s_waitcnt lgkmcnt(0)
	s_setprio 1
	s_barrier
	v_mfma_f32_16x16x32_bf16 v[92:95], v[128:131], v[170:173], v[92:95]
	v_mfma_f32_16x16x32_bf16 v[88:91], v[154:157], v[170:173], v[88:91]
	v_mfma_f32_16x16x32_bf16 v[84:87], v[128:131], v[178:181], v[84:87]
	v_mfma_f32_16x16x32_bf16 v[80:83], v[154:157], v[178:181], v[80:83]
	v_mfma_f32_16x16x32_bf16 v[76:79], v[128:131], v[186:189], v[76:79]
	v_mfma_f32_16x16x32_bf16 v[72:75], v[154:157], v[186:189], v[72:75]
	v_mfma_f32_16x16x32_bf16 v[68:71], v[128:131], v[194:197], v[68:71]
	v_mfma_f32_16x16x32_bf16 v[64:67], v[154:157], v[194:197], v[64:67]
	s_add_i32 vcc_hi, vcc_hi, 2
	s_add_u32 s68, s68, 0x100
	s_addc_u32 s69, s69, 0
	s_add_u32 s97, s97, 0x100
	s_addc_u32 vcc_lo, vcc_lo, 0
	s_cmp_gt_u32 vcc_hi, 29
	v_mfma_f32_16x16x32_bf16 v[92:95], v[132:135], v[174:177], v[92:95]
	v_mfma_f32_16x16x32_bf16 v[88:91], v[166:169], v[174:177], v[88:91]
	v_mfma_f32_16x16x32_bf16 v[84:87], v[132:135], v[182:185], v[84:87]
	v_mfma_f32_16x16x32_bf16 v[80:83], v[166:169], v[182:185], v[80:83]
	v_mfma_f32_16x16x32_bf16 v[76:79], v[132:135], v[190:193], v[76:79]
	v_mfma_f32_16x16x32_bf16 v[72:75], v[166:169], v[190:193], v[72:75]
	v_mfma_f32_16x16x32_bf16 v[68:71], v[132:135], v[198:201], v[68:71]
	v_mfma_f32_16x16x32_bf16 v[64:67], v[166:169], v[198:201], v[64:67]
	v_mfma_f32_16x16x32_bf16 v[28:31], v[202:205], v[170:173], v[28:31]
	v_mfma_f32_16x16x32_bf16 v[24:27], v[210:213], v[170:173], v[24:27]
	v_mfma_f32_16x16x32_bf16 v[20:23], v[202:205], v[178:181], v[20:23]
	v_mfma_f32_16x16x32_bf16 v[16:19], v[210:213], v[178:181], v[16:19]
	v_mfma_f32_16x16x32_bf16 v[12:15], v[202:205], v[186:189], v[12:15]
	v_mfma_f32_16x16x32_bf16 v[8:11], v[210:213], v[186:189], v[8:11]
	v_mfma_f32_16x16x32_bf16 v[4:7], v[202:205], v[194:197], v[4:7]
	v_mfma_f32_16x16x32_bf16 v[0:3], v[210:213], v[194:197], v[0:3]
	v_mfma_f32_16x16x32_bf16 v[28:31], v[206:209], v[174:177], v[28:31]
	v_mfma_f32_16x16x32_bf16 v[24:27], v[214:217], v[174:177], v[24:27]
	v_mfma_f32_16x16x32_bf16 v[20:23], v[206:209], v[182:185], v[20:23]
	v_mfma_f32_16x16x32_bf16 v[16:19], v[214:217], v[182:185], v[16:19]
	v_mfma_f32_16x16x32_bf16 v[12:15], v[206:209], v[190:193], v[12:15]
	v_mfma_f32_16x16x32_bf16 v[8:11], v[214:217], v[190:193], v[8:11]
	v_mfma_f32_16x16x32_bf16 v[4:7], v[206:209], v[198:201], v[4:7]
	v_mfma_f32_16x16x32_bf16 v[0:3], v[214:217], v[198:201], v[0:3]
	s_barrier
	s_cbranch_scc0 .LBB0_235
	s_setprio 0
	v_lshl_add_u32 v154, s4, 8, v147
	s_cmp_gt_i32 s66, 7
	s_mov_b64 s[68:69], -1
	s_cbranch_scc0 .LBB0_277
	s_cmpk_gt_i32 s4, 0x7f
	s_cselect_b64 s[68:69], -1, 0
	s_cmpk_lt_i32 s4, 0x80
	s_cselect_b64 s[70:71], -1, 0
	s_cmp_gt_u32 s66, 23
	s_mov_b64 s[4:5], -1
	s_cbranch_scc0 .LBB0_241
	s_andn2_b64 vcc, exec, s[70:71]
	s_cbranch_vccnz .LBB0_240
; __device__ __forceinline__ unsigned cvt_pk_bf16(float lo, float hi) { const bf16v2_t v = __builtin_convertvector((f32x2){lo, hi}, bf16v2_t); return __builtin_bit_cast(unsigned, v); }
;     __device__ __forceinline__ void operator()(const AccT& acc, const pg8::Unit& u, int wr, int wc, int fr, int fq) const {
;     ...
;             if (u.pm >= 128) return;
;             const int col = (pn - 24) * 128 + cl;
; #pragma unroll
;             for (int ai = 0; ai < 2; ++ai)
; #pragma unroll
;                 for (int m = 0; m < 4; ++m) {
;                     const f32x4 a = acc[ai][0][m][0] * acc[ai][1][m][0], b = acc[ai][0][m][1] * acc[ai][1][m][1];
;                     u32x4 w; w.x = cvt_pk_bf16(a[0], a[1]); w.y = cvt_pk_bf16(a[2], a[3]); w.z = cvt_pk_bf16(b[0], b[1]); w.w = cvt_pk_bf16(b[2], b[3]);
;                     *(u32x4*)(P + (size_t)(row0 + ai * 128 + m * 16) * 1024 + col) = w;
;                 }
	v_pk_mul_f32 v[130:131], v[126:127], v[62:63]
	v_pk_mul_f32 v[128:129], v[124:125], v[60:61]
	v_pk_mul_f32 v[132:133], v[122:123], v[58:59]
	v_ashrrev_i32_e32 v155, 31, v154
	v_lshl_add_u32 v144, s66, 7, v161
	v_pk_mul_f32 v[134:135], v[120:121], v[56:57]
	v_cvt_pk_bf16_f32 v128, v128, v129
	v_cvt_pk_bf16_f32 v129, v130, v131
	v_cvt_pk_bf16_f32 v131, v132, v133
	v_lshlrev_b64 v[132:133], 11, v[154:155]
	v_cvt_pk_bf16_f32 v130, v134, v135
	v_lshl_add_u64 v[132:133], s[8:9], 0, v[132:133]
	v_lshlrev_b64 v[134:135], 1, v[144:145]
	v_lshl_add_u64 v[132:133], v[132:133], 0, v[134:135]
	global_store_dwordx4 v[132:133], v[128:131], off
	v_pk_mul_f32 v[156:157], v[114:115], v[50:51]
	v_pk_mul_f32 v[158:159], v[112:113], v[48:49]
	v_pk_mul_f32 v[130:131], v[118:119], v[54:55]
	v_pk_mul_f32 v[128:129], v[116:117], v[52:53]
	s_mov_b32 s0, 0x40000
	v_cvt_pk_bf16_f32 v128, v128, v129
	v_cvt_pk_bf16_f32 v129, v130, v131
	v_cvt_pk_bf16_f32 v131, v156, v157
	v_or_b32_e32 v156, 16, v154
	v_ashrrev_i32_e32 v157, 31, v156
	v_lshlrev_b64 v[156:157], 11, v[156:157]
	v_lshl_add_u64 v[156:157], s[8:9], 0, v[156:157]
	v_cvt_pk_bf16_f32 v130, v158, v159
	v_lshl_add_u64 v[156:157], v[156:157], 0, v[134:135]
	global_store_dwordx4 v[156:157], v[128:131], off
	v_pk_mul_f32 v[156:157], v[106:107], v[42:43]
	v_pk_mul_f32 v[158:159], v[104:105], v[40:41]
	v_pk_mul_f32 v[130:131], v[110:111], v[46:47]
	v_pk_mul_f32 v[128:129], v[108:109], v[44:45]
	s_nop 0
	v_cvt_pk_bf16_f32 v128, v128, v129
	v_cvt_pk_bf16_f32 v129, v130, v131
	v_cvt_pk_bf16_f32 v131, v156, v157
	v_or_b32_e32 v156, 32, v154
	v_ashrrev_i32_e32 v157, 31, v156
	v_lshlrev_b64 v[156:157], 11, v[156:157]
	v_lshl_add_u64 v[156:157], s[8:9], 0, v[156:157]
	v_cvt_pk_bf16_f32 v130, v158, v159
	v_lshl_add_u64 v[156:157], v[156:157], 0, v[134:135]
	global_store_dwordx4 v[156:157], v[128:131], off
	v_pk_mul_f32 v[156:157], v[98:99], v[34:35]
	v_pk_mul_f32 v[158:159], v[96:97], v[32:33]
	v_pk_mul_f32 v[130:131], v[102:103], v[38:39]
	v_pk_mul_f32 v[128:129], v[100:101], v[36:37]
	s_nop 0
	v_cvt_pk_bf16_f32 v128, v128, v129
	v_cvt_pk_bf16_f32 v129, v130, v131
	v_cvt_pk_bf16_f32 v131, v156, v157
	v_or_b32_e32 v156, 48, v154
	v_ashrrev_i32_e32 v157, 31, v156
	v_lshlrev_b64 v[156:157], 11, v[156:157]
	v_lshl_add_u64 v[156:157], s[8:9], 0, v[156:157]
	v_cvt_pk_bf16_f32 v130, v158, v159
	v_lshl_add_u64 v[134:135], v[156:157], 0, v[134:135]
	global_store_dwordx4 v[134:135], v[128:131], off
	v_pk_mul_f32 v[134:135], v[90:91], v[26:27]
	v_pk_mul_f32 v[156:157], v[88:89], v[24:25]
	v_pk_mul_f32 v[130:131], v[94:95], v[30:31]
	v_pk_mul_f32 v[128:129], v[92:93], v[28:29]
	s_nop 0
	v_cvt_pk_bf16_f32 v128, v128, v129
	v_cvt_pk_bf16_f32 v129, v130, v131
	v_cvt_pk_bf16_f32 v131, v134, v135
	v_add_co_u32_e32 v134, vcc, s0, v132
	v_cvt_pk_bf16_f32 v130, v156, v157
	s_nop 0
	v_addc_co_u32_e32 v135, vcc, 0, v133, vcc
	global_store_dwordx4 v[134:135], v[128:131], off
	v_pk_mul_f32 v[134:135], v[82:83], v[18:19]
	s_mov_b32 s0, 0x48000
	v_pk_mul_f32 v[130:131], v[86:87], v[22:23]
	v_pk_mul_f32 v[128:129], v[84:85], v[20:21]
	v_pk_mul_f32 v[156:157], v[80:81], v[16:17]
	v_cvt_pk_bf16_f32 v128, v128, v129
	v_cvt_pk_bf16_f32 v129, v130, v131
	v_cvt_pk_bf16_f32 v131, v134, v135
	v_add_co_u32_e32 v134, vcc, s0, v132
	v_cvt_pk_bf16_f32 v130, v156, v157
	s_nop 0
	v_addc_co_u32_e32 v135, vcc, 0, v133, vcc
	global_store_dwordx4 v[134:135], v[128:131], off
	v_pk_mul_f32 v[134:135], v[74:75], v[10:11]
	s_mov_b32 s0, 0x50000
	v_pk_mul_f32 v[130:131], v[78:79], v[14:15]
	v_pk_mul_f32 v[128:129], v[76:77], v[12:13]
	v_pk_mul_f32 v[156:157], v[72:73], v[8:9]
	v_cvt_pk_bf16_f32 v128, v128, v129
	v_cvt_pk_bf16_f32 v129, v130, v131
	v_cvt_pk_bf16_f32 v131, v134, v135
	v_add_co_u32_e32 v134, vcc, s0, v132
	v_cvt_pk_bf16_f32 v130, v156, v157
	s_nop 0
	v_addc_co_u32_e32 v135, vcc, 0, v133, vcc
	global_store_dwordx4 v[134:135], v[128:131], off
	v_pk_mul_f32 v[134:135], v[66:67], v[2:3]
	v_pk_mul_f32 v[156:157], v[64:65], v[0:1]
	v_pk_mul_f32 v[130:131], v[70:71], v[6:7]
	v_pk_mul_f32 v[128:129], v[68:69], v[4:5]
	v_add_co_u32_e32 v132, vcc, 0x58000, v132
	v_cvt_pk_bf16_f32 v128, v128, v129
	v_cvt_pk_bf16_f32 v129, v130, v131
	v_cvt_pk_bf16_f32 v130, v156, v157
	v_cvt_pk_bf16_f32 v131, v134, v135
	v_addc_co_u32_e32 v133, vcc, 0, v133, vcc
	global_store_dwordx4 v[132:133], v[128:131], off

; #define PG8_STAGE(bufoff, gbase, voff) do { _Pragma("unroll") for (int _i = 0; _i < 2; ++_i) \
;         __builtin_amdgcn_global_load_lds((const unsigned*)((const char*)(gbase) + (voff)[_i]), (PG8_LAS unsigned*)(lds + (bufoff) + ldsw + _i * 8192), 16, 0, 0); } while (0)
; #define PG8_LDA(dst, b, h) do { _Pragma("unroll") for (int m = 0; m < 4; ++m) _Pragma("unroll") for (int k = 0; k < 2; ++k) dst[m][k] = *(const PG8_LAS bf16x8*)(lds + PG8_SA(b, h) + aoff + m * 2048 + k * 1024); } while (0)
; #define PG8_LDB(dst, b, h) do { _Pragma("unroll") for (int n = 0; n < 2; ++n) _Pragma("unroll") for (int k = 0; k < 2; ++k) dst[n][k] = *(const PG8_LAS bf16x8*)(lds + PG8_SB(b, h) + boff + n * 2048 + k * 1024); } while (0)
; #define PG8_WAIT_V(n) asm volatile("s_waitcnt vmcnt(" #n ")" ::: "memory")
; #define PG8_WAIT_L(n) asm volatile("s_waitcnt lgkmcnt(" #n ")" ::: "memory")
; #define PG8_BAR __builtin_amdgcn_s_barrier()
; #define PG8_SCHED __builtin_amdgcn_sched_barrier(0)
; template <class Epi, class Sched>
; __device__ __forceinline__ void gemm_phase(PG8_LAS unsigned char* lds, const Gemm g, const Sched& S, const Epi& E) {
;     ...
;         for (int t = 0; t < nt; t += 2) {
;             const bool last = (t == nt - 2);
;             const char* a1 = cA + (size_t)(t + 1) * kstep;
;             const char* a2 = last ? nA : cA + (size_t)(t + 2) * kstep; const char* b2 = last ? nB : cB + (size_t)(t + 2) * kstep;
;             const char* a3 = a2 + kstep; const char* b3 = b2 + kstep;
;             if (last && has_next) S.a_ready(nxt);
;             PG8_LDB(B0, 0, 0); PG8_SCHED; PG8_LDA(At, 0, 0); PG8_STAGE(PG8_SA(1, 1), a1 + hstep, voffA);
;             PG8_WAIT_L(8); PG8_BAR; PG8_WAIT_L(0); PG8_MMA(0, 0, At, B0); PG8_BAR; PG8_SCHED;
;             PG8_LDB(B1, 0, 1); PG8_STAGE(PG8_SB(0, 0), b2, voffB);
;             PG8_BAR; PG8_WAIT_L(0); PG8_MMA(0, 1, At, B1); PG8_BAR;
;             PG8_LDA(At, 0, 1); PG8_STAGE(PG8_SA(0, 0), a2, voffA);
;             PG8_BAR; PG8_WAIT_L(0); PG8_MMA(1, 0, At, B0); PG8_BAR; PG8_SCHED;
;             PG8_STAGE(PG8_SB(0, 1), b2 + hstep, voffB);
;             PG8_WAIT_V(6); PG8_BAR; PG8_MMA(1, 1, At, B1); PG8_BAR;
;             PG8_LDB(B0, 1, 0); PG8_SCHED; PG8_LDA(At, 1, 0); PG8_STAGE(PG8_SA(0, 1), a2 + hstep, voffA);
;             PG8_WAIT_L(8); PG8_BAR; PG8_WAIT_L(0); PG8_MMA(0, 0, At, B0); PG8_BAR; PG8_SCHED;
.LBB0_666:
	s_setprio 0
	ds_read_b128 v[128:131], v169
	ds_read_b128 v[132:135], v169 offset:1024
	ds_read_b128 v[136:139], v169 offset:2048
	ds_read_b128 v[140:143], v169 offset:3072
	ds_read_b128 v[160:163], v170
	ds_read_b128 v[172:175], v170 offset:1024
	ds_read_b128 v[176:179], v170 offset:2048
	ds_read_b128 v[180:183], v170 offset:3072
	ds_read_b128 v[184:187], v170 offset:4096
	ds_read_b128 v[188:191], v170 offset:5120
	ds_read_b128 v[192:195], v170 offset:6144
	ds_read_b128 v[196:199], v170 offset:7168
	ds_read_b128 v[200:203], v171
	ds_read_b128 v[204:207], v171 offset:1024
	ds_read_b128 v[208:211], v171 offset:2048
	ds_read_b128 v[212:215], v171 offset:3072
	s_add_u32 s10, s30, 0xfff80080
	s_addc_u32 s11, s31, -1
	s_cmp_eq_u32 s74, 28
	s_cselect_b32 s39, s19, s11
	s_cselect_b32 s38, s70, s10
	s_cselect_b32 s35, s17, s73
	s_cselect_b32 s34, s71, s72
	v_lshl_add_u64 v[164:165], s[30:31], 0, v[152:153]
	s_add_i32 m0, s29, 0xc000
	s_nop 0
	global_load_lds_dwordx4 v[164:165], off
	v_lshl_add_u64 v[164:165], s[30:31], 0, v[154:155]
	s_add_i32 m0, s29, 0xe000
	s_nop 0
	global_load_lds_dwordx4 v[164:165], off
	s_waitcnt vmcnt(8)
	s_waitcnt lgkmcnt(0)
	s_setprio 1
	s_barrier
	v_mfma_f32_16x16x32_bf16 v[120:123], v[128:131], v[160:163], v[120:123]
	v_mfma_f32_16x16x32_bf16 v[124:127], v[136:139], v[160:163], v[124:127]
	v_mfma_f32_16x16x32_bf16 v[112:115], v[128:131], v[176:179], v[112:115]
	v_mfma_f32_16x16x32_bf16 v[116:119], v[136:139], v[176:179], v[116:119]
	v_mfma_f32_16x16x32_bf16 v[96:99], v[128:131], v[184:187], v[96:99]
	v_mfma_f32_16x16x32_bf16 v[88:91], v[136:139], v[184:187], v[88:91]
	v_mfma_f32_16x16x32_bf16 v[80:83], v[128:131], v[192:195], v[80:83]
	v_mfma_f32_16x16x32_bf16 v[72:75], v[136:139], v[192:195], v[72:75]
	v_mfma_f32_16x16x32_bf16 v[120:123], v[132:135], v[172:175], v[120:123]
	v_mfma_f32_16x16x32_bf16 v[124:127], v[140:143], v[172:175], v[124:127]
	v_mfma_f32_16x16x32_bf16 v[112:115], v[132:135], v[180:183], v[112:115]
	v_mfma_f32_16x16x32_bf16 v[116:119], v[140:143], v[180:183], v[116:119]
	v_mfma_f32_16x16x32_bf16 v[96:99], v[132:135], v[188:191], v[96:99]
	v_mfma_f32_16x16x32_bf16 v[88:91], v[140:143], v[188:191], v[88:91]
	v_mfma_f32_16x16x32_bf16 v[80:83], v[132:135], v[196:199], v[80:83]
	v_mfma_f32_16x16x32_bf16 v[72:75], v[140:143], v[196:199], v[72:75]
	v_mfma_f32_16x16x32_bf16 v[108:111], v[200:203], v[160:163], v[108:111]
	v_mfma_f32_16x16x32_bf16 v[104:107], v[208:211], v[160:163], v[104:107]
	v_mfma_f32_16x16x32_bf16 v[100:103], v[200:203], v[176:179], v[100:103]
	v_mfma_f32_16x16x32_bf16 v[92:95], v[208:211], v[176:179], v[92:95]
	v_mfma_f32_16x16x32_bf16 v[84:87], v[200:203], v[184:187], v[84:87]
	v_mfma_f32_16x16x32_bf16 v[76:79], v[208:211], v[184:187], v[76:79]
	v_mfma_f32_16x16x32_bf16 v[68:71], v[200:203], v[192:195], v[68:71]
	v_mfma_f32_16x16x32_bf16 v[64:67], v[208:211], v[192:195], v[64:67]
	v_mfma_f32_16x16x32_bf16 v[108:111], v[204:207], v[172:175], v[108:111]
	v_mfma_f32_16x16x32_bf16 v[104:107], v[212:215], v[172:175], v[104:107]
	v_mfma_f32_16x16x32_bf16 v[100:103], v[204:207], v[180:183], v[100:103]
	v_mfma_f32_16x16x32_bf16 v[92:95], v[212:215], v[180:183], v[92:95]
	v_mfma_f32_16x16x32_bf16 v[84:87], v[204:207], v[188:191], v[84:87]
	v_mfma_f32_16x16x32_bf16 v[76:79], v[212:215], v[188:191], v[76:79]
	v_mfma_f32_16x16x32_bf16 v[68:71], v[204:207], v[196:199], v[68:71]
	v_mfma_f32_16x16x32_bf16 v[64:67], v[212:215], v[196:199], v[64:67]
	s_barrier
	s_setprio 0
	ds_read_b128 v[160:163], v170 offset:16384
	ds_read_b128 v[172:175], v170 offset:17408
	ds_read_b128 v[176:179], v170 offset:18432
	ds_read_b128 v[180:183], v170 offset:19456
	ds_read_b128 v[184:187], v170 offset:20480
	ds_read_b128 v[188:191], v170 offset:21504
	ds_read_b128 v[192:195], v170 offset:22528
	ds_read_b128 v[196:199], v170 offset:23552
	s_add_i32 s10, s66, s45
	v_lshl_add_u64 v[164:165], s[34:35], 0, v[146:147]
	s_mov_b32 m0, s10
	s_nop 0
	global_load_lds_dwordx4 v[164:165], off
	v_lshl_add_u64 v[216:217], s[34:35], 0, v[150:151]
	s_add_i32 m0, s10, 0x2000
	s_nop 0
	global_load_lds_dwordx4 v[216:217], off
	s_mov_b32 m0, s29
	v_lshl_add_u64 v[218:219], s[38:39], 0, v[144:145]
	global_load_lds_dwordx4 v[218:219], off
	v_lshl_add_u64 v[220:221], s[38:39], 0, v[148:149]
	s_mov_b32 m0, s46
	s_nop 0
	global_load_lds_dwordx4 v[220:221], off
	s_add_u32 s10, s34, 0x80000
	s_addc_u32 s11, s35, 0
	s_add_i32 s33, s67, s45
	v_lshl_add_u64 v[246:247], s[10:11], 0, v[146:147]
	s_mov_b32 m0, s33
	s_nop 0
	global_load_lds_dwordx4 v[246:247], off
	v_lshl_add_u64 v[246:247], s[10:11], 0, v[150:151]
	s_add_i32 m0, s33, 0x2000
	s_nop 0
	global_load_lds_dwordx4 v[246:247], off
	s_waitcnt vmcnt(8)
	s_waitcnt lgkmcnt(0)
	s_setprio 1
	s_barrier
; #define PG8_STAGE(bufoff, gbase, voff) do { _Pragma("unroll") for (int _i = 0; _i < 2; ++_i) \
;         __builtin_amdgcn_global_load_lds((const unsigned*)((const char*)(gbase) + (voff)[_i]), (PG8_LAS unsigned*)(lds + (bufoff) + ldsw + _i * 8192), 16, 0, 0); } while (0)
; #define PG8_LDA(dst, b, h) do { _Pragma("unroll") for (int m = 0; m < 4; ++m) _Pragma("unroll") for (int k = 0; k < 2; ++k) dst[m][k] = *(const PG8_LAS bf16x8*)(lds + PG8_SA(b, h) + aoff + m * 2048 + k * 1024); } while (0)
; #define PG8_LDB(dst, b, h) do { _Pragma("unroll") for (int n = 0; n < 2; ++n) _Pragma("unroll") for (int k = 0; k < 2; ++k) dst[n][k] = *(const PG8_LAS bf16x8*)(lds + PG8_SB(b, h) + boff + n * 2048 + k * 1024); } while (0)
; #define PG8_WAIT_V(n) asm volatile("s_waitcnt vmcnt(" #n ")" ::: "memory")
; #define PG8_WAIT_L(n) asm volatile("s_waitcnt lgkmcnt(" #n ")" ::: "memory")
; #define PG8_BAR __builtin_amdgcn_s_barrier()
; #define PG8_SCHED __builtin_amdgcn_sched_barrier(0)
; template <class Epi, class Sched>
; __device__ __forceinline__ void gemm_phase(PG8_LAS unsigned char* lds, const Gemm g, const Sched& S, const Epi& E) {
;     ...
;             PG8_LDB(B0, 0, 0); PG8_SCHED; PG8_LDA(At, 0, 0); PG8_STAGE(PG8_SA(1, 1), a1 + hstep, voffA);
;             PG8_WAIT_L(8); PG8_BAR; PG8_WAIT_L(0); PG8_MMA(0, 0, At, B0); PG8_BAR; PG8_SCHED;
;             PG8_LDB(B1, 0, 1); PG8_STAGE(PG8_SB(0, 0), b2, voffB);
;             PG8_BAR; PG8_WAIT_L(0); PG8_MMA(0, 1, At, B1); PG8_BAR;
;             PG8_LDA(At, 0, 1); PG8_STAGE(PG8_SA(0, 0), a2, voffA);
;             PG8_BAR; PG8_WAIT_L(0); PG8_MMA(1, 0, At, B0); PG8_BAR; PG8_SCHED;
;             PG8_STAGE(PG8_SB(0, 1), b2 + hstep, voffB);
;             PG8_WAIT_V(6); PG8_BAR; PG8_MMA(1, 1, At, B1); PG8_BAR;
;             PG8_LDB(B0, 1, 0); PG8_SCHED; PG8_LDA(At, 1, 0); PG8_STAGE(PG8_SA(0, 1), a2 + hstep, voffA);
;             PG8_WAIT_L(8); PG8_BAR; PG8_WAIT_L(0); PG8_MMA(0, 0, At, B0); PG8_BAR; PG8_SCHED;
;             PG8_LDB(B1, 1, 1); PG8_STAGE(PG8_SB(1, 0), b3, voffB);
;             PG8_BAR; PG8_WAIT_L(0); PG8_MMA(0, 1, At, B1); PG8_BAR;
;             PG8_LDA(At, 1, 1); PG8_STAGE(PG8_SA(1, 0), a3, voffA);
;             PG8_BAR; PG8_WAIT_L(0); PG8_MMA(1, 0, At, B0); PG8_BAR; PG8_SCHED;
;             PG8_STAGE(PG8_SB(1, 1), b3 + hstep, voffB);
;             PG8_WAIT_V(6); PG8_BAR; PG8_MMA(1, 1, At, B1); PG8_BAR;
	v_mfma_f32_16x16x32_bf16 v[60:63], v[128:131], v[160:163], v[60:63]
	v_mfma_f32_16x16x32_bf16 v[56:59], v[136:139], v[160:163], v[56:59]
	v_mfma_f32_16x16x32_bf16 v[48:51], v[128:131], v[176:179], v[48:51]
	v_mfma_f32_16x16x32_bf16 v[40:43], v[136:139], v[176:179], v[40:43]
	v_mfma_f32_16x16x32_bf16 v[32:35], v[128:131], v[184:187], v[32:35]
	v_mfma_f32_16x16x32_bf16 v[24:27], v[136:139], v[184:187], v[24:27]
	v_mfma_f32_16x16x32_bf16 v[16:19], v[128:131], v[192:195], v[16:19]
	v_mfma_f32_16x16x32_bf16 v[8:11], v[136:139], v[192:195], v[8:11]
	s_add_i32 s33, 0, 0x18000
	v_mfma_f32_16x16x32_bf16 v[60:63], v[132:135], v[172:175], v[60:63]
	v_mfma_f32_16x16x32_bf16 v[56:59], v[140:143], v[172:175], v[56:59]
	v_mfma_f32_16x16x32_bf16 v[48:51], v[132:135], v[180:183], v[48:51]
	v_mfma_f32_16x16x32_bf16 v[40:43], v[140:143], v[180:183], v[40:43]
	v_mfma_f32_16x16x32_bf16 v[32:35], v[132:135], v[188:191], v[32:35]
	v_mfma_f32_16x16x32_bf16 v[24:27], v[140:143], v[188:191], v[24:27]
	v_mfma_f32_16x16x32_bf16 v[16:19], v[132:135], v[196:199], v[16:19]
	v_mfma_f32_16x16x32_bf16 v[8:11], v[140:143], v[196:199], v[8:11]
	v_mfma_f32_16x16x32_bf16 v[52:55], v[200:203], v[160:163], v[52:55]
	v_mfma_f32_16x16x32_bf16 v[44:47], v[208:211], v[160:163], v[44:47]
	v_mfma_f32_16x16x32_bf16 v[36:39], v[200:203], v[176:179], v[36:39]
	v_mfma_f32_16x16x32_bf16 v[28:31], v[208:211], v[176:179], v[28:31]
	v_mfma_f32_16x16x32_bf16 v[20:23], v[200:203], v[184:187], v[20:23]
	v_mfma_f32_16x16x32_bf16 v[12:15], v[208:211], v[184:187], v[12:15]
	v_mfma_f32_16x16x32_bf16 v[4:7], v[200:203], v[192:195], v[4:7]
	v_mfma_f32_16x16x32_bf16 v[0:3], v[208:211], v[192:195], v[0:3]
	v_mfma_f32_16x16x32_bf16 v[52:55], v[204:207], v[172:175], v[52:55]
	v_mfma_f32_16x16x32_bf16 v[44:47], v[212:215], v[172:175], v[44:47]
	v_mfma_f32_16x16x32_bf16 v[36:39], v[204:207], v[180:183], v[36:39]
	v_mfma_f32_16x16x32_bf16 v[28:31], v[212:215], v[180:183], v[28:31]
	v_mfma_f32_16x16x32_bf16 v[20:23], v[204:207], v[188:191], v[20:23]
	v_mfma_f32_16x16x32_bf16 v[12:15], v[212:215], v[188:191], v[12:15]
	v_mfma_f32_16x16x32_bf16 v[4:7], v[204:207], v[196:199], v[4:7]
	v_mfma_f32_16x16x32_bf16 v[0:3], v[212:215], v[196:199], v[0:3]
	s_barrier
	s_setprio 0
	ds_read_b128 v[128:131], v169 offset:32768
	ds_read_b128 v[132:135], v169 offset:33792
	ds_read_b128 v[136:139], v169 offset:34816
	ds_read_b128 v[140:143], v169 offset:35840
	ds_read_b128 v[160:163], v170 offset:32768
	ds_read_b128 v[172:175], v170 offset:33792
	ds_read_b128 v[176:179], v170 offset:34816
	ds_read_b128 v[180:183], v170 offset:35840
	ds_read_b128 v[184:187], v170 offset:36864
	ds_read_b128 v[188:191], v170 offset:37888
	ds_read_b128 v[192:195], v170 offset:38912
	ds_read_b128 v[196:199], v170 offset:39936
	ds_read_b128 v[200:203], v171 offset:32768
	ds_read_b128 v[204:207], v171 offset:33792
	ds_read_b128 v[208:211], v171 offset:34816
	ds_read_b128 v[212:215], v171 offset:35840
	s_add_u32 s10, s38, 0x80000
	s_addc_u32 s11, s39, 0
	s_mov_b32 m0, s47
	v_lshl_add_u64 v[246:247], s[10:11], 0, v[144:145]
	global_load_lds_dwordx4 v[246:247], off
	v_lshl_add_u64 v[246:247], s[10:11], 0, v[148:149]
	s_mov_b32 m0, s48
	s_nop 0
	global_load_lds_dwordx4 v[246:247], off
	s_waitcnt vmcnt(8)
	s_waitcnt lgkmcnt(0)
	s_setprio 1
	s_barrier
	v_mfma_f32_16x16x32_bf16 v[120:123], v[128:131], v[160:163], v[120:123]
	v_mfma_f32_16x16x32_bf16 v[124:127], v[136:139], v[160:163], v[124:127]
	v_mfma_f32_16x16x32_bf16 v[112:115], v[128:131], v[176:179], v[112:115]
	v_mfma_f32_16x16x32_bf16 v[116:119], v[136:139], v[176:179], v[116:119]
	v_mfma_f32_16x16x32_bf16 v[96:99], v[128:131], v[184:187], v[96:99]
	v_mfma_f32_16x16x32_bf16 v[88:91], v[136:139], v[184:187], v[88:91]
	v_mfma_f32_16x16x32_bf16 v[80:83], v[128:131], v[192:195], v[80:83]
	v_mfma_f32_16x16x32_bf16 v[72:75], v[136:139], v[192:195], v[72:75]
	v_mfma_f32_16x16x32_bf16 v[120:123], v[132:135], v[172:175], v[120:123]
	v_mfma_f32_16x16x32_bf16 v[124:127], v[140:143], v[172:175], v[124:127]
	v_mfma_f32_16x16x32_bf16 v[112:115], v[132:135], v[180:183], v[112:115]
	v_mfma_f32_16x16x32_bf16 v[116:119], v[140:143], v[180:183], v[116:119]
	v_mfma_f32_16x16x32_bf16 v[96:99], v[132:135], v[188:191], v[96:99]
	v_mfma_f32_16x16x32_bf16 v[88:91], v[140:143], v[188:191], v[88:91]
	v_mfma_f32_16x16x32_bf16 v[80:83], v[132:135], v[196:199], v[80:83]
	v_mfma_f32_16x16x32_bf16 v[72:75], v[140:143], v[196:199], v[72:75]
	v_mfma_f32_16x16x32_bf16 v[108:111], v[200:203], v[160:163], v[108:111]
	v_mfma_f32_16x16x32_bf16 v[104:107], v[208:211], v[160:163], v[104:107]
	v_mfma_f32_16x16x32_bf16 v[100:103], v[200:203], v[176:179], v[100:103]
	v_mfma_f32_16x16x32_bf16 v[92:95], v[208:211], v[176:179], v[92:95]
	v_mfma_f32_16x16x32_bf16 v[84:87], v[200:203], v[184:187], v[84:87]
	v_mfma_f32_16x16x32_bf16 v[76:79], v[208:211], v[184:187], v[76:79]
	v_mfma_f32_16x16x32_bf16 v[68:71], v[200:203], v[192:195], v[68:71]
	v_mfma_f32_16x16x32_bf16 v[64:67], v[208:211], v[192:195], v[64:67]
	v_mfma_f32_16x16x32_bf16 v[108:111], v[204:207], v[172:175], v[108:111]
	v_mfma_f32_16x16x32_bf16 v[104:107], v[212:215], v[172:175], v[104:107]
	v_mfma_f32_16x16x32_bf16 v[100:103], v[204:207], v[180:183], v[100:103]
	v_mfma_f32_16x16x32_bf16 v[92:95], v[212:215], v[180:183], v[92:95]
	v_mfma_f32_16x16x32_bf16 v[84:87], v[204:207], v[188:191], v[84:87]
	v_mfma_f32_16x16x32_bf16 v[76:79], v[212:215], v[188:191], v[76:79]
	v_mfma_f32_16x16x32_bf16 v[68:71], v[204:207], v[196:199], v[68:71]
	v_mfma_f32_16x16x32_bf16 v[64:67], v[212:215], v[196:199], v[64:67]
	s_barrier
; #define PG8_STAGE(bufoff, gbase, voff) do { _Pragma("unroll") for (int _i = 0; _i < 2; ++_i) \
;         __builtin_amdgcn_global_load_lds((const unsigned*)((const char*)(gbase) + (voff)[_i]), (PG8_LAS unsigned*)(lds + (bufoff) + ldsw + _i * 8192), 16, 0, 0); } while (0)
; #define PG8_LDA(dst, b, h) do { _Pragma("unroll") for (int m = 0; m < 4; ++m) _Pragma("unroll") for (int k = 0; k < 2; ++k) dst[m][k] = *(const PG8_LAS bf16x8*)(lds + PG8_SA(b, h) + aoff + m * 2048 + k * 1024); } while (0)
; #define PG8_WAIT_V(n) asm volatile("s_waitcnt vmcnt(" #n ")" ::: "memory")
; #define PG8_BAR __builtin_amdgcn_s_barrier()
; template <class Epi, class Sched>
; __device__ __forceinline__ void gemm_phase(PG8_LAS unsigned char* lds, const Gemm g, const Sched& S, const Epi& E) {
;     ...
;             PG8_LDB(B0, 1, 0); PG8_SCHED; PG8_LDA(At, 1, 0); PG8_STAGE(PG8_SA(0, 1), a2 + hstep, voffA);
;             PG8_WAIT_L(8); PG8_BAR; PG8_WAIT_L(0); PG8_MMA(0, 0, At, B0); PG8_BAR; PG8_SCHED;
;             PG8_LDB(B1, 1, 1); PG8_STAGE(PG8_SB(1, 0), b3, voffB);
;             PG8_BAR; PG8_WAIT_L(0); PG8_MMA(0, 1, At, B1); PG8_BAR;
;             PG8_LDA(At, 1, 1); PG8_STAGE(PG8_SA(1, 0), a3, voffA);
;             PG8_BAR; PG8_WAIT_L(0); PG8_MMA(1, 0, At, B0); PG8_BAR; PG8_SCHED;
;             PG8_STAGE(PG8_SB(1, 1), b3 + hstep, voffB);
;             PG8_WAIT_V(6); PG8_BAR; PG8_MMA(1, 1, At, B1); PG8_BAR;
;         }
;         E(acc, cur, wr, wc, fr, fq); S.done(cur);
;         if (!has_next) break;
;     __device__ __forceinline__ void operator()(const AccT& acc, const pg8::Unit& u, int wr, int wc, int fr, int fq) const {
;         const int row0 = u.pm * 256 + wr * 64 + fr, col0 = u.pn * 256 + wc * 32 + 8 * fq;
;         const float* ga = mod + (u.pm >= 64 ? 12288 : 0) + 2 * 2048;
;         f32x4 gv[2][2];
; #pragma unroll
;         for (int bj = 0; bj < 2; ++bj)
; #pragma unroll
;             for (int n = 0; n < 2; ++n) gv[bj][n] = *(const f32x4*)(ga + col0 + bj * 128 + n * 4);
; #pragma unroll
;         for (int ai = 0; ai < 2; ++ai) {
;             f32x4 xa[4][2], xb[4][2];
; #pragma unroll
;             for (int m = 0; m < 4; ++m) { const size_t off = (size_t)(row0 + ai * 128 + m * 16) * D + col0;
; #pragma unroll
;                 for (int bj = 0; bj < 2; ++bj) { xa[m][bj] = *(const f32x4*)(x + off + bj * 128); xb[m][bj] = *(const f32x4*)(x + off + bj * 128 + 4); } }
	s_setprio 0
	ds_read_b128 v[160:163], v170 offset:49152
	ds_read_b128 v[172:175], v170 offset:50176
	ds_read_b128 v[176:179], v170 offset:51200
	ds_read_b128 v[180:183], v170 offset:52224
	ds_read_b128 v[184:187], v170 offset:53248
	ds_read_b128 v[188:191], v170 offset:54272
	ds_read_b128 v[192:195], v170 offset:55296
	ds_read_b128 v[196:199], v170 offset:56320
	s_add_i32 s38, 0, 0x1c000
	s_add_i32 s10, s33, s45
	v_lshl_add_u64 v[164:165], v[164:165], 0, s[4:5]
	s_mov_b32 m0, s10
	s_nop 0
	global_load_lds_dwordx4 v[164:165], off
	v_lshl_add_u64 v[164:165], v[216:217], 0, s[4:5]
	s_add_i32 m0, s10, 0x2000
	s_nop 0
	global_load_lds_dwordx4 v[164:165], off
	s_mov_b32 m0, s50
	v_lshl_add_u64 v[164:165], v[218:219], 0, s[4:5]
	global_load_lds_dwordx4 v[164:165], off
	v_lshl_add_u64 v[164:165], v[220:221], 0, s[4:5]
	s_mov_b32 m0, s51
	s_nop 0
	global_load_lds_dwordx4 v[164:165], off
	s_add_u32 s10, s34, 0x80080
	s_addc_u32 s11, s35, 0
	s_add_i32 s33, s38, s45
	v_lshl_add_u64 v[246:247], s[10:11], 0, v[146:147]
	s_mov_b32 m0, s33
	s_nop 0
	global_load_lds_dwordx4 v[246:247], off
	v_lshl_add_u64 v[246:247], s[10:11], 0, v[150:151]
	s_add_i32 m0, s33, 0x2000
	s_nop 0
	global_load_lds_dwordx4 v[246:247], off
	s_waitcnt vmcnt(8)
	s_waitcnt lgkmcnt(0)
	s_setprio 1
	s_barrier
	v_mfma_f32_16x16x32_bf16 v[60:63], v[128:131], v[160:163], v[60:63]
	v_mfma_f32_16x16x32_bf16 v[56:59], v[136:139], v[160:163], v[56:59]
	v_mfma_f32_16x16x32_bf16 v[48:51], v[128:131], v[176:179], v[48:51]
	v_mfma_f32_16x16x32_bf16 v[40:43], v[136:139], v[176:179], v[40:43]
	v_mfma_f32_16x16x32_bf16 v[32:35], v[128:131], v[184:187], v[32:35]
	v_mfma_f32_16x16x32_bf16 v[24:27], v[136:139], v[184:187], v[24:27]
	v_mfma_f32_16x16x32_bf16 v[16:19], v[128:131], v[192:195], v[16:19]
	v_mfma_f32_16x16x32_bf16 v[8:11], v[136:139], v[192:195], v[8:11]
	s_add_i32 s74, s74, 2
	s_add_u32 s30, s30, 0x100
	s_addc_u32 s31, s31, 0
	s_add_u32 s72, s72, 0x100
	s_addc_u32 s73, s73, 0
	s_cmp_gt_u32 s74, 29
	v_mfma_f32_16x16x32_bf16 v[60:63], v[132:135], v[172:175], v[60:63]
	v_mfma_f32_16x16x32_bf16 v[56:59], v[140:143], v[172:175], v[56:59]
	v_mfma_f32_16x16x32_bf16 v[48:51], v[132:135], v[180:183], v[48:51]
	v_mfma_f32_16x16x32_bf16 v[40:43], v[140:143], v[180:183], v[40:43]
	v_mfma_f32_16x16x32_bf16 v[32:35], v[132:135], v[188:191], v[32:35]
	v_mfma_f32_16x16x32_bf16 v[24:27], v[140:143], v[188:191], v[24:27]
	v_mfma_f32_16x16x32_bf16 v[16:19], v[132:135], v[196:199], v[16:19]
	v_mfma_f32_16x16x32_bf16 v[8:11], v[140:143], v[196:199], v[8:11]
	v_mfma_f32_16x16x32_bf16 v[52:55], v[200:203], v[160:163], v[52:55]
	v_mfma_f32_16x16x32_bf16 v[44:47], v[208:211], v[160:163], v[44:47]
	v_mfma_f32_16x16x32_bf16 v[36:39], v[200:203], v[176:179], v[36:39]
	v_mfma_f32_16x16x32_bf16 v[28:31], v[208:211], v[176:179], v[28:31]
	v_mfma_f32_16x16x32_bf16 v[20:23], v[200:203], v[184:187], v[20:23]
	v_mfma_f32_16x16x32_bf16 v[12:15], v[208:211], v[184:187], v[12:15]
	v_mfma_f32_16x16x32_bf16 v[4:7], v[200:203], v[192:195], v[4:7]
	v_mfma_f32_16x16x32_bf16 v[0:3], v[208:211], v[192:195], v[0:3]
	v_mfma_f32_16x16x32_bf16 v[52:55], v[204:207], v[172:175], v[52:55]
	v_mfma_f32_16x16x32_bf16 v[44:47], v[212:215], v[172:175], v[44:47]
	v_mfma_f32_16x16x32_bf16 v[36:39], v[204:207], v[180:183], v[36:39]
	v_mfma_f32_16x16x32_bf16 v[28:31], v[212:215], v[180:183], v[28:31]
	v_mfma_f32_16x16x32_bf16 v[20:23], v[204:207], v[188:191], v[20:23]
	v_mfma_f32_16x16x32_bf16 v[12:15], v[212:215], v[188:191], v[12:15]
	v_mfma_f32_16x16x32_bf16 v[4:7], v[204:207], v[196:199], v[4:7]
	v_mfma_f32_16x16x32_bf16 v[0:3], v[212:215], v[196:199], v[0:3]
	s_barrier
	s_cbranch_scc0 .LBB0_666
	s_setprio 0
	v_lshl_or_b32 v160, s69, 8, v168
	s_cmp_gt_i32 s28, 63
	v_ashrrev_i32_e32 v161, 31, v160
	v_lshl_add_u32 v164, s28, 8, v166
	s_cselect_b32 s10, 0xc000, 0
	v_lshlrev_b64 v[128:129], 2, v[160:161]
	v_ashrrev_i32_e32 v165, 31, v164
	s_add_u32 s10, s58, s10
	v_lshl_add_u64 v[162:163], s[36:37], 0, v[128:129]
	v_lshlrev_b64 v[130:131], 13, v[164:165]
	v_or_b32_e32 v220, 16, v164
	s_addc_u32 s11, s59, 0
	v_lshl_add_u64 v[130:131], v[162:163], 0, v[130:131]
	v_ashrrev_i32_e32 v221, 31, v220
	global_load_dwordx4 v[172:175], v[130:131], off offset:16
	global_load_dwordx4 v[176:179], v[130:131], off
	global_load_dwordx4 v[180:183], v[130:131], off offset:528
	global_load_dwordx4 v[184:187], v[130:131], off offset:512
	v_lshlrev_b64 v[130:131], 13, v[220:221]
	v_lshl_add_u64 v[128:129], s[10:11], 0, v[128:129]
	v_lshl_add_u64 v[200:201], v[162:163], 0, v[130:131]
	v_lshl_add_u64 v[130:131], v[128:129], 0, s[6:7]
	global_load_dwordx4 v[188:191], v[200:201], off offset:16
	global_load_dwordx4 v[192:195], v[200:201], off
	global_load_dwordx4 v[136:139], v[130:131], off offset:16
	global_load_dwordx4 v[132:135], v[130:131], off offset:512
	v_add_co_u32_e32 v128, vcc, s68, v128
	v_or_b32_e32 v236, 32, v164
	s_nop 0
	v_addc_co_u32_e32 v129, vcc, 0, v129, vcc
	global_load_dwordx4 v[140:143], v[128:129], off
	s_nop 0
	global_load_dwordx4 v[128:131], v[130:131], off offset:528
	s_nop 0
	global_load_dwordx4 v[196:199], v[200:201], off offset:512
	s_nop 0
	global_load_dwordx4 v[200:203], v[200:201], off offset:528
	v_ashrrev_i32_e32 v237, 31, v236
	v_lshlrev_b64 v[204:205], 13, v[236:237]
	v_lshl_add_u64 v[216:217], v[162:163], 0, v[204:205]
	global_load_dwordx4 v[204:207], v[216:217], off
	global_load_dwordx4 v[208:211], v[216:217], off offset:16
	global_load_dwordx4 v[212:215], v[216:217], off offset:528
	s_nop 0
	global_load_dwordx4 v[216:219], v[216:217], off offset:512
	v_or_b32_e32 v238, 48, v164
	v_ashrrev_i32_e32 v239, 31, v238
	v_lshlrev_b64 v[222:223], 12, v[164:165]
	v_lshlrev_b64 v[224:225], 13, v[238:239]
	v_lshlrev_b64 v[160:161], 1, v[160:161]
	v_lshl_add_u64 v[222:223], s[0:1], 0, v[222:223]
	v_lshl_add_u64 v[232:233], v[162:163], 0, v[224:225]
	v_lshlrev_b64 v[240:241], 12, v[220:221]
	v_lshl_add_u64 v[244:245], v[222:223], 0, v[160:161]
	global_load_dwordx4 v[220:223], v[232:233], off offset:16
	global_load_dwordx4 v[224:227], v[232:233], off
	global_load_dwordx4 v[228:231], v[232:233], off offset:528
	s_nop 0
	global_load_dwordx4 v[232:235], v[232:233], off offset:512
	s_and_b64 vcc, exec, s[2:3]
	s_mov_b32 s69, s16
	s_mov_b32 s28, s18
	s_mov_b64 s[34:35], s[26:27]
	s_mov_b64 s[30:31], s[20:21]
	s_waitcnt vmcnt(0)
;     __device__ __forceinline__ void operator()(const AccT& acc, const pg8::Unit& u, int wr, int wc, int fr, int fq) const {
;     ...
;         for (int ai = 0; ai < 2; ++ai) {
;             f32x4 xa[4][2], xb[4][2];
; #pragma unroll
;             for (int m = 0; m < 4; ++m) { const size_t off = (size_t)(row0 + ai * 128 + m * 16) * D + col0;
; #pragma unroll
;                 for (int bj = 0; bj < 2; ++bj) { xa[m][bj] = *(const f32x4*)(x + off + bj * 128); xb[m][bj] = *(const f32x4*)(x + off + bj * 128 + 4); } }
; #pragma unroll
;             for (int m = 0; m < 4; ++m) { const size_t off = (size_t)(row0 + ai * 128 + m * 16) * D + col0;
; #pragma unroll
;                 for (int bj = 0; bj < 2; ++bj) {
;                     const f32x4 a = ALPHA * xa[m][bj] + gv[bj][0] * acc[ai][bj][m][0], b = ALPHA * xb[m][bj] + gv[bj][1] * acc[ai][bj][m][1];
;                     u32x4 w; w.x = pk_h2(a[0], a[1]); w.y = pk_h2(a[2], a[3]); w.z = pk_h2(b[0], b[1]); w.w = pk_h2(b[2], b[3]);
;                     *(u32x4*)(U1 + off + bj * 128) = w; } }
	v_pk_mul_f32 v[174:175], v[174:175], s[8:9] op_sel_hi:[1,0]
	v_pk_mul_f32 v[178:179], v[178:179], s[8:9] op_sel_hi:[1,0]
	v_pk_mul_f32 v[176:177], v[176:177], s[8:9] op_sel_hi:[1,0]
	v_pk_mul_f32 v[172:173], v[172:173], s[8:9] op_sel_hi:[1,0]
	v_pk_mul_f32 v[186:187], v[186:187], s[8:9] op_sel_hi:[1,0]
	v_pk_mul_f32 v[184:185], v[184:185], s[8:9] op_sel_hi:[1,0]
	v_pk_mul_f32 v[182:183], v[182:183], s[8:9] op_sel_hi:[1,0]
	v_pk_mul_f32 v[180:181], v[180:181], s[8:9] op_sel_hi:[1,0]
	v_pk_mul_f32 v[194:195], v[194:195], s[8:9] op_sel_hi:[1,0]
	v_pk_fma_f32 v[126:127], v[126:127], v[138:139], v[174:175]
	v_pk_fma_f32 v[124:125], v[124:125], v[136:137], v[172:173]
	v_pk_mul_f32 v[192:193], v[192:193], s[8:9] op_sel_hi:[1,0]
	v_pk_mul_f32 v[190:191], v[190:191], s[8:9] op_sel_hi:[1,0]
	v_pk_fma_f32 v[122:123], v[122:123], v[142:143], v[178:179]
	v_pk_fma_f32 v[120:121], v[120:121], v[140:141], v[176:177]
	v_pk_mul_f32 v[188:189], v[188:189], s[8:9] op_sel_hi:[1,0]
	v_pk_fma_f32 v[172:173], v[110:111], v[134:135], v[186:187]
	v_pk_fma_f32 v[110:111], v[108:109], v[132:133], v[184:185]
	v_cvt_pk_f16_f32 v108, v124, v125
	v_cvt_pk_f16_f32 v109, v126, v127
	v_pk_fma_f32 v[124:125], v[106:107], v[130:131], v[182:183]
	v_pk_fma_f32 v[104:105], v[104:105], v[128:129], v[180:181]
	v_cvt_pk_f16_f32 v106, v120, v121
	v_cvt_pk_f16_f32 v107, v122, v123
	v_pk_fma_f32 v[118:119], v[118:119], v[138:139], v[190:191]
	v_pk_fma_f32 v[116:117], v[116:117], v[136:137], v[188:189]
	v_cvt_pk_f16_f32 v110, v110, v111
	v_cvt_pk_f16_f32 v111, v172, v173
	v_pk_fma_f32 v[114:115], v[114:115], v[142:143], v[194:195]
	v_pk_fma_f32 v[126:127], v[112:113], v[140:141], v[192:193]
	v_cvt_pk_f16_f32 v112, v104, v105
	v_cvt_pk_f16_f32 v113, v124, v125
	global_store_dwordx4 v[244:245], v[106:109], off
	global_store_dwordx4 v[244:245], v[110:113], off offset:256
	v_cvt_pk_f16_f32 v104, v126, v127
	v_lshl_add_u64 v[108:109], s[0:1], 0, v[240:241]
	v_cvt_pk_f16_f32 v105, v114, v115
	v_cvt_pk_f16_f32 v106, v116, v117
	v_cvt_pk_f16_f32 v107, v118, v119
	v_lshl_add_u64 v[108:109], v[108:109], 0, v[160:161]
	global_store_dwordx4 v[108:109], v[104:107], off
	v_add_u32_e32 v172, 0x80, v164
	v_ashrrev_i32_e32 v173, 31, v172
	v_pk_mul_f32 v[104:105], v[198:199], s[8:9] op_sel_hi:[1,0]
	v_pk_mul_f32 v[106:107], v[196:197], s[8:9] op_sel_hi:[1,0]
	v_pk_fma_f32 v[102:103], v[102:103], v[134:135], v[104:105]
	v_pk_fma_f32 v[100:101], v[100:101], v[132:133], v[106:107]
	v_pk_mul_f32 v[104:105], v[202:203], s[8:9] op_sel_hi:[1,0]
	v_pk_mul_f32 v[106:107], v[200:201], s[8:9] op_sel_hi:[1,0]
	v_pk_fma_f32 v[104:105], v[94:95], v[130:131], v[104:105]
	v_pk_fma_f32 v[94:95], v[92:93], v[128:129], v[106:107]
	v_cvt_pk_f16_f32 v92, v100, v101
	v_cvt_pk_f16_f32 v93, v102, v103
	v_cvt_pk_f16_f32 v94, v94, v95
	v_cvt_pk_f16_f32 v95, v104, v105
	global_store_dwordx4 v[108:109], v[92:95], off offset:256
	v_pk_mul_f32 v[100:101], v[204:205], s[8:9] op_sel_hi:[1,0]
	v_add_u32_e32 v174, 0x90, v164
	v_pk_mul_f32 v[94:95], v[206:207], s[8:9] op_sel_hi:[1,0]
	v_lshlrev_b64 v[92:93], 12, v[236:237]
	v_pk_fma_f32 v[94:95], v[98:99], v[142:143], v[94:95]
	v_pk_fma_f32 v[96:97], v[96:97], v[140:141], v[100:101]
	v_pk_mul_f32 v[98:99], v[210:211], s[8:9] op_sel_hi:[1,0]
	v_pk_mul_f32 v[100:101], v[208:209], s[8:9] op_sel_hi:[1,0]
	v_pk_fma_f32 v[98:99], v[90:91], v[138:139], v[98:99]
	v_pk_fma_f32 v[90:91], v[88:89], v[136:137], v[100:101]
	v_lshl_add_u64 v[92:93], s[0:1], 0, v[92:93]
	v_cvt_pk_f16_f32 v88, v96, v97
	v_cvt_pk_f16_f32 v89, v94, v95
	v_cvt_pk_f16_f32 v90, v90, v91
	v_cvt_pk_f16_f32 v91, v98, v99
	v_lshl_add_u64 v[92:93], v[92:93], 0, v[160:161]
	global_store_dwordx4 v[92:93], v[88:91], off
	v_ashrrev_i32_e32 v175, 31, v174
	v_add_u32_e32 v176, 0xa0, v164
	v_pk_mul_f32 v[88:89], v[218:219], s[8:9] op_sel_hi:[1,0]
	v_pk_mul_f32 v[90:91], v[216:217], s[8:9] op_sel_hi:[1,0]
	v_pk_fma_f32 v[86:87], v[86:87], v[134:135], v[88:89]
	v_pk_fma_f32 v[84:85], v[84:85], v[132:133], v[90:91]
	v_pk_mul_f32 v[88:89], v[214:215], s[8:9] op_sel_hi:[1,0]
	v_pk_mul_f32 v[90:91], v[212:213], s[8:9] op_sel_hi:[1,0]
	v_pk_fma_f32 v[88:89], v[78:79], v[130:131], v[88:89]
	v_pk_fma_f32 v[78:79], v[76:77], v[128:129], v[90:91]
	v_cvt_pk_f16_f32 v76, v84, v85
	v_cvt_pk_f16_f32 v77, v86, v87
	v_cvt_pk_f16_f32 v78, v78, v79
	v_cvt_pk_f16_f32 v79, v88, v89
	global_store_dwordx4 v[92:93], v[76:79], off offset:256
	v_pk_mul_f32 v[84:85], v[224:225], s[8:9] op_sel_hi:[1,0]
	v_ashrrev_i32_e32 v177, 31, v176
	v_pk_mul_f32 v[78:79], v[226:227], s[8:9] op_sel_hi:[1,0]
	v_lshlrev_b64 v[76:77], 12, v[238:239]
	v_pk_fma_f32 v[78:79], v[82:83], v[142:143], v[78:79]
	v_pk_fma_f32 v[80:81], v[80:81], v[140:141], v[84:85]
	v_pk_mul_f32 v[82:83], v[222:223], s[8:9] op_sel_hi:[1,0]
	v_pk_mul_f32 v[84:85], v[220:221], s[8:9] op_sel_hi:[1,0]
	v_pk_fma_f32 v[82:83], v[74:75], v[138:139], v[82:83]
	v_pk_fma_f32 v[74:75], v[72:73], v[136:137], v[84:85]
	v_lshl_add_u64 v[76:77], s[0:1], 0, v[76:77]
	v_cvt_pk_f16_f32 v72, v80, v81
	v_cvt_pk_f16_f32 v73, v78, v79
	v_cvt_pk_f16_f32 v74, v74, v75
	v_cvt_pk_f16_f32 v75, v82, v83
	v_lshl_add_u64 v[76:77], v[76:77], 0, v[160:161]
	global_store_dwordx4 v[76:77], v[72:75], off
	v_lshlrev_b64 v[80:81], 13, v[174:175]
	v_lshl_add_u64 v[92:93], v[162:163], 0, v[80:81]
	v_pk_mul_f32 v[72:73], v[234:235], s[8:9] op_sel_hi:[1,0]
	v_pk_mul_f32 v[74:75], v[232:233], s[8:9] op_sel_hi:[1,0]
	v_pk_fma_f32 v[70:71], v[70:71], v[134:135], v[72:73]
	v_pk_fma_f32 v[68:69], v[68:69], v[132:133], v[74:75]
	v_pk_mul_f32 v[72:73], v[230:231], s[8:9] op_sel_hi:[1,0]
	v_pk_mul_f32 v[74:75], v[228:229], s[8:9] op_sel_hi:[1,0]
;     __device__ __forceinline__ void operator()(const AccT& acc, const pg8::Unit& u, int wr, int wc, int fr, int fq) const {
;     ...
;             for (int m = 0; m < 4; ++m) { const size_t off = (size_t)(row0 + ai * 128 + m * 16) * D + col0;
; #pragma unroll
;                 for (int bj = 0; bj < 2; ++bj) { xa[m][bj] = *(const f32x4*)(x + off + bj * 128); xb[m][bj] = *(const f32x4*)(x + off + bj * 128 + 4); } }
; #pragma unroll
;             for (int m = 0; m < 4; ++m) { const size_t off = (size_t)(row0 + ai * 128 + m * 16) * D + col0;
; #pragma unroll
;                 for (int bj = 0; bj < 2; ++bj) {
;                     const f32x4 a = ALPHA * xa[m][bj] + gv[bj][0] * acc[ai][bj][m][0], b = ALPHA * xb[m][bj] + gv[bj][1] * acc[ai][bj][m][1];
;                     u32x4 w; w.x = pk_h2(a[0], a[1]); w.y = pk_h2(a[2], a[3]); w.z = pk_h2(b[0], b[1]); w.w = pk_h2(b[2], b[3]);
;                     *(u32x4*)(U1 + off + bj * 128) = w; } }
	v_pk_fma_f32 v[72:73], v[66:67], v[130:131], v[72:73]
	v_pk_fma_f32 v[66:67], v[64:65], v[128:129], v[74:75]
	v_cvt_pk_f16_f32 v64, v68, v69
	v_cvt_pk_f16_f32 v65, v70, v71
	v_cvt_pk_f16_f32 v66, v66, v67
	v_cvt_pk_f16_f32 v67, v72, v73
	global_store_dwordx4 v[76:77], v[64:67], off offset:256
	v_lshlrev_b64 v[96:97], 13, v[176:177]
	v_lshl_add_u64 v[108:109], v[162:163], 0, v[96:97]
	v_lshlrev_b64 v[64:65], 13, v[172:173]
	v_lshl_add_u64 v[76:77], v[162:163], 0, v[64:65]
	global_load_dwordx4 v[64:67], v[76:77], off
	global_load_dwordx4 v[68:71], v[76:77], off offset:16
	global_load_dwordx4 v[72:75], v[76:77], off offset:512
	s_nop 0
	global_load_dwordx4 v[76:79], v[76:77], off offset:528
	s_nop 0
	global_load_dwordx4 v[80:83], v[92:93], off
	global_load_dwordx4 v[84:87], v[92:93], off offset:16
	global_load_dwordx4 v[88:91], v[92:93], off offset:512
	s_nop 0
	global_load_dwordx4 v[92:95], v[92:93], off offset:528
	s_nop 0
	global_load_dwordx4 v[96:99], v[108:109], off
	global_load_dwordx4 v[100:103], v[108:109], off offset:16
	global_load_dwordx4 v[104:107], v[108:109], off offset:528
	s_nop 0
	global_load_dwordx4 v[108:111], v[108:109], off offset:512
	v_add_u32_e32 v164, 0xb0, v164
	v_ashrrev_i32_e32 v165, 31, v164
	v_lshlrev_b64 v[112:113], 13, v[164:165]
	v_lshl_add_u64 v[124:125], v[162:163], 0, v[112:113]
	global_load_dwordx4 v[112:115], v[124:125], off offset:16
	global_load_dwordx4 v[116:119], v[124:125], off
	global_load_dwordx4 v[120:123], v[124:125], off offset:528
	s_nop 0
	global_load_dwordx4 v[124:127], v[124:125], off offset:512
	v_lshlrev_b64 v[162:163], 12, v[172:173]
	s_waitcnt vmcnt(0)
; #define PG8_WAIT_V(n) asm volatile("s_waitcnt vmcnt(" #n ")" ::: "memory")
; #define PG8_BAR __builtin_amdgcn_s_barrier()
; template <class Epi, class Sched>
; __device__ __forceinline__ void gemm_phase(PG8_LAS unsigned char* lds, const Gemm g, const Sched& S, const Epi& E) {
;     ...
;         if (!has_next) break;
; #pragma unroll
;         for (int a = 0; a < 2; ++a)
; #pragma unroll
;             for (int b = 0; b < 2; ++b)
; #pragma unroll
;                 for (int m = 0; m < 4; ++m)
; #pragma unroll
;                     for (int n = 0; n < 2; ++n) acc[a][b][m][n] = (f32x4){0.f, 0.f, 0.f, 0.f};
;         cur = nxt; cA = nA; cB = nB; ++ui;
;     }
;     PG8_WAIT_V(0);
;     if (wr == 0) PG8_BAR;
;     PG8_BAR;
;     __device__ __forceinline__ void operator()(const AccT& acc, const pg8::Unit& u, int wr, int wc, int fr, int fq) const {
;     ...
;             for (int m = 0; m < 4; ++m) { const size_t off = (size_t)(row0 + ai * 128 + m * 16) * D + col0;
; #pragma unroll
;                 for (int bj = 0; bj < 2; ++bj) {
;                     const f32x4 a = ALPHA * xa[m][bj] + gv[bj][0] * acc[ai][bj][m][0], b = ALPHA * xb[m][bj] + gv[bj][1] * acc[ai][bj][m][1];
;                     u32x4 w; w.x = pk_h2(a[0], a[1]); w.y = pk_h2(a[2], a[3]); w.z = pk_h2(b[0], b[1]); w.w = pk_h2(b[2], b[3]);
;                     *(u32x4*)(U1 + off + bj * 128) = w; } }
	v_pk_mul_f32 v[66:67], v[66:67], s[8:9] op_sel_hi:[1,0]
	v_pk_mul_f32 v[64:65], v[64:65], s[8:9] op_sel_hi:[1,0]
	v_pk_fma_f32 v[62:63], v[62:63], v[142:143], v[66:67]
	v_pk_fma_f32 v[60:61], v[60:61], v[140:141], v[64:65]
	v_pk_mul_f32 v[64:65], v[70:71], s[8:9] op_sel_hi:[1,0]
	v_pk_mul_f32 v[66:67], v[68:69], s[8:9] op_sel_hi:[1,0]
	v_pk_fma_f32 v[64:65], v[58:59], v[138:139], v[64:65]
	v_pk_fma_f32 v[58:59], v[56:57], v[136:137], v[66:67]
	v_cvt_pk_f16_f32 v56, v60, v61
	v_lshl_add_u64 v[60:61], s[0:1], 0, v[162:163]
	v_cvt_pk_f16_f32 v57, v62, v63
	v_cvt_pk_f16_f32 v58, v58, v59
	v_cvt_pk_f16_f32 v59, v64, v65
	v_lshl_add_u64 v[60:61], v[60:61], 0, v[160:161]
	global_store_dwordx4 v[60:61], v[56:59], off
	s_nop 1
	v_pk_mul_f32 v[56:57], v[74:75], s[8:9] op_sel_hi:[1,0]
	v_pk_mul_f32 v[58:59], v[72:73], s[8:9] op_sel_hi:[1,0]
	v_pk_fma_f32 v[54:55], v[54:55], v[134:135], v[56:57]
	v_pk_fma_f32 v[52:53], v[52:53], v[132:133], v[58:59]
	v_pk_mul_f32 v[56:57], v[78:79], s[8:9] op_sel_hi:[1,0]
	v_pk_mul_f32 v[58:59], v[76:77], s[8:9] op_sel_hi:[1,0]
	v_pk_fma_f32 v[56:57], v[46:47], v[130:131], v[56:57]
	v_pk_fma_f32 v[46:47], v[44:45], v[128:129], v[58:59]
	v_cvt_pk_f16_f32 v44, v52, v53
	v_cvt_pk_f16_f32 v45, v54, v55
	v_cvt_pk_f16_f32 v46, v46, v47
	v_cvt_pk_f16_f32 v47, v56, v57
	global_store_dwordx4 v[60:61], v[44:47], off offset:256
	v_pk_mul_f32 v[52:53], v[80:81], s[8:9] op_sel_hi:[1,0]
	s_nop 0
	v_pk_mul_f32 v[46:47], v[82:83], s[8:9] op_sel_hi:[1,0]
	v_lshlrev_b64 v[44:45], 12, v[174:175]
	v_pk_fma_f32 v[46:47], v[50:51], v[142:143], v[46:47]
	v_pk_fma_f32 v[48:49], v[48:49], v[140:141], v[52:53]
	v_pk_mul_f32 v[50:51], v[86:87], s[8:9] op_sel_hi:[1,0]
	v_pk_mul_f32 v[52:53], v[84:85], s[8:9] op_sel_hi:[1,0]
	v_pk_fma_f32 v[50:51], v[42:43], v[138:139], v[50:51]
	v_pk_fma_f32 v[42:43], v[40:41], v[136:137], v[52:53]
	v_lshl_add_u64 v[44:45], s[0:1], 0, v[44:45]
	v_cvt_pk_f16_f32 v40, v48, v49
	v_cvt_pk_f16_f32 v41, v46, v47
	v_cvt_pk_f16_f32 v42, v42, v43
	v_cvt_pk_f16_f32 v43, v50, v51
	v_lshl_add_u64 v[44:45], v[44:45], 0, v[160:161]
	global_store_dwordx4 v[44:45], v[40:43], off
	s_nop 1
	v_pk_mul_f32 v[40:41], v[90:91], s[8:9] op_sel_hi:[1,0]
	v_pk_mul_f32 v[42:43], v[88:89], s[8:9] op_sel_hi:[1,0]
	v_pk_fma_f32 v[38:39], v[38:39], v[134:135], v[40:41]
	v_pk_fma_f32 v[36:37], v[36:37], v[132:133], v[42:43]
	v_pk_mul_f32 v[40:41], v[94:95], s[8:9] op_sel_hi:[1,0]
	v_pk_mul_f32 v[42:43], v[92:93], s[8:9] op_sel_hi:[1,0]
	v_pk_fma_f32 v[40:41], v[30:31], v[130:131], v[40:41]
	v_pk_fma_f32 v[30:31], v[28:29], v[128:129], v[42:43]
	v_cvt_pk_f16_f32 v28, v36, v37
	v_cvt_pk_f16_f32 v29, v38, v39
	v_cvt_pk_f16_f32 v30, v30, v31
	v_cvt_pk_f16_f32 v31, v40, v41
	global_store_dwordx4 v[44:45], v[28:31], off offset:256
	v_pk_mul_f32 v[36:37], v[96:97], s[8:9] op_sel_hi:[1,0]
	s_nop 0
	v_pk_mul_f32 v[30:31], v[98:99], s[8:9] op_sel_hi:[1,0]
	v_lshlrev_b64 v[28:29], 12, v[176:177]
	v_pk_fma_f32 v[30:31], v[34:35], v[142:143], v[30:31]
	v_pk_fma_f32 v[32:33], v[32:33], v[140:141], v[36:37]
	v_pk_mul_f32 v[34:35], v[102:103], s[8:9] op_sel_hi:[1,0]
	v_pk_mul_f32 v[36:37], v[100:101], s[8:9] op_sel_hi:[1,0]
	v_pk_fma_f32 v[34:35], v[26:27], v[138:139], v[34:35]
	v_pk_fma_f32 v[26:27], v[24:25], v[136:137], v[36:37]
	v_lshl_add_u64 v[28:29], s[0:1], 0, v[28:29]
	v_cvt_pk_f16_f32 v24, v32, v33
	v_cvt_pk_f16_f32 v25, v30, v31
	v_cvt_pk_f16_f32 v26, v26, v27
	v_cvt_pk_f16_f32 v27, v34, v35
	v_lshl_add_u64 v[28:29], v[28:29], 0, v[160:161]
	global_store_dwordx4 v[28:29], v[24:27], off
	s_nop 1
	v_pk_mul_f32 v[24:25], v[110:111], s[8:9] op_sel_hi:[1,0]
	v_pk_mul_f32 v[26:27], v[108:109], s[8:9] op_sel_hi:[1,0]
	v_pk_fma_f32 v[22:23], v[22:23], v[134:135], v[24:25]
	v_pk_fma_f32 v[20:21], v[20:21], v[132:133], v[26:27]
	v_pk_mul_f32 v[24:25], v[106:107], s[8:9] op_sel_hi:[1,0]
	v_pk_mul_f32 v[26:27], v[104:105], s[8:9] op_sel_hi:[1,0]
	v_pk_fma_f32 v[24:25], v[14:15], v[130:131], v[24:25]
	v_pk_fma_f32 v[14:15], v[12:13], v[128:129], v[26:27]
	v_cvt_pk_f16_f32 v12, v20, v21
	v_cvt_pk_f16_f32 v13, v22, v23
	v_cvt_pk_f16_f32 v14, v14, v15
	v_cvt_pk_f16_f32 v15, v24, v25
	global_store_dwordx4 v[28:29], v[12:15], off offset:256
	v_pk_mul_f32 v[20:21], v[116:117], s[8:9] op_sel_hi:[1,0]
	s_nop 0
	v_pk_mul_f32 v[14:15], v[118:119], s[8:9] op_sel_hi:[1,0]
	v_lshlrev_b64 v[12:13], 12, v[164:165]
	v_pk_fma_f32 v[14:15], v[18:19], v[142:143], v[14:15]
	v_pk_fma_f32 v[16:17], v[16:17], v[140:141], v[20:21]
	v_pk_mul_f32 v[18:19], v[114:115], s[8:9] op_sel_hi:[1,0]
	v_pk_mul_f32 v[20:21], v[112:113], s[8:9] op_sel_hi:[1,0]
	v_pk_fma_f32 v[18:19], v[10:11], v[138:139], v[18:19]
	v_pk_fma_f32 v[10:11], v[8:9], v[136:137], v[20:21]
	v_lshl_add_u64 v[12:13], s[0:1], 0, v[12:13]
	v_cvt_pk_f16_f32 v8, v16, v17
	v_cvt_pk_f16_f32 v9, v14, v15
	v_cvt_pk_f16_f32 v10, v10, v11
	v_cvt_pk_f16_f32 v11, v18, v19
	v_lshl_add_u64 v[12:13], v[12:13], 0, v[160:161]
	global_store_dwordx4 v[12:13], v[8:11], off
	s_nop 1
	v_pk_mul_f32 v[8:9], v[126:127], s[8:9] op_sel_hi:[1,0]
	v_pk_mul_f32 v[10:11], v[124:125], s[8:9] op_sel_hi:[1,0]
	v_pk_fma_f32 v[6:7], v[6:7], v[134:135], v[8:9]
	v_pk_fma_f32 v[4:5], v[4:5], v[132:133], v[10:11]
	v_pk_mul_f32 v[8:9], v[122:123], s[8:9] op_sel_hi:[1,0]
	v_pk_mul_f32 v[10:11], v[120:121], s[8:9] op_sel_hi:[1,0]
	v_pk_fma_f32 v[8:9], v[2:3], v[130:131], v[8:9]
	v_pk_fma_f32 v[2:3], v[0:1], v[128:129], v[10:11]
	v_cvt_pk_f16_f32 v0, v4, v5
	v_cvt_pk_f16_f32 v1, v6, v7
	v_cvt_pk_f16_f32 v2, v2, v3
	v_cvt_pk_f16_f32 v3, v8, v9
	global_store_dwordx4 v[12:13], v[0:3], off offset:256
	s_cbranch_vccz .LBB0_659
	s_waitcnt vmcnt(0)
	s_cmpk_gt_u32 s9, 0xff
	s_cbranch_scc1 .LBB0_670
	s_barrier

; #define PG8_STAGE(bufoff, gbase, voff) do { _Pragma("unroll") for (int _i = 0; _i < 2; ++_i) \
;         __builtin_amdgcn_global_load_lds((const unsigned*)((const char*)(gbase) + (voff)[_i]), (PG8_LAS unsigned*)(lds + (bufoff) + ldsw + _i * 8192), 16, 0, 0); } while (0)
; #define PG8_LDA(dst, b, h) do { _Pragma("unroll") for (int m = 0; m < 4; ++m) _Pragma("unroll") for (int k = 0; k < 2; ++k) dst[m][k] = *(const PG8_LAS bf16x8*)(lds + PG8_SA(b, h) + aoff + m * 2048 + k * 1024); } while (0)
; #define PG8_LDB(dst, b, h) do { _Pragma("unroll") for (int n = 0; n < 2; ++n) _Pragma("unroll") for (int k = 0; k < 2; ++k) dst[n][k] = *(const PG8_LAS bf16x8*)(lds + PG8_SB(b, h) + boff + n * 2048 + k * 1024); } while (0)
; #define PG8_WAIT_V(n) asm volatile("s_waitcnt vmcnt(" #n ")" ::: "memory")
; #define PG8_WAIT_L(n) asm volatile("s_waitcnt lgkmcnt(" #n ")" ::: "memory")
; #define PG8_BAR __builtin_amdgcn_s_barrier()
; #define PG8_SCHED __builtin_amdgcn_sched_barrier(0)
; template <class Epi, class Sched>
; __device__ __forceinline__ void gemm_phase(PG8_LAS unsigned char* lds, const Gemm g, const Sched& S, const Epi& E) {
;     ...
;         for (int t = 0; t < nt; t += 2) {
;             const bool last = (t == nt - 2);
;             const char* a1 = cA + (size_t)(t + 1) * kstep;
;             const char* a2 = last ? nA : cA + (size_t)(t + 2) * kstep; const char* b2 = last ? nB : cB + (size_t)(t + 2) * kstep;
;             const char* a3 = a2 + kstep; const char* b3 = b2 + kstep;
;             if (last && has_next) S.a_ready(nxt);
;             PG8_LDB(B0, 0, 0); PG8_SCHED; PG8_LDA(At, 0, 0); PG8_STAGE(PG8_SA(1, 1), a1 + hstep, voffA);
;             PG8_WAIT_L(8); PG8_BAR; PG8_WAIT_L(0); PG8_MMA(0, 0, At, B0); PG8_BAR; PG8_SCHED;
;             PG8_LDB(B1, 0, 1); PG8_STAGE(PG8_SB(0, 0), b2, voffB);
;             PG8_BAR; PG8_WAIT_L(0); PG8_MMA(0, 1, At, B1); PG8_BAR;
;             PG8_LDA(At, 0, 1); PG8_STAGE(PG8_SA(0, 0), a2, voffA);
;             PG8_BAR; PG8_WAIT_L(0); PG8_MMA(1, 0, At, B0); PG8_BAR; PG8_SCHED;
;             PG8_STAGE(PG8_SB(0, 1), b2 + hstep, voffB);
;             PG8_WAIT_V(6); PG8_BAR; PG8_MMA(1, 1, At, B1); PG8_BAR;
;             PG8_LDB(B0, 1, 0); PG8_SCHED; PG8_LDA(At, 1, 0); PG8_STAGE(PG8_SA(0, 1), a2 + hstep, voffA);
;             PG8_WAIT_L(8); PG8_BAR; PG8_WAIT_L(0); PG8_MMA(0, 0, At, B0); PG8_BAR; PG8_SCHED;
.LBB0_803:
	s_setprio 0
	ds_read_b128 v[150:153], v147
	ds_read_b128 v[154:157], v147 offset:1024
	ds_read_b128 v[158:161], v147 offset:2048
	ds_read_b128 v[162:165], v147 offset:3072
	ds_read_b128 v[166:169], v148
	ds_read_b128 v[170:173], v148 offset:1024
	ds_read_b128 v[174:177], v148 offset:2048
	ds_read_b128 v[178:181], v148 offset:3072
	ds_read_b128 v[182:185], v148 offset:4096
	ds_read_b128 v[186:189], v148 offset:5120
	ds_read_b128 v[190:193], v148 offset:6144
	ds_read_b128 v[194:197], v148 offset:7168
	ds_read_b128 v[198:201], v149
	ds_read_b128 v[202:205], v149 offset:1024
	ds_read_b128 v[206:209], v149 offset:2048
	ds_read_b128 v[210:213], v149 offset:3072
	s_add_u32 s10, s26, 0xfff80080
	s_addc_u32 s11, s27, -1
	s_cmp_eq_u32 s70, 28
	s_cselect_b32 s31, s9, s11
	s_cselect_b32 s30, s66, s10
	s_cselect_b32 s29, s7, s69
	s_cselect_b32 s28, s67, s68
	v_lshl_add_u64 v[222:223], s[26:27], 0, v[136:137]
	s_add_i32 m0, s21, 0xc000
	s_nop 0
	global_load_lds_dwordx4 v[222:223], off
	v_lshl_add_u64 v[222:223], s[26:27], 0, v[138:139]
	s_add_i32 m0, s21, 0xe000
	s_nop 0
	global_load_lds_dwordx4 v[222:223], off
	s_waitcnt vmcnt(8)
	s_waitcnt lgkmcnt(0)
	s_setprio 1
	s_barrier
	v_mfma_f32_16x16x32_bf16 v[124:127], v[150:153], v[166:169], v[124:127]
	v_mfma_f32_16x16x32_bf16 v[120:123], v[158:161], v[166:169], v[120:123]
	v_mfma_f32_16x16x32_bf16 v[108:111], v[150:153], v[174:177], v[108:111]
	v_mfma_f32_16x16x32_bf16 v[104:107], v[158:161], v[174:177], v[104:107]
	v_mfma_f32_16x16x32_bf16 v[92:95], v[150:153], v[182:185], v[92:95]
	v_mfma_f32_16x16x32_bf16 v[88:91], v[158:161], v[182:185], v[88:91]
	v_mfma_f32_16x16x32_bf16 v[76:79], v[150:153], v[190:193], v[76:79]
	v_mfma_f32_16x16x32_bf16 v[72:75], v[158:161], v[190:193], v[72:75]
	v_mfma_f32_16x16x32_bf16 v[124:127], v[154:157], v[170:173], v[124:127]
	v_mfma_f32_16x16x32_bf16 v[120:123], v[162:165], v[170:173], v[120:123]
	v_mfma_f32_16x16x32_bf16 v[108:111], v[154:157], v[178:181], v[108:111]
	v_mfma_f32_16x16x32_bf16 v[104:107], v[162:165], v[178:181], v[104:107]
	v_mfma_f32_16x16x32_bf16 v[92:95], v[154:157], v[186:189], v[92:95]
	v_mfma_f32_16x16x32_bf16 v[88:91], v[162:165], v[186:189], v[88:91]
	v_mfma_f32_16x16x32_bf16 v[76:79], v[154:157], v[194:197], v[76:79]
	v_mfma_f32_16x16x32_bf16 v[72:75], v[162:165], v[194:197], v[72:75]
	v_mfma_f32_16x16x32_bf16 v[116:119], v[198:201], v[166:169], v[116:119]
	v_mfma_f32_16x16x32_bf16 v[112:115], v[206:209], v[166:169], v[112:115]
	v_mfma_f32_16x16x32_bf16 v[100:103], v[198:201], v[174:177], v[100:103]
	v_mfma_f32_16x16x32_bf16 v[96:99], v[206:209], v[174:177], v[96:99]
	v_mfma_f32_16x16x32_bf16 v[84:87], v[198:201], v[182:185], v[84:87]
	v_mfma_f32_16x16x32_bf16 v[80:83], v[206:209], v[182:185], v[80:83]
	v_mfma_f32_16x16x32_bf16 v[68:71], v[198:201], v[190:193], v[68:71]
	v_mfma_f32_16x16x32_bf16 v[64:67], v[206:209], v[190:193], v[64:67]
	v_mfma_f32_16x16x32_bf16 v[116:119], v[202:205], v[170:173], v[116:119]
	v_mfma_f32_16x16x32_bf16 v[112:115], v[210:213], v[170:173], v[112:115]
	v_mfma_f32_16x16x32_bf16 v[100:103], v[202:205], v[178:181], v[100:103]
	v_mfma_f32_16x16x32_bf16 v[96:99], v[210:213], v[178:181], v[96:99]
	v_mfma_f32_16x16x32_bf16 v[84:87], v[202:205], v[186:189], v[84:87]
	v_mfma_f32_16x16x32_bf16 v[80:83], v[210:213], v[186:189], v[80:83]
	v_mfma_f32_16x16x32_bf16 v[68:71], v[202:205], v[194:197], v[68:71]
	v_mfma_f32_16x16x32_bf16 v[64:67], v[210:213], v[194:197], v[64:67]
	s_barrier
	s_setprio 0
	ds_read_b128 v[166:169], v148 offset:16384
	ds_read_b128 v[170:173], v148 offset:17408
	ds_read_b128 v[174:177], v148 offset:18432
	ds_read_b128 v[178:181], v148 offset:19456
	ds_read_b128 v[182:185], v148 offset:20480
	ds_read_b128 v[186:189], v148 offset:21504
	ds_read_b128 v[190:193], v148 offset:22528
	ds_read_b128 v[194:197], v148 offset:23552
	s_add_i32 s10, s50, s39
	v_lshl_add_u64 v[214:215], s[28:29], 0, v[132:133]
	s_mov_b32 m0, s10
	s_nop 0
	global_load_lds_dwordx4 v[214:215], off
	v_lshl_add_u64 v[216:217], s[28:29], 0, v[128:129]
	s_add_i32 m0, s10, 0x2000
	s_nop 0
	global_load_lds_dwordx4 v[216:217], off
	s_mov_b32 m0, s21
	v_lshl_add_u64 v[218:219], s[30:31], 0, v[134:135]
	global_load_lds_dwordx4 v[218:219], off
	v_lshl_add_u64 v[220:221], s[30:31], 0, v[130:131]
	s_mov_b32 m0, s42
	s_nop 0
	global_load_lds_dwordx4 v[220:221], off
	s_add_u32 s10, s28, 0x80000
	s_addc_u32 s11, s29, 0
	s_add_i32 s33, s51, s39
	v_lshl_add_u64 v[222:223], s[10:11], 0, v[132:133]
	s_mov_b32 m0, s33
	s_nop 0
	global_load_lds_dwordx4 v[222:223], off
	v_lshl_add_u64 v[222:223], s[10:11], 0, v[128:129]
	s_add_i32 m0, s33, 0x2000
	s_nop 0
	global_load_lds_dwordx4 v[222:223], off
	s_waitcnt vmcnt(8)
	s_waitcnt lgkmcnt(0)
	s_setprio 1
	s_barrier
; #define PG8_STAGE(bufoff, gbase, voff) do { _Pragma("unroll") for (int _i = 0; _i < 2; ++_i) \
;         __builtin_amdgcn_global_load_lds((const unsigned*)((const char*)(gbase) + (voff)[_i]), (PG8_LAS unsigned*)(lds + (bufoff) + ldsw + _i * 8192), 16, 0, 0); } while (0)
; #define PG8_LDA(dst, b, h) do { _Pragma("unroll") for (int m = 0; m < 4; ++m) _Pragma("unroll") for (int k = 0; k < 2; ++k) dst[m][k] = *(const PG8_LAS bf16x8*)(lds + PG8_SA(b, h) + aoff + m * 2048 + k * 1024); } while (0)
; #define PG8_LDB(dst, b, h) do { _Pragma("unroll") for (int n = 0; n < 2; ++n) _Pragma("unroll") for (int k = 0; k < 2; ++k) dst[n][k] = *(const PG8_LAS bf16x8*)(lds + PG8_SB(b, h) + boff + n * 2048 + k * 1024); } while (0)
; #define PG8_WAIT_V(n) asm volatile("s_waitcnt vmcnt(" #n ")" ::: "memory")
; #define PG8_WAIT_L(n) asm volatile("s_waitcnt lgkmcnt(" #n ")" ::: "memory")
; #define PG8_BAR __builtin_amdgcn_s_barrier()
; #define PG8_SCHED __builtin_amdgcn_sched_barrier(0)
; template <class Epi, class Sched>
; __device__ __forceinline__ void gemm_phase(PG8_LAS unsigned char* lds, const Gemm g, const Sched& S, const Epi& E) {
;     ...
;             PG8_LDB(B0, 0, 0); PG8_SCHED; PG8_LDA(At, 0, 0); PG8_STAGE(PG8_SA(1, 1), a1 + hstep, voffA);
;             PG8_WAIT_L(8); PG8_BAR; PG8_WAIT_L(0); PG8_MMA(0, 0, At, B0); PG8_BAR; PG8_SCHED;
;             PG8_LDB(B1, 0, 1); PG8_STAGE(PG8_SB(0, 0), b2, voffB);
;             PG8_BAR; PG8_WAIT_L(0); PG8_MMA(0, 1, At, B1); PG8_BAR;
;             PG8_LDA(At, 0, 1); PG8_STAGE(PG8_SA(0, 0), a2, voffA);
;             PG8_BAR; PG8_WAIT_L(0); PG8_MMA(1, 0, At, B0); PG8_BAR; PG8_SCHED;
;             PG8_STAGE(PG8_SB(0, 1), b2 + hstep, voffB);
;             PG8_WAIT_V(6); PG8_BAR; PG8_MMA(1, 1, At, B1); PG8_BAR;
;             PG8_LDB(B0, 1, 0); PG8_SCHED; PG8_LDA(At, 1, 0); PG8_STAGE(PG8_SA(0, 1), a2 + hstep, voffA);
;             PG8_WAIT_L(8); PG8_BAR; PG8_WAIT_L(0); PG8_MMA(0, 0, At, B0); PG8_BAR; PG8_SCHED;
;             PG8_LDB(B1, 1, 1); PG8_STAGE(PG8_SB(1, 0), b3, voffB);
;             PG8_BAR; PG8_WAIT_L(0); PG8_MMA(0, 1, At, B1); PG8_BAR;
;             PG8_LDA(At, 1, 1); PG8_STAGE(PG8_SA(1, 0), a3, voffA);
;             PG8_BAR; PG8_WAIT_L(0); PG8_MMA(1, 0, At, B0); PG8_BAR; PG8_SCHED;
;             PG8_STAGE(PG8_SB(1, 1), b3 + hstep, voffB);
;             PG8_WAIT_V(6); PG8_BAR; PG8_MMA(1, 1, At, B1); PG8_BAR;
	v_mfma_f32_16x16x32_bf16 v[60:63], v[150:153], v[166:169], v[60:63]
	v_mfma_f32_16x16x32_bf16 v[56:59], v[158:161], v[166:169], v[56:59]
	v_mfma_f32_16x16x32_bf16 v[44:47], v[150:153], v[174:177], v[44:47]
	v_mfma_f32_16x16x32_bf16 v[40:43], v[158:161], v[174:177], v[40:43]
	v_mfma_f32_16x16x32_bf16 v[28:31], v[150:153], v[182:185], v[28:31]
	v_mfma_f32_16x16x32_bf16 v[24:27], v[158:161], v[182:185], v[24:27]
	v_mfma_f32_16x16x32_bf16 v[12:15], v[150:153], v[190:193], v[12:15]
	v_mfma_f32_16x16x32_bf16 v[8:11], v[158:161], v[190:193], v[8:11]
	s_add_i32 s33, 0, 0x18000
	v_mfma_f32_16x16x32_bf16 v[60:63], v[154:157], v[170:173], v[60:63]
	v_mfma_f32_16x16x32_bf16 v[56:59], v[162:165], v[170:173], v[56:59]
	v_mfma_f32_16x16x32_bf16 v[44:47], v[154:157], v[178:181], v[44:47]
	v_mfma_f32_16x16x32_bf16 v[40:43], v[162:165], v[178:181], v[40:43]
	v_mfma_f32_16x16x32_bf16 v[28:31], v[154:157], v[186:189], v[28:31]
	v_mfma_f32_16x16x32_bf16 v[24:27], v[162:165], v[186:189], v[24:27]
	v_mfma_f32_16x16x32_bf16 v[12:15], v[154:157], v[194:197], v[12:15]
	v_mfma_f32_16x16x32_bf16 v[8:11], v[162:165], v[194:197], v[8:11]
	v_mfma_f32_16x16x32_bf16 v[52:55], v[198:201], v[166:169], v[52:55]
	v_mfma_f32_16x16x32_bf16 v[48:51], v[206:209], v[166:169], v[48:51]
	v_mfma_f32_16x16x32_bf16 v[36:39], v[198:201], v[174:177], v[36:39]
	v_mfma_f32_16x16x32_bf16 v[32:35], v[206:209], v[174:177], v[32:35]
	v_mfma_f32_16x16x32_bf16 v[20:23], v[198:201], v[182:185], v[20:23]
	v_mfma_f32_16x16x32_bf16 v[16:19], v[206:209], v[182:185], v[16:19]
	v_mfma_f32_16x16x32_bf16 v[4:7], v[198:201], v[190:193], v[4:7]
	v_mfma_f32_16x16x32_bf16 v[0:3], v[206:209], v[190:193], v[0:3]
	v_mfma_f32_16x16x32_bf16 v[52:55], v[202:205], v[170:173], v[52:55]
	v_mfma_f32_16x16x32_bf16 v[48:51], v[210:213], v[170:173], v[48:51]
	v_mfma_f32_16x16x32_bf16 v[36:39], v[202:205], v[178:181], v[36:39]
	v_mfma_f32_16x16x32_bf16 v[32:35], v[210:213], v[178:181], v[32:35]
	v_mfma_f32_16x16x32_bf16 v[20:23], v[202:205], v[186:189], v[20:23]
	v_mfma_f32_16x16x32_bf16 v[16:19], v[210:213], v[186:189], v[16:19]
	v_mfma_f32_16x16x32_bf16 v[4:7], v[202:205], v[194:197], v[4:7]
	v_mfma_f32_16x16x32_bf16 v[0:3], v[210:213], v[194:197], v[0:3]
	s_barrier
	s_setprio 0
	ds_read_b128 v[150:153], v147 offset:32768
	ds_read_b128 v[154:157], v147 offset:33792
	ds_read_b128 v[158:161], v147 offset:34816
	ds_read_b128 v[162:165], v147 offset:35840
	ds_read_b128 v[166:169], v148 offset:32768
	ds_read_b128 v[170:173], v148 offset:33792
	ds_read_b128 v[174:177], v148 offset:34816
	ds_read_b128 v[178:181], v148 offset:35840
	ds_read_b128 v[182:185], v148 offset:36864
	ds_read_b128 v[186:189], v148 offset:37888
	ds_read_b128 v[190:193], v148 offset:38912
	ds_read_b128 v[194:197], v148 offset:39936
	ds_read_b128 v[198:201], v149 offset:32768
	ds_read_b128 v[202:205], v149 offset:33792
	ds_read_b128 v[206:209], v149 offset:34816
	ds_read_b128 v[210:213], v149 offset:35840
	s_add_u32 s10, s30, 0x80000
	s_addc_u32 s11, s31, 0
	s_mov_b32 m0, s43
	v_lshl_add_u64 v[222:223], s[10:11], 0, v[134:135]
	global_load_lds_dwordx4 v[222:223], off
	v_lshl_add_u64 v[222:223], s[10:11], 0, v[130:131]
	s_mov_b32 m0, s44
	s_nop 0
	global_load_lds_dwordx4 v[222:223], off
	s_waitcnt vmcnt(8)
	s_waitcnt lgkmcnt(0)
	s_setprio 1
	s_barrier
	v_mfma_f32_16x16x32_bf16 v[124:127], v[150:153], v[166:169], v[124:127]
	v_mfma_f32_16x16x32_bf16 v[120:123], v[158:161], v[166:169], v[120:123]
	v_mfma_f32_16x16x32_bf16 v[108:111], v[150:153], v[174:177], v[108:111]
	v_mfma_f32_16x16x32_bf16 v[104:107], v[158:161], v[174:177], v[104:107]
	v_mfma_f32_16x16x32_bf16 v[92:95], v[150:153], v[182:185], v[92:95]
	v_mfma_f32_16x16x32_bf16 v[88:91], v[158:161], v[182:185], v[88:91]
	v_mfma_f32_16x16x32_bf16 v[76:79], v[150:153], v[190:193], v[76:79]
	v_mfma_f32_16x16x32_bf16 v[72:75], v[158:161], v[190:193], v[72:75]
	v_mfma_f32_16x16x32_bf16 v[124:127], v[154:157], v[170:173], v[124:127]
	v_mfma_f32_16x16x32_bf16 v[120:123], v[162:165], v[170:173], v[120:123]
	v_mfma_f32_16x16x32_bf16 v[108:111], v[154:157], v[178:181], v[108:111]
	v_mfma_f32_16x16x32_bf16 v[104:107], v[162:165], v[178:181], v[104:107]
	v_mfma_f32_16x16x32_bf16 v[92:95], v[154:157], v[186:189], v[92:95]
	v_mfma_f32_16x16x32_bf16 v[88:91], v[162:165], v[186:189], v[88:91]
	v_mfma_f32_16x16x32_bf16 v[76:79], v[154:157], v[194:197], v[76:79]
	v_mfma_f32_16x16x32_bf16 v[72:75], v[162:165], v[194:197], v[72:75]
	v_mfma_f32_16x16x32_bf16 v[116:119], v[198:201], v[166:169], v[116:119]
	v_mfma_f32_16x16x32_bf16 v[112:115], v[206:209], v[166:169], v[112:115]
	v_mfma_f32_16x16x32_bf16 v[100:103], v[198:201], v[174:177], v[100:103]
	v_mfma_f32_16x16x32_bf16 v[96:99], v[206:209], v[174:177], v[96:99]
	v_mfma_f32_16x16x32_bf16 v[84:87], v[198:201], v[182:185], v[84:87]
	v_mfma_f32_16x16x32_bf16 v[80:83], v[206:209], v[182:185], v[80:83]
	v_mfma_f32_16x16x32_bf16 v[68:71], v[198:201], v[190:193], v[68:71]
	v_mfma_f32_16x16x32_bf16 v[64:67], v[206:209], v[190:193], v[64:67]
	v_mfma_f32_16x16x32_bf16 v[116:119], v[202:205], v[170:173], v[116:119]
	v_mfma_f32_16x16x32_bf16 v[112:115], v[210:213], v[170:173], v[112:115]
	v_mfma_f32_16x16x32_bf16 v[100:103], v[202:205], v[178:181], v[100:103]
	v_mfma_f32_16x16x32_bf16 v[96:99], v[210:213], v[178:181], v[96:99]
	v_mfma_f32_16x16x32_bf16 v[84:87], v[202:205], v[186:189], v[84:87]
	v_mfma_f32_16x16x32_bf16 v[80:83], v[210:213], v[186:189], v[80:83]
	v_mfma_f32_16x16x32_bf16 v[68:71], v[202:205], v[194:197], v[68:71]
	v_mfma_f32_16x16x32_bf16 v[64:67], v[210:213], v[194:197], v[64:67]
	s_barrier
; __device__ __forceinline__ unsigned cvt_pk_bf16(float lo, float hi) { const bf16v2_t v = __builtin_convertvector((f32x2){lo, hi}, bf16v2_t); return __builtin_bit_cast(unsigned, v); }
; __device__ __forceinline__ float silu_f(float v) { return v * __builtin_amdgcn_rcpf(1.0f + __expf(-v)); }
; #define PG8_STAGE(bufoff, gbase, voff) do { _Pragma("unroll") for (int _i = 0; _i < 2; ++_i) \
;         __builtin_amdgcn_global_load_lds((const unsigned*)((const char*)(gbase) + (voff)[_i]), (PG8_LAS unsigned*)(lds + (bufoff) + ldsw + _i * 8192), 16, 0, 0); } while (0)
; #define PG8_WAIT_V(n) asm volatile("s_waitcnt vmcnt(" #n ")" ::: "memory")
; #define PG8_WAIT_L(n) asm volatile("s_waitcnt lgkmcnt(" #n ")" ::: "memory")
; template <class Epi, class Sched>
; __device__ __forceinline__ void gemm_phase(PG8_LAS unsigned char* lds, const Gemm g, const Sched& S, const Epi& E) {
;     ...
;             PG8_LDB(B0, 1, 0); PG8_SCHED; PG8_LDA(At, 1, 0); PG8_STAGE(PG8_SA(0, 1), a2 + hstep, voffA);
;             PG8_WAIT_L(8); PG8_BAR; PG8_WAIT_L(0); PG8_MMA(0, 0, At, B0); PG8_BAR; PG8_SCHED;
;             PG8_LDB(B1, 1, 1); PG8_STAGE(PG8_SB(1, 0), b3, voffB);
;             PG8_BAR; PG8_WAIT_L(0); PG8_MMA(0, 1, At, B1); PG8_BAR;
;             PG8_LDA(At, 1, 1); PG8_STAGE(PG8_SA(1, 0), a3, voffA);
;             PG8_BAR; PG8_WAIT_L(0); PG8_MMA(1, 0, At, B0); PG8_BAR; PG8_SCHED;
;             PG8_STAGE(PG8_SB(1, 1), b3 + hstep, voffB);
;             PG8_WAIT_V(6); PG8_BAR; PG8_MMA(1, 1, At, B1); PG8_BAR;
;         }
;         E(acc, cur, wr, wc, fr, fq); S.done(cur);
;     __device__ __forceinline__ void operator()(const AccT& acc, const pg8::Unit& u, int wr, int wc, int fr, int fq) const {
;         const int row0 = u.pm * 256 + wr * 64 + fr, col = u.pn * 128 + wc * 32 + 8 * fq;
; #pragma unroll
;         for (int ai = 0; ai < 2; ++ai)
; #pragma unroll
;             for (int m = 0; m < 4; ++m) {
;                 f32x4 a = acc[ai][0][m][0], b = acc[ai][0][m][1];
; #pragma unroll
;                 for (int j = 0; j < 4; ++j) { a[j] = silu_f(a[j]) * acc[ai][1][m][0][j]; b[j] = silu_f(b[j]) * acc[ai][1][m][1][j]; }
;                 u32x4 w; w.x = cvt_pk_bf16(a[0], a[1]); w.y = cvt_pk_bf16(a[2], a[3]); w.z = cvt_pk_bf16(b[0], b[1]); w.w = cvt_pk_bf16(b[2], b[3]);
;                 *(u32x4*)(HID + (size_t)(row0 + ai * 128 + m * 16) * DFF + col) = w;
	s_setprio 0
	ds_read_b128 v[166:169], v148 offset:49152
	ds_read_b128 v[170:173], v148 offset:50176
	ds_read_b128 v[174:177], v148 offset:51200
	ds_read_b128 v[178:181], v148 offset:52224
	ds_read_b128 v[182:185], v148 offset:53248
	ds_read_b128 v[186:189], v148 offset:54272
	ds_read_b128 v[190:193], v148 offset:55296
	ds_read_b128 v[194:197], v148 offset:56320
	s_add_i32 s30, 0, 0x1c000
	s_add_i32 s10, s33, s39
	v_lshl_add_u64 v[214:215], v[214:215], 0, s[4:5]
	s_mov_b32 m0, s10
	s_nop 0
	global_load_lds_dwordx4 v[214:215], off
	v_lshl_add_u64 v[214:215], v[216:217], 0, s[4:5]
	s_add_i32 m0, s10, 0x2000
	s_nop 0
	global_load_lds_dwordx4 v[214:215], off
	s_mov_b32 m0, s46
	v_lshl_add_u64 v[214:215], v[218:219], 0, s[4:5]
	global_load_lds_dwordx4 v[214:215], off
	v_lshl_add_u64 v[214:215], v[220:221], 0, s[4:5]
	s_mov_b32 m0, s47
	s_nop 0
	global_load_lds_dwordx4 v[214:215], off
	s_add_u32 s10, s28, 0x80080
	s_addc_u32 s11, s29, 0
	s_add_i32 s28, s30, s39
	v_lshl_add_u64 v[222:223], s[10:11], 0, v[132:133]
	s_mov_b32 m0, s28
	s_nop 0
	global_load_lds_dwordx4 v[222:223], off
	v_lshl_add_u64 v[222:223], s[10:11], 0, v[128:129]
	s_add_i32 m0, s28, 0x2000
	s_nop 0
	global_load_lds_dwordx4 v[222:223], off
	s_waitcnt vmcnt(8)
	s_waitcnt lgkmcnt(0)
	s_setprio 1
	s_barrier
	v_mfma_f32_16x16x32_bf16 v[60:63], v[150:153], v[166:169], v[60:63]
	v_mfma_f32_16x16x32_bf16 v[56:59], v[158:161], v[166:169], v[56:59]
	v_mfma_f32_16x16x32_bf16 v[44:47], v[150:153], v[174:177], v[44:47]
	v_mfma_f32_16x16x32_bf16 v[40:43], v[158:161], v[174:177], v[40:43]
	v_mfma_f32_16x16x32_bf16 v[28:31], v[150:153], v[182:185], v[28:31]
	v_mfma_f32_16x16x32_bf16 v[24:27], v[158:161], v[182:185], v[24:27]
	v_mfma_f32_16x16x32_bf16 v[12:15], v[150:153], v[190:193], v[12:15]
	v_mfma_f32_16x16x32_bf16 v[8:11], v[158:161], v[190:193], v[8:11]
	s_add_i32 s70, s70, 2
	s_add_u32 s26, s26, 0x100
	s_addc_u32 s27, s27, 0
	s_add_u32 s68, s68, 0x100
	s_addc_u32 s69, s69, 0
	s_cmp_gt_u32 s70, 29
	v_mfma_f32_16x16x32_bf16 v[60:63], v[154:157], v[170:173], v[60:63]
	v_mfma_f32_16x16x32_bf16 v[56:59], v[162:165], v[170:173], v[56:59]
	v_mfma_f32_16x16x32_bf16 v[44:47], v[154:157], v[178:181], v[44:47]
	v_mfma_f32_16x16x32_bf16 v[40:43], v[162:165], v[178:181], v[40:43]
	v_mfma_f32_16x16x32_bf16 v[28:31], v[154:157], v[186:189], v[28:31]
	v_mfma_f32_16x16x32_bf16 v[24:27], v[162:165], v[186:189], v[24:27]
	v_mfma_f32_16x16x32_bf16 v[12:15], v[154:157], v[194:197], v[12:15]
	v_mfma_f32_16x16x32_bf16 v[8:11], v[162:165], v[194:197], v[8:11]
	v_mfma_f32_16x16x32_bf16 v[52:55], v[198:201], v[166:169], v[52:55]
	v_mfma_f32_16x16x32_bf16 v[48:51], v[206:209], v[166:169], v[48:51]
	v_mfma_f32_16x16x32_bf16 v[36:39], v[198:201], v[174:177], v[36:39]
	v_mfma_f32_16x16x32_bf16 v[32:35], v[206:209], v[174:177], v[32:35]
	v_mfma_f32_16x16x32_bf16 v[20:23], v[198:201], v[182:185], v[20:23]
	v_mfma_f32_16x16x32_bf16 v[16:19], v[206:209], v[182:185], v[16:19]
	v_mfma_f32_16x16x32_bf16 v[4:7], v[198:201], v[190:193], v[4:7]
	v_mfma_f32_16x16x32_bf16 v[0:3], v[206:209], v[190:193], v[0:3]
	v_mfma_f32_16x16x32_bf16 v[52:55], v[202:205], v[170:173], v[52:55]
	v_mfma_f32_16x16x32_bf16 v[48:51], v[210:213], v[170:173], v[48:51]
	v_mfma_f32_16x16x32_bf16 v[36:39], v[202:205], v[178:181], v[36:39]
	v_mfma_f32_16x16x32_bf16 v[32:35], v[210:213], v[178:181], v[32:35]
	v_mfma_f32_16x16x32_bf16 v[20:23], v[202:205], v[186:189], v[20:23]
	v_mfma_f32_16x16x32_bf16 v[16:19], v[210:213], v[186:189], v[16:19]
	v_mfma_f32_16x16x32_bf16 v[4:7], v[202:205], v[194:197], v[4:7]
	v_mfma_f32_16x16x32_bf16 v[0:3], v[210:213], v[194:197], v[0:3]
	s_barrier
	s_cbranch_scc0 .LBB0_803
	s_setprio 0
	v_mul_f32_e32 v151, 0xbfb8aa3b, v124
	v_mul_f32_e32 v154, 0xbfb8aa3b, v120
	v_exp_f32_e32 v151, v151
	v_exp_f32_e32 v155, v154
	v_mul_f32_e32 v154, 0xbfb8aa3b, v125
	v_exp_f32_e32 v156, v154
	v_add_f32_e32 v151, 1.0, v151
	v_rcp_f32_e32 v154, v151
	v_add_f32_e32 v151, 1.0, v155
	v_add_f32_e32 v155, 1.0, v156
	v_rcp_f32_e32 v155, v155
	v_mul_f32_e32 v156, 0xbfb8aa3b, v121
	v_exp_f32_e32 v157, v156
	v_rcp_f32_e32 v156, v151
	v_pk_mul_f32 v[124:125], v[124:125], v[154:155]
	v_mul_f32_e32 v151, 0xbfb8aa3b, v127
	v_pk_mul_f32 v[116:117], v[124:125], v[116:117]
	v_add_f32_e32 v124, 1.0, v157
	v_mul_f32_e32 v125, 0xbfb8aa3b, v122
	v_rcp_f32_e32 v157, v124
	v_mul_f32_e32 v124, 0xbfb8aa3b, v126
	v_exp_f32_e32 v125, v125
	v_exp_f32_e32 v124, v124
	v_exp_f32_e32 v151, v151
	v_mul_f32_e32 v154, 0xbfb8aa3b, v123
	v_exp_f32_e32 v155, v154
	v_add_f32_e32 v125, 1.0, v125
	v_add_f32_e32 v124, 1.0, v124
	v_rcp_f32_e32 v154, v125
	v_add_f32_e32 v125, 1.0, v151
	v_rcp_f32_e32 v124, v124
	v_rcp_f32_e32 v125, v125
	v_add_f32_e32 v151, 1.0, v155
	v_rcp_f32_e32 v155, v151
	v_pk_mul_f32 v[120:121], v[120:121], v[156:157]
	v_lshl_or_b32 v152, s65, 7, v146
	v_pk_mul_f32 v[112:113], v[120:121], v[112:113]
	v_pk_mul_f32 v[120:121], v[126:127], v[124:125]
	v_lshl_add_u32 v150, s20, 8, v144
	v_pk_mul_f32 v[118:119], v[120:121], v[118:119]
	v_pk_mul_f32 v[120:121], v[122:123], v[154:155]
	v_ashrrev_i32_e32 v153, 31, v152
	v_pk_mul_f32 v[114:115], v[120:121], v[114:115]
	v_cvt_pk_bf16_f32 v116, v116, v117
	v_cvt_pk_bf16_f32 v117, v118, v119
	v_cvt_pk_bf16_f32 v118, v112, v113
	v_mov_b64_e32 v[112:113], s[0:1]
	v_cvt_pk_bf16_f32 v119, v114, v115
	v_mad_i64_i32 v[120:121], s[10:11], v150, s64, v[112:113]
	v_lshlrev_b64 v[114:115], 1, v[152:153]
	v_lshl_add_u64 v[120:121], v[120:121], 0, v[114:115]
	global_store_dwordx4 v[120:121], v[116:119], off
	s_and_b64 vcc, exec, s[2:3]
	s_mov_b32 s65, s6
	v_mul_f32_e32 v116, 0xbfb8aa3b, v108
	v_mul_f32_e32 v117, 0xbfb8aa3b, v104
; __device__ __forceinline__ unsigned cvt_pk_bf16(float lo, float hi) { const bf16v2_t v = __builtin_convertvector((f32x2){lo, hi}, bf16v2_t); return __builtin_bit_cast(unsigned, v); }
; __device__ __forceinline__ float silu_f(float v) { return v * __builtin_amdgcn_rcpf(1.0f + __expf(-v)); }
;     __device__ __forceinline__ void operator()(const AccT& acc, const pg8::Unit& u, int wr, int wc, int fr, int fq) const {
;     ...
;         for (int ai = 0; ai < 2; ++ai)
; #pragma unroll
;             for (int m = 0; m < 4; ++m) {
;                 f32x4 a = acc[ai][0][m][0], b = acc[ai][0][m][1];
; #pragma unroll
;                 for (int j = 0; j < 4; ++j) { a[j] = silu_f(a[j]) * acc[ai][1][m][0][j]; b[j] = silu_f(b[j]) * acc[ai][1][m][1][j]; }
;                 u32x4 w; w.x = cvt_pk_bf16(a[0], a[1]); w.y = cvt_pk_bf16(a[2], a[3]); w.z = cvt_pk_bf16(b[0], b[1]); w.w = cvt_pk_bf16(b[2], b[3]);
;                 *(u32x4*)(HID + (size_t)(row0 + ai * 128 + m * 16) * DFF + col) = w;
	v_mul_f32_e32 v118, 0xbfb8aa3b, v109
	v_exp_f32_e32 v116, v116
	v_exp_f32_e32 v117, v117
	v_exp_f32_e32 v118, v118
	s_mov_b32 s20, s8
	v_add_f32_e32 v116, 1.0, v116
	v_add_f32_e32 v119, 1.0, v117
	v_add_f32_e32 v117, 1.0, v118
	v_rcp_f32_e32 v116, v116
	v_rcp_f32_e32 v117, v117
	v_mul_f32_e32 v118, 0xbfb8aa3b, v105
	v_exp_f32_e32 v120, v118
	v_rcp_f32_e32 v118, v119
	v_pk_mul_f32 v[108:109], v[108:109], v[116:117]
	v_mul_f32_e32 v116, 0xbfb8aa3b, v111
	v_pk_mul_f32 v[100:101], v[108:109], v[100:101]
	v_add_f32_e32 v108, 1.0, v120
	v_rcp_f32_e32 v119, v108
	v_mul_f32_e32 v109, 0xbfb8aa3b, v106
	v_mul_f32_e32 v108, 0xbfb8aa3b, v110
	v_exp_f32_e32 v109, v109
	v_exp_f32_e32 v108, v108
	v_exp_f32_e32 v117, v116
	v_mul_f32_e32 v116, 0xbfb8aa3b, v107
	v_pk_mul_f32 v[104:105], v[104:105], v[118:119]
	v_exp_f32_e32 v118, v116
	v_add_f32_e32 v109, 1.0, v109
	v_add_f32_e32 v108, 1.0, v108
	v_rcp_f32_e32 v116, v109
	v_add_f32_e32 v109, 1.0, v117
	v_rcp_f32_e32 v108, v108
	v_rcp_f32_e32 v109, v109
	v_add_f32_e32 v117, 1.0, v118
	v_rcp_f32_e32 v117, v117
	v_pk_mul_f32 v[104:105], v[104:105], v[96:97]
	v_pk_mul_f32 v[96:97], v[110:111], v[108:109]
	s_mov_b64 s[28:29], s[18:19]
	v_pk_mul_f32 v[102:103], v[96:97], v[102:103]
	v_pk_mul_f32 v[96:97], v[106:107], v[116:117]
	s_mov_b64 s[26:27], s[16:17]
	v_pk_mul_f32 v[106:107], v[96:97], v[98:99]
	v_cvt_pk_bf16_f32 v96, v100, v101
	v_or_b32_e32 v100, 16, v150
	v_mad_i64_i32 v[100:101], s[10:11], v100, s64, v[112:113]
	v_cvt_pk_bf16_f32 v97, v102, v103
	v_cvt_pk_bf16_f32 v98, v104, v105
	v_cvt_pk_bf16_f32 v99, v106, v107
	v_lshl_add_u64 v[100:101], v[100:101], 0, v[114:115]
	global_store_dwordx4 v[100:101], v[96:99], off
	s_nop 1
	v_mul_f32_e32 v96, 0xbfb8aa3b, v92
	v_mul_f32_e32 v97, 0xbfb8aa3b, v88
	v_mul_f32_e32 v98, 0xbfb8aa3b, v93
	v_exp_f32_e32 v96, v96
	v_exp_f32_e32 v97, v97
	v_exp_f32_e32 v98, v98
	v_add_f32_e32 v96, 1.0, v96
	v_add_f32_e32 v99, 1.0, v97
	v_add_f32_e32 v97, 1.0, v98
	v_rcp_f32_e32 v96, v96
	v_rcp_f32_e32 v97, v97
	v_mul_f32_e32 v98, 0xbfb8aa3b, v89
	v_exp_f32_e32 v100, v98
	v_rcp_f32_e32 v98, v99
	v_pk_mul_f32 v[92:93], v[92:93], v[96:97]
	v_mul_f32_e32 v96, 0xbfb8aa3b, v95
	v_pk_mul_f32 v[84:85], v[92:93], v[84:85]
	v_add_f32_e32 v92, 1.0, v100
	v_rcp_f32_e32 v99, v92
	v_mul_f32_e32 v93, 0xbfb8aa3b, v90
	v_mul_f32_e32 v92, 0xbfb8aa3b, v94
	v_exp_f32_e32 v93, v93
	v_exp_f32_e32 v92, v92
	v_exp_f32_e32 v97, v96
	v_mul_f32_e32 v96, 0xbfb8aa3b, v91
	v_pk_mul_f32 v[88:89], v[88:89], v[98:99]
	v_exp_f32_e32 v98, v96
	v_add_f32_e32 v93, 1.0, v93
	v_add_f32_e32 v92, 1.0, v92
	v_rcp_f32_e32 v96, v93
	v_add_f32_e32 v93, 1.0, v97
	v_rcp_f32_e32 v92, v92
	v_rcp_f32_e32 v93, v93
	v_add_f32_e32 v97, 1.0, v98
	v_rcp_f32_e32 v97, v97
	v_pk_mul_f32 v[88:89], v[88:89], v[80:81]
	v_pk_mul_f32 v[80:81], v[94:95], v[92:93]
	s_nop 0
	v_pk_mul_f32 v[86:87], v[80:81], v[86:87]
	v_pk_mul_f32 v[80:81], v[90:91], v[96:97]
	s_nop 0
	v_pk_mul_f32 v[90:91], v[80:81], v[82:83]
	v_cvt_pk_bf16_f32 v80, v84, v85
	v_or_b32_e32 v84, 32, v150
	v_mad_i64_i32 v[84:85], s[10:11], v84, s64, v[112:113]
	v_cvt_pk_bf16_f32 v81, v86, v87
	v_cvt_pk_bf16_f32 v82, v88, v89
	v_cvt_pk_bf16_f32 v83, v90, v91
	v_lshl_add_u64 v[84:85], v[84:85], 0, v[114:115]
	global_store_dwordx4 v[84:85], v[80:83], off
	s_nop 1
	v_mul_f32_e32 v80, 0xbfb8aa3b, v76
	v_mul_f32_e32 v81, 0xbfb8aa3b, v72
	v_mul_f32_e32 v82, 0xbfb8aa3b, v77
	v_exp_f32_e32 v80, v80
	v_exp_f32_e32 v81, v81
	v_exp_f32_e32 v82, v82
	v_add_f32_e32 v80, 1.0, v80
	v_add_f32_e32 v83, 1.0, v81
	v_add_f32_e32 v81, 1.0, v82
	v_rcp_f32_e32 v80, v80
	v_rcp_f32_e32 v81, v81
	v_mul_f32_e32 v82, 0xbfb8aa3b, v73
	v_exp_f32_e32 v84, v82
	v_rcp_f32_e32 v82, v83
	v_pk_mul_f32 v[76:77], v[76:77], v[80:81]
	v_mul_f32_e32 v80, 0xbfb8aa3b, v79
	v_pk_mul_f32 v[68:69], v[76:77], v[68:69]
	v_add_f32_e32 v76, 1.0, v84
	v_rcp_f32_e32 v83, v76
	v_mul_f32_e32 v77, 0xbfb8aa3b, v74
	v_mul_f32_e32 v76, 0xbfb8aa3b, v78
	v_exp_f32_e32 v77, v77
	v_exp_f32_e32 v76, v76
	v_exp_f32_e32 v81, v80
	v_mul_f32_e32 v80, 0xbfb8aa3b, v75
	v_pk_mul_f32 v[72:73], v[72:73], v[82:83]
	v_exp_f32_e32 v82, v80
	v_add_f32_e32 v77, 1.0, v77
	v_add_f32_e32 v76, 1.0, v76
	v_rcp_f32_e32 v80, v77
	v_add_f32_e32 v77, 1.0, v81
	v_rcp_f32_e32 v76, v76
	v_rcp_f32_e32 v77, v77
	v_add_f32_e32 v81, 1.0, v82
	v_rcp_f32_e32 v81, v81
	v_pk_mul_f32 v[72:73], v[72:73], v[64:65]
	v_pk_mul_f32 v[64:65], v[78:79], v[76:77]
	s_nop 0
	v_pk_mul_f32 v[70:71], v[64:65], v[70:71]
	v_pk_mul_f32 v[64:65], v[74:75], v[80:81]
	s_nop 0
	v_pk_mul_f32 v[74:75], v[64:65], v[66:67]
	v_cvt_pk_bf16_f32 v64, v68, v69
	v_or_b32_e32 v68, 48, v150
	v_mad_i64_i32 v[68:69], s[10:11], v68, s64, v[112:113]
	v_cvt_pk_bf16_f32 v65, v70, v71
	v_cvt_pk_bf16_f32 v66, v72, v73
	v_cvt_pk_bf16_f32 v67, v74, v75
	v_lshl_add_u64 v[68:69], v[68:69], 0, v[114:115]
	global_store_dwordx4 v[68:69], v[64:67], off
	v_add_u32_e32 v68, 0x80, v150
	s_nop 0
	v_mul_f32_e32 v64, 0xbfb8aa3b, v60
	v_mul_f32_e32 v65, 0xbfb8aa3b, v56
	v_mul_f32_e32 v66, 0xbfb8aa3b, v61
	v_exp_f32_e32 v64, v64
	v_exp_f32_e32 v65, v65
	v_exp_f32_e32 v66, v66
	v_add_f32_e32 v64, 1.0, v64
	v_add_f32_e32 v67, 1.0, v65
	v_add_f32_e32 v65, 1.0, v66
	v_rcp_f32_e32 v64, v64
	v_rcp_f32_e32 v65, v65
	v_mul_f32_e32 v66, 0xbfb8aa3b, v57
	v_exp_f32_e32 v69, v66
	v_rcp_f32_e32 v66, v67
	v_pk_mul_f32 v[60:61], v[60:61], v[64:65]
	v_mul_f32_e32 v64, 0xbfb8aa3b, v63
	v_pk_mul_f32 v[52:53], v[60:61], v[52:53]
	v_add_f32_e32 v60, 1.0, v69
	v_rcp_f32_e32 v67, v60
	v_mul_f32_e32 v61, 0xbfb8aa3b, v58
	v_mul_f32_e32 v60, 0xbfb8aa3b, v62
	v_exp_f32_e32 v61, v61
	v_exp_f32_e32 v60, v60
	v_exp_f32_e32 v65, v64
	v_mul_f32_e32 v64, 0xbfb8aa3b, v59
; __device__ __forceinline__ unsigned cvt_pk_bf16(float lo, float hi) { const bf16v2_t v = __builtin_convertvector((f32x2){lo, hi}, bf16v2_t); return __builtin_bit_cast(unsigned, v); }
; __device__ __forceinline__ float silu_f(float v) { return v * __builtin_amdgcn_rcpf(1.0f + __expf(-v)); }
; #define PG8_WAIT_V(n) asm volatile("s_waitcnt vmcnt(" #n ")" ::: "memory")
; #define PG8_BAR __builtin_amdgcn_s_barrier()
; template <class Epi, class Sched>
; __device__ __forceinline__ void gemm_phase(PG8_LAS unsigned char* lds, const Gemm g, const Sched& S, const Epi& E) {
;     ...
;         if (!has_next) break;
; #pragma unroll
;         for (int a = 0; a < 2; ++a)
; #pragma unroll
;             for (int b = 0; b < 2; ++b)
; #pragma unroll
;                 for (int m = 0; m < 4; ++m)
; #pragma unroll
;                     for (int n = 0; n < 2; ++n) acc[a][b][m][n] = (f32x4){0.f, 0.f, 0.f, 0.f};
;         cur = nxt; cA = nA; cB = nB; ++ui;
;     }
;     PG8_WAIT_V(0);
;     if (wr == 0) PG8_BAR;
;     PG8_BAR;
;     __device__ __forceinline__ void operator()(const AccT& acc, const pg8::Unit& u, int wr, int wc, int fr, int fq) const {
;     ...
;         for (int ai = 0; ai < 2; ++ai)
; #pragma unroll
;             for (int m = 0; m < 4; ++m) {
;                 f32x4 a = acc[ai][0][m][0], b = acc[ai][0][m][1];
; #pragma unroll
;                 for (int j = 0; j < 4; ++j) { a[j] = silu_f(a[j]) * acc[ai][1][m][0][j]; b[j] = silu_f(b[j]) * acc[ai][1][m][1][j]; }
;                 u32x4 w; w.x = cvt_pk_bf16(a[0], a[1]); w.y = cvt_pk_bf16(a[2], a[3]); w.z = cvt_pk_bf16(b[0], b[1]); w.w = cvt_pk_bf16(b[2], b[3]);
;                 *(u32x4*)(HID + (size_t)(row0 + ai * 128 + m * 16) * DFF + col) = w;
	v_pk_mul_f32 v[56:57], v[56:57], v[66:67]
	v_exp_f32_e32 v66, v64
	v_add_f32_e32 v61, 1.0, v61
	v_add_f32_e32 v60, 1.0, v60
	v_rcp_f32_e32 v64, v61
	v_add_f32_e32 v61, 1.0, v65
	v_rcp_f32_e32 v60, v60
	v_rcp_f32_e32 v61, v61
	v_add_f32_e32 v65, 1.0, v66
	v_rcp_f32_e32 v65, v65
	v_pk_mul_f32 v[56:57], v[56:57], v[48:49]
	v_pk_mul_f32 v[48:49], v[62:63], v[60:61]
	s_nop 0
	v_pk_mul_f32 v[54:55], v[48:49], v[54:55]
	v_pk_mul_f32 v[48:49], v[58:59], v[64:65]
	s_nop 0
	v_pk_mul_f32 v[58:59], v[48:49], v[50:51]
	v_cvt_pk_bf16_f32 v48, v52, v53
	v_mad_i64_i32 v[52:53], s[10:11], v68, s64, v[112:113]
	v_cvt_pk_bf16_f32 v49, v54, v55
	v_cvt_pk_bf16_f32 v50, v56, v57
	v_cvt_pk_bf16_f32 v51, v58, v59
	v_lshl_add_u64 v[52:53], v[52:53], 0, v[114:115]
	global_store_dwordx4 v[52:53], v[48:51], off
	s_nop 1
	v_mul_f32_e32 v48, 0xbfb8aa3b, v44
	v_mul_f32_e32 v49, 0xbfb8aa3b, v40
	v_mul_f32_e32 v50, 0xbfb8aa3b, v45
	v_exp_f32_e32 v48, v48
	v_exp_f32_e32 v49, v49
	v_exp_f32_e32 v50, v50
	v_add_f32_e32 v48, 1.0, v48
	v_add_f32_e32 v51, 1.0, v49
	v_add_f32_e32 v49, 1.0, v50
	v_rcp_f32_e32 v48, v48
	v_rcp_f32_e32 v49, v49
	v_mul_f32_e32 v50, 0xbfb8aa3b, v41
	v_exp_f32_e32 v52, v50
	v_rcp_f32_e32 v50, v51
	v_pk_mul_f32 v[44:45], v[44:45], v[48:49]
	v_mul_f32_e32 v48, 0xbfb8aa3b, v47
	v_pk_mul_f32 v[36:37], v[44:45], v[36:37]
	v_add_f32_e32 v44, 1.0, v52
	v_rcp_f32_e32 v51, v44
	v_mul_f32_e32 v45, 0xbfb8aa3b, v42
	v_mul_f32_e32 v44, 0xbfb8aa3b, v46
	v_exp_f32_e32 v45, v45
	v_exp_f32_e32 v44, v44
	v_exp_f32_e32 v49, v48
	v_mul_f32_e32 v48, 0xbfb8aa3b, v43
	v_pk_mul_f32 v[40:41], v[40:41], v[50:51]
	v_exp_f32_e32 v50, v48
	v_add_f32_e32 v45, 1.0, v45
	v_add_f32_e32 v44, 1.0, v44
	v_rcp_f32_e32 v48, v45
	v_add_f32_e32 v45, 1.0, v49
	v_rcp_f32_e32 v44, v44
	v_rcp_f32_e32 v45, v45
	v_add_f32_e32 v49, 1.0, v50
	v_rcp_f32_e32 v49, v49
	v_pk_mul_f32 v[40:41], v[40:41], v[32:33]
	v_pk_mul_f32 v[32:33], v[46:47], v[44:45]
	s_nop 0
	v_pk_mul_f32 v[38:39], v[32:33], v[38:39]
	v_pk_mul_f32 v[32:33], v[42:43], v[48:49]
	s_nop 0
	v_pk_mul_f32 v[42:43], v[32:33], v[34:35]
	v_cvt_pk_bf16_f32 v32, v36, v37
	v_add_u32_e32 v36, 0x90, v150
	v_mad_i64_i32 v[36:37], s[10:11], v36, s64, v[112:113]
	v_cvt_pk_bf16_f32 v33, v38, v39
	v_cvt_pk_bf16_f32 v34, v40, v41
	v_cvt_pk_bf16_f32 v35, v42, v43
	v_lshl_add_u64 v[36:37], v[36:37], 0, v[114:115]
	global_store_dwordx4 v[36:37], v[32:35], off
	s_nop 1
	v_mul_f32_e32 v32, 0xbfb8aa3b, v28
	v_mul_f32_e32 v33, 0xbfb8aa3b, v24
	v_mul_f32_e32 v34, 0xbfb8aa3b, v29
	v_exp_f32_e32 v32, v32
	v_exp_f32_e32 v33, v33
	v_exp_f32_e32 v34, v34
	v_add_f32_e32 v32, 1.0, v32
	v_add_f32_e32 v35, 1.0, v33
	v_add_f32_e32 v33, 1.0, v34
	v_rcp_f32_e32 v32, v32
	v_rcp_f32_e32 v33, v33
	v_mul_f32_e32 v34, 0xbfb8aa3b, v25
	v_exp_f32_e32 v36, v34
	v_rcp_f32_e32 v34, v35
	v_pk_mul_f32 v[28:29], v[28:29], v[32:33]
	v_mul_f32_e32 v32, 0xbfb8aa3b, v31
	v_pk_mul_f32 v[20:21], v[28:29], v[20:21]
	v_add_f32_e32 v28, 1.0, v36
	v_rcp_f32_e32 v35, v28
	v_mul_f32_e32 v29, 0xbfb8aa3b, v26
	v_mul_f32_e32 v28, 0xbfb8aa3b, v30
	v_exp_f32_e32 v29, v29
	v_exp_f32_e32 v28, v28
	v_exp_f32_e32 v33, v32
	v_mul_f32_e32 v32, 0xbfb8aa3b, v27
	v_pk_mul_f32 v[24:25], v[24:25], v[34:35]
	v_exp_f32_e32 v34, v32
	v_add_f32_e32 v29, 1.0, v29
	v_add_f32_e32 v28, 1.0, v28
	v_rcp_f32_e32 v32, v29
	v_add_f32_e32 v29, 1.0, v33
	v_rcp_f32_e32 v28, v28
	v_rcp_f32_e32 v29, v29
	v_add_f32_e32 v33, 1.0, v34
	v_rcp_f32_e32 v33, v33
	v_pk_mul_f32 v[24:25], v[24:25], v[16:17]
	v_pk_mul_f32 v[16:17], v[30:31], v[28:29]
	s_nop 0
	v_pk_mul_f32 v[22:23], v[16:17], v[22:23]
	v_pk_mul_f32 v[16:17], v[26:27], v[32:33]
	s_nop 0
	v_pk_mul_f32 v[26:27], v[16:17], v[18:19]
	v_cvt_pk_bf16_f32 v16, v20, v21
	v_add_u32_e32 v20, 0xa0, v150
	v_mad_i64_i32 v[20:21], s[10:11], v20, s64, v[112:113]
	v_cvt_pk_bf16_f32 v17, v22, v23
	v_cvt_pk_bf16_f32 v18, v24, v25
	v_cvt_pk_bf16_f32 v19, v26, v27
	v_lshl_add_u64 v[20:21], v[20:21], 0, v[114:115]
	global_store_dwordx4 v[20:21], v[16:19], off
	s_nop 1
	v_mul_f32_e32 v16, 0xbfb8aa3b, v12
	v_mul_f32_e32 v17, 0xbfb8aa3b, v8
	v_mul_f32_e32 v18, 0xbfb8aa3b, v13
	v_exp_f32_e32 v16, v16
	v_exp_f32_e32 v17, v17
	v_exp_f32_e32 v18, v18
	v_add_f32_e32 v16, 1.0, v16
	v_add_f32_e32 v19, 1.0, v17
	v_add_f32_e32 v17, 1.0, v18
	v_rcp_f32_e32 v16, v16
	v_rcp_f32_e32 v17, v17
	v_mul_f32_e32 v18, 0xbfb8aa3b, v9
	v_exp_f32_e32 v20, v18
	v_rcp_f32_e32 v18, v19
	v_pk_mul_f32 v[12:13], v[12:13], v[16:17]
	v_mul_f32_e32 v16, 0xbfb8aa3b, v15
	v_pk_mul_f32 v[4:5], v[12:13], v[4:5]
	v_add_f32_e32 v12, 1.0, v20
	v_rcp_f32_e32 v19, v12
	v_mul_f32_e32 v13, 0xbfb8aa3b, v10
	v_mul_f32_e32 v12, 0xbfb8aa3b, v14
	v_exp_f32_e32 v13, v13
	v_exp_f32_e32 v12, v12
	v_exp_f32_e32 v17, v16
	v_mul_f32_e32 v16, 0xbfb8aa3b, v11
	v_pk_mul_f32 v[8:9], v[8:9], v[18:19]
	v_exp_f32_e32 v18, v16
	v_add_f32_e32 v13, 1.0, v13
	v_add_f32_e32 v12, 1.0, v12
	v_rcp_f32_e32 v16, v13
	v_add_f32_e32 v13, 1.0, v17
	v_rcp_f32_e32 v12, v12
	v_rcp_f32_e32 v13, v13
	v_add_f32_e32 v17, 1.0, v18
	v_rcp_f32_e32 v17, v17
	v_pk_mul_f32 v[8:9], v[8:9], v[0:1]
	v_pk_mul_f32 v[0:1], v[14:15], v[12:13]
	s_nop 0
	v_pk_mul_f32 v[6:7], v[0:1], v[6:7]
	v_pk_mul_f32 v[0:1], v[10:11], v[16:17]
	s_nop 0
	v_pk_mul_f32 v[10:11], v[0:1], v[2:3]
	v_cvt_pk_bf16_f32 v0, v4, v5
	v_add_u32_e32 v4, 0xb0, v150
	v_mad_i64_i32 v[4:5], s[10:11], v4, s64, v[112:113]
	v_cvt_pk_bf16_f32 v1, v6, v7
	v_cvt_pk_bf16_f32 v2, v8, v9
	v_cvt_pk_bf16_f32 v3, v10, v11
	v_lshl_add_u64 v[4:5], v[4:5], 0, v[114:115]
	global_store_dwordx4 v[4:5], v[0:3], off
	s_cbranch_vccz .LBB0_800
	s_waitcnt vmcnt(0)
	s_cmpk_gt_u32 s34, 0xff
	s_cbranch_scc1 .LBB0_807
	s_barrier

; #define PG8_STAGE(bufoff, gbase, voff) do { _Pragma("unroll") for (int _i = 0; _i < 2; ++_i) \
;         __builtin_amdgcn_global_load_lds((const unsigned*)((const char*)(gbase) + (voff)[_i]), (PG8_LAS unsigned*)(lds + (bufoff) + ldsw + _i * 8192), 16, 0, 0); } while (0)
; #define PG8_LDA(dst, b, h) do { _Pragma("unroll") for (int m = 0; m < 4; ++m) _Pragma("unroll") for (int k = 0; k < 2; ++k) dst[m][k] = *(const PG8_LAS bf16x8*)(lds + PG8_SA(b, h) + aoff + m * 2048 + k * 1024); } while (0)
; #define PG8_LDB(dst, b, h) do { _Pragma("unroll") for (int n = 0; n < 2; ++n) _Pragma("unroll") for (int k = 0; k < 2; ++k) dst[n][k] = *(const PG8_LAS bf16x8*)(lds + PG8_SB(b, h) + boff + n * 2048 + k * 1024); } while (0)
; #define PG8_WAIT_V(n) asm volatile("s_waitcnt vmcnt(" #n ")" ::: "memory")
; #define PG8_WAIT_L(n) asm volatile("s_waitcnt lgkmcnt(" #n ")" ::: "memory")
; #define PG8_BAR __builtin_amdgcn_s_barrier()
; #define PG8_SCHED __builtin_amdgcn_sched_barrier(0)
; template <class Epi, class Sched>
; __device__ __forceinline__ void gemm_phase(PG8_LAS unsigned char* lds, const Gemm g, const Sched& S, const Epi& E) {
;     ...
;         for (int t = 0; t < nt; t += 2) {
;             const bool last = (t == nt - 2);
;             const char* a1 = cA + (size_t)(t + 1) * kstep;
;             const char* a2 = last ? nA : cA + (size_t)(t + 2) * kstep; const char* b2 = last ? nB : cB + (size_t)(t + 2) * kstep;
;             const char* a3 = a2 + kstep; const char* b3 = b2 + kstep;
;             if (last && has_next) S.a_ready(nxt);
;             PG8_LDB(B0, 0, 0); PG8_SCHED; PG8_LDA(At, 0, 0); PG8_STAGE(PG8_SA(1, 1), a1 + hstep, voffA);
;             PG8_WAIT_L(8); PG8_BAR; PG8_WAIT_L(0); PG8_MMA(0, 0, At, B0); PG8_BAR; PG8_SCHED;
;             PG8_LDB(B1, 0, 1); PG8_STAGE(PG8_SB(0, 0), b2, voffB);
;             PG8_BAR; PG8_WAIT_L(0); PG8_MMA(0, 1, At, B1); PG8_BAR;
;             PG8_LDA(At, 0, 1); PG8_STAGE(PG8_SA(0, 0), a2, voffA);
;             PG8_BAR; PG8_WAIT_L(0); PG8_MMA(1, 0, At, B0); PG8_BAR; PG8_SCHED;
;             PG8_STAGE(PG8_SB(0, 1), b2 + hstep, voffB);
;             PG8_WAIT_V(6); PG8_BAR; PG8_MMA(1, 1, At, B1); PG8_BAR;
;             PG8_LDB(B0, 1, 0); PG8_SCHED; PG8_LDA(At, 1, 0); PG8_STAGE(PG8_SA(0, 1), a2 + hstep, voffA);
;             PG8_WAIT_L(8); PG8_BAR; PG8_WAIT_L(0); PG8_MMA(0, 0, At, B0); PG8_BAR; PG8_SCHED;
.LBB0_882:
	s_setprio 0
	ds_read_b128 v[108:111], v247
	ds_read_b128 v[112:115], v247 offset:1024
	ds_read_b128 v[124:127], v247 offset:2048
	ds_read_b128 v[128:131], v247 offset:3072
	ds_read_b128 v[144:147], v248
	ds_read_b128 v[148:151], v248 offset:1024
	ds_read_b128 v[152:155], v248 offset:2048
	ds_read_b128 v[156:159], v248 offset:3072
	ds_read_b128 v[160:163], v248 offset:4096
	ds_read_b128 v[164:167], v248 offset:5120
	ds_read_b128 v[168:171], v248 offset:6144
	ds_read_b128 v[172:175], v248 offset:7168
	ds_read_b128 v[188:191], v249
	ds_read_b128 v[192:195], v249 offset:1024
	ds_read_b128 v[196:199], v249 offset:2048
	ds_read_b128 v[200:203], v249 offset:3072
	s_add_u32 s10, s26, 0xffea0080
	s_addc_u32 s11, s27, -1
	s_cmpk_eq_i32 s69, 0x54
	s_cselect_b32 s31, s1, s11
	s_cselect_b32 s30, s0, s10
	s_cselect_b32 s29, s5, s68
	s_cselect_b32 s28, s4, s67
	v_lshl_add_u64 v[252:253], s[26:27], 0, v[184:185]
	s_add_i32 m0, s40, 0xc000
	s_nop 0
	global_load_lds_dwordx4 v[252:253], off
	v_lshl_add_u64 v[252:253], s[26:27], 0, v[186:187]
	s_add_i32 m0, s40, 0xe000
	s_nop 0
	global_load_lds_dwordx4 v[252:253], off
	s_waitcnt vmcnt(8)
	s_waitcnt lgkmcnt(0)
	s_setprio 1
	s_barrier
	v_mfma_f32_16x16x32_bf16 v[140:143], v[108:111], v[144:147], v[140:143]
	v_mfma_f32_16x16x32_bf16 v[136:139], v[124:127], v[144:147], v[136:139]
	v_mfma_f32_16x16x32_bf16 v[116:119], v[108:111], v[152:155], v[116:119]
	v_mfma_f32_16x16x32_bf16 v[104:107], v[124:127], v[152:155], v[104:107]
	v_mfma_f32_16x16x32_bf16 v[92:95], v[108:111], v[160:163], v[92:95]
	v_mfma_f32_16x16x32_bf16 v[88:91], v[124:127], v[160:163], v[88:91]
	v_mfma_f32_16x16x32_bf16 v[76:79], v[108:111], v[168:171], v[76:79]
	v_mfma_f32_16x16x32_bf16 v[72:75], v[124:127], v[168:171], v[72:75]
	v_mfma_f32_16x16x32_bf16 v[140:143], v[112:115], v[148:151], v[140:143]
	v_mfma_f32_16x16x32_bf16 v[136:139], v[128:131], v[148:151], v[136:139]
	v_mfma_f32_16x16x32_bf16 v[116:119], v[112:115], v[156:159], v[116:119]
	v_mfma_f32_16x16x32_bf16 v[104:107], v[128:131], v[156:159], v[104:107]
	v_mfma_f32_16x16x32_bf16 v[92:95], v[112:115], v[164:167], v[92:95]
	v_mfma_f32_16x16x32_bf16 v[88:91], v[128:131], v[164:167], v[88:91]
	v_mfma_f32_16x16x32_bf16 v[76:79], v[112:115], v[172:175], v[76:79]
	v_mfma_f32_16x16x32_bf16 v[72:75], v[128:131], v[172:175], v[72:75]
	v_mfma_f32_16x16x32_bf16 v[132:135], v[188:191], v[144:147], v[132:135]
	v_mfma_f32_16x16x32_bf16 v[120:123], v[196:199], v[144:147], v[120:123]
	v_mfma_f32_16x16x32_bf16 v[100:103], v[188:191], v[152:155], v[100:103]
	v_mfma_f32_16x16x32_bf16 v[96:99], v[196:199], v[152:155], v[96:99]
	v_mfma_f32_16x16x32_bf16 v[84:87], v[188:191], v[160:163], v[84:87]
	v_mfma_f32_16x16x32_bf16 v[80:83], v[196:199], v[160:163], v[80:83]
	v_mfma_f32_16x16x32_bf16 v[68:71], v[188:191], v[168:171], v[68:71]
	v_mfma_f32_16x16x32_bf16 v[64:67], v[196:199], v[168:171], v[64:67]
	v_mfma_f32_16x16x32_bf16 v[132:135], v[192:195], v[148:151], v[132:135]
	v_mfma_f32_16x16x32_bf16 v[120:123], v[200:203], v[148:151], v[120:123]
	v_mfma_f32_16x16x32_bf16 v[100:103], v[192:195], v[156:159], v[100:103]
	v_mfma_f32_16x16x32_bf16 v[96:99], v[200:203], v[156:159], v[96:99]
	v_mfma_f32_16x16x32_bf16 v[84:87], v[192:195], v[164:167], v[84:87]
	v_mfma_f32_16x16x32_bf16 v[80:83], v[200:203], v[164:167], v[80:83]
	v_mfma_f32_16x16x32_bf16 v[68:71], v[192:195], v[172:175], v[68:71]
	v_mfma_f32_16x16x32_bf16 v[64:67], v[200:203], v[172:175], v[64:67]
	s_barrier
	s_setprio 0
	ds_read_b128 v[144:147], v248 offset:16384
	ds_read_b128 v[148:151], v248 offset:17408
	ds_read_b128 v[152:155], v248 offset:18432
	ds_read_b128 v[156:159], v248 offset:19456
	ds_read_b128 v[160:163], v248 offset:20480
	ds_read_b128 v[164:167], v248 offset:21504
	ds_read_b128 v[168:171], v248 offset:22528
	ds_read_b128 v[172:175], v248 offset:23552
	s_add_i32 s10, s49, s39
	v_lshl_add_u64 v[204:205], s[28:29], 0, v[178:179]
	s_mov_b32 m0, s10
	s_nop 0
	global_load_lds_dwordx4 v[204:205], off
	v_lshl_add_u64 v[206:207], s[28:29], 0, v[182:183]
	s_add_i32 m0, s10, 0x2000
	s_nop 0
	global_load_lds_dwordx4 v[206:207], off
	s_mov_b32 m0, s40
	v_lshl_add_u64 v[208:209], s[30:31], 0, v[176:177]
	global_load_lds_dwordx4 v[208:209], off
	v_lshl_add_u64 v[210:211], s[30:31], 0, v[180:181]
	s_mov_b32 m0, s41
	s_nop 0
	global_load_lds_dwordx4 v[210:211], off
	s_add_u32 s10, s28, 0x160000
	s_addc_u32 s11, s29, 0
	s_add_i32 s33, s50, s39
	v_lshl_add_u64 v[252:253], s[10:11], 0, v[178:179]
	s_mov_b32 m0, s33
	s_nop 0
	global_load_lds_dwordx4 v[252:253], off
	v_lshl_add_u64 v[252:253], s[10:11], 0, v[182:183]
	s_add_i32 m0, s33, 0x2000
	s_nop 0
	global_load_lds_dwordx4 v[252:253], off
	s_waitcnt vmcnt(8)
	s_waitcnt lgkmcnt(0)
	s_setprio 1
	s_barrier
; #define PG8_STAGE(bufoff, gbase, voff) do { _Pragma("unroll") for (int _i = 0; _i < 2; ++_i) \
;         __builtin_amdgcn_global_load_lds((const unsigned*)((const char*)(gbase) + (voff)[_i]), (PG8_LAS unsigned*)(lds + (bufoff) + ldsw + _i * 8192), 16, 0, 0); } while (0)
; #define PG8_LDA(dst, b, h) do { _Pragma("unroll") for (int m = 0; m < 4; ++m) _Pragma("unroll") for (int k = 0; k < 2; ++k) dst[m][k] = *(const PG8_LAS bf16x8*)(lds + PG8_SA(b, h) + aoff + m * 2048 + k * 1024); } while (0)
; #define PG8_LDB(dst, b, h) do { _Pragma("unroll") for (int n = 0; n < 2; ++n) _Pragma("unroll") for (int k = 0; k < 2; ++k) dst[n][k] = *(const PG8_LAS bf16x8*)(lds + PG8_SB(b, h) + boff + n * 2048 + k * 1024); } while (0)
; #define PG8_WAIT_V(n) asm volatile("s_waitcnt vmcnt(" #n ")" ::: "memory")
; #define PG8_WAIT_L(n) asm volatile("s_waitcnt lgkmcnt(" #n ")" ::: "memory")
; #define PG8_BAR __builtin_amdgcn_s_barrier()
; #define PG8_SCHED __builtin_amdgcn_sched_barrier(0)
; template <class Epi, class Sched>
; __device__ __forceinline__ void gemm_phase(PG8_LAS unsigned char* lds, const Gemm g, const Sched& S, const Epi& E) {
;     ...
;             PG8_LDB(B0, 0, 0); PG8_SCHED; PG8_LDA(At, 0, 0); PG8_STAGE(PG8_SA(1, 1), a1 + hstep, voffA);
;             PG8_WAIT_L(8); PG8_BAR; PG8_WAIT_L(0); PG8_MMA(0, 0, At, B0); PG8_BAR; PG8_SCHED;
;             PG8_LDB(B1, 0, 1); PG8_STAGE(PG8_SB(0, 0), b2, voffB);
;             PG8_BAR; PG8_WAIT_L(0); PG8_MMA(0, 1, At, B1); PG8_BAR;
;             PG8_LDA(At, 0, 1); PG8_STAGE(PG8_SA(0, 0), a2, voffA);
;             PG8_BAR; PG8_WAIT_L(0); PG8_MMA(1, 0, At, B0); PG8_BAR; PG8_SCHED;
;             PG8_STAGE(PG8_SB(0, 1), b2 + hstep, voffB);
;             PG8_WAIT_V(6); PG8_BAR; PG8_MMA(1, 1, At, B1); PG8_BAR;
;             PG8_LDB(B0, 1, 0); PG8_SCHED; PG8_LDA(At, 1, 0); PG8_STAGE(PG8_SA(0, 1), a2 + hstep, voffA);
;             PG8_WAIT_L(8); PG8_BAR; PG8_WAIT_L(0); PG8_MMA(0, 0, At, B0); PG8_BAR; PG8_SCHED;
;             PG8_LDB(B1, 1, 1); PG8_STAGE(PG8_SB(1, 0), b3, voffB);
;             PG8_BAR; PG8_WAIT_L(0); PG8_MMA(0, 1, At, B1); PG8_BAR;
;             PG8_LDA(At, 1, 1); PG8_STAGE(PG8_SA(1, 0), a3, voffA);
;             PG8_BAR; PG8_WAIT_L(0); PG8_MMA(1, 0, At, B0); PG8_BAR; PG8_SCHED;
;             PG8_STAGE(PG8_SB(1, 1), b3 + hstep, voffB);
;             PG8_WAIT_V(6); PG8_BAR; PG8_MMA(1, 1, At, B1); PG8_BAR;
	v_mfma_f32_16x16x32_bf16 v[60:63], v[108:111], v[144:147], v[60:63]
	v_mfma_f32_16x16x32_bf16 v[56:59], v[124:127], v[144:147], v[56:59]
	v_mfma_f32_16x16x32_bf16 v[44:47], v[108:111], v[152:155], v[44:47]
	v_mfma_f32_16x16x32_bf16 v[40:43], v[124:127], v[152:155], v[40:43]
	v_mfma_f32_16x16x32_bf16 v[28:31], v[108:111], v[160:163], v[28:31]
	v_mfma_f32_16x16x32_bf16 v[24:27], v[124:127], v[160:163], v[24:27]
	v_mfma_f32_16x16x32_bf16 v[12:15], v[108:111], v[168:171], v[12:15]
	v_mfma_f32_16x16x32_bf16 v[8:11], v[124:127], v[168:171], v[8:11]
	s_add_i32 s33, 0, 0x18000
	v_mfma_f32_16x16x32_bf16 v[60:63], v[112:115], v[148:151], v[60:63]
	v_mfma_f32_16x16x32_bf16 v[56:59], v[128:131], v[148:151], v[56:59]
	v_mfma_f32_16x16x32_bf16 v[44:47], v[112:115], v[156:159], v[44:47]
	v_mfma_f32_16x16x32_bf16 v[40:43], v[128:131], v[156:159], v[40:43]
	v_mfma_f32_16x16x32_bf16 v[28:31], v[112:115], v[164:167], v[28:31]
	v_mfma_f32_16x16x32_bf16 v[24:27], v[128:131], v[164:167], v[24:27]
	v_mfma_f32_16x16x32_bf16 v[12:15], v[112:115], v[172:175], v[12:15]
	v_mfma_f32_16x16x32_bf16 v[8:11], v[128:131], v[172:175], v[8:11]
	v_mfma_f32_16x16x32_bf16 v[52:55], v[188:191], v[144:147], v[52:55]
	v_mfma_f32_16x16x32_bf16 v[48:51], v[196:199], v[144:147], v[48:51]
	v_mfma_f32_16x16x32_bf16 v[36:39], v[188:191], v[152:155], v[36:39]
	v_mfma_f32_16x16x32_bf16 v[32:35], v[196:199], v[152:155], v[32:35]
	v_mfma_f32_16x16x32_bf16 v[20:23], v[188:191], v[160:163], v[20:23]
	v_mfma_f32_16x16x32_bf16 v[16:19], v[196:199], v[160:163], v[16:19]
	v_mfma_f32_16x16x32_bf16 v[4:7], v[188:191], v[168:171], v[4:7]
	v_mfma_f32_16x16x32_bf16 v[0:3], v[196:199], v[168:171], v[0:3]
	v_mfma_f32_16x16x32_bf16 v[52:55], v[192:195], v[148:151], v[52:55]
	v_mfma_f32_16x16x32_bf16 v[48:51], v[200:203], v[148:151], v[48:51]
	v_mfma_f32_16x16x32_bf16 v[36:39], v[192:195], v[156:159], v[36:39]
	v_mfma_f32_16x16x32_bf16 v[32:35], v[200:203], v[156:159], v[32:35]
	v_mfma_f32_16x16x32_bf16 v[20:23], v[192:195], v[164:167], v[20:23]
	v_mfma_f32_16x16x32_bf16 v[16:19], v[200:203], v[164:167], v[16:19]
	v_mfma_f32_16x16x32_bf16 v[4:7], v[192:195], v[172:175], v[4:7]
	v_mfma_f32_16x16x32_bf16 v[0:3], v[200:203], v[172:175], v[0:3]
	s_barrier
	s_setprio 0
	ds_read_b128 v[108:111], v247 offset:32768
	ds_read_b128 v[112:115], v247 offset:33792
	ds_read_b128 v[124:127], v247 offset:34816
	ds_read_b128 v[128:131], v247 offset:35840
	ds_read_b128 v[144:147], v248 offset:32768
	ds_read_b128 v[148:151], v248 offset:33792
	ds_read_b128 v[152:155], v248 offset:34816
	ds_read_b128 v[156:159], v248 offset:35840
	ds_read_b128 v[160:163], v248 offset:36864
	ds_read_b128 v[164:167], v248 offset:37888
	ds_read_b128 v[168:171], v248 offset:38912
	ds_read_b128 v[172:175], v248 offset:39936
	ds_read_b128 v[188:191], v249 offset:32768
	ds_read_b128 v[192:195], v249 offset:33792
	ds_read_b128 v[196:199], v249 offset:34816
	ds_read_b128 v[200:203], v249 offset:35840
	s_add_u32 s10, s30, 0x160000
	s_addc_u32 s11, s31, 0
	s_mov_b32 m0, s42
	v_lshl_add_u64 v[252:253], s[10:11], 0, v[176:177]
	global_load_lds_dwordx4 v[252:253], off
	v_lshl_add_u64 v[252:253], s[10:11], 0, v[180:181]
	s_mov_b32 m0, s43
	s_nop 0
	global_load_lds_dwordx4 v[252:253], off
	s_waitcnt vmcnt(8)
	s_waitcnt lgkmcnt(0)
	s_setprio 1
	s_barrier
	v_mfma_f32_16x16x32_bf16 v[140:143], v[108:111], v[144:147], v[140:143]
	v_mfma_f32_16x16x32_bf16 v[136:139], v[124:127], v[144:147], v[136:139]
	v_mfma_f32_16x16x32_bf16 v[116:119], v[108:111], v[152:155], v[116:119]
	v_mfma_f32_16x16x32_bf16 v[104:107], v[124:127], v[152:155], v[104:107]
	v_mfma_f32_16x16x32_bf16 v[92:95], v[108:111], v[160:163], v[92:95]
	v_mfma_f32_16x16x32_bf16 v[88:91], v[124:127], v[160:163], v[88:91]
	v_mfma_f32_16x16x32_bf16 v[76:79], v[108:111], v[168:171], v[76:79]
	v_mfma_f32_16x16x32_bf16 v[72:75], v[124:127], v[168:171], v[72:75]
	v_mfma_f32_16x16x32_bf16 v[140:143], v[112:115], v[148:151], v[140:143]
	v_mfma_f32_16x16x32_bf16 v[136:139], v[128:131], v[148:151], v[136:139]
	v_mfma_f32_16x16x32_bf16 v[116:119], v[112:115], v[156:159], v[116:119]
	v_mfma_f32_16x16x32_bf16 v[104:107], v[128:131], v[156:159], v[104:107]
	v_mfma_f32_16x16x32_bf16 v[92:95], v[112:115], v[164:167], v[92:95]
	v_mfma_f32_16x16x32_bf16 v[88:91], v[128:131], v[164:167], v[88:91]
	v_mfma_f32_16x16x32_bf16 v[76:79], v[112:115], v[172:175], v[76:79]
	v_mfma_f32_16x16x32_bf16 v[72:75], v[128:131], v[172:175], v[72:75]
	v_mfma_f32_16x16x32_bf16 v[132:135], v[188:191], v[144:147], v[132:135]
	v_mfma_f32_16x16x32_bf16 v[120:123], v[196:199], v[144:147], v[120:123]
	v_mfma_f32_16x16x32_bf16 v[100:103], v[188:191], v[152:155], v[100:103]
	v_mfma_f32_16x16x32_bf16 v[96:99], v[196:199], v[152:155], v[96:99]
	v_mfma_f32_16x16x32_bf16 v[84:87], v[188:191], v[160:163], v[84:87]
	v_mfma_f32_16x16x32_bf16 v[80:83], v[196:199], v[160:163], v[80:83]
	v_mfma_f32_16x16x32_bf16 v[68:71], v[188:191], v[168:171], v[68:71]
	v_mfma_f32_16x16x32_bf16 v[64:67], v[196:199], v[168:171], v[64:67]
	v_mfma_f32_16x16x32_bf16 v[132:135], v[192:195], v[148:151], v[132:135]
	v_mfma_f32_16x16x32_bf16 v[120:123], v[200:203], v[148:151], v[120:123]
	v_mfma_f32_16x16x32_bf16 v[100:103], v[192:195], v[156:159], v[100:103]
	v_mfma_f32_16x16x32_bf16 v[96:99], v[200:203], v[156:159], v[96:99]
	v_mfma_f32_16x16x32_bf16 v[84:87], v[192:195], v[164:167], v[84:87]
	v_mfma_f32_16x16x32_bf16 v[80:83], v[200:203], v[164:167], v[80:83]
	v_mfma_f32_16x16x32_bf16 v[68:71], v[192:195], v[172:175], v[68:71]
	v_mfma_f32_16x16x32_bf16 v[64:67], v[200:203], v[172:175], v[64:67]
	s_barrier
; #define PG8_STAGE(bufoff, gbase, voff) do { _Pragma("unroll") for (int _i = 0; _i < 2; ++_i) \
;         __builtin_amdgcn_global_load_lds((const unsigned*)((const char*)(gbase) + (voff)[_i]), (PG8_LAS unsigned*)(lds + (bufoff) + ldsw + _i * 8192), 16, 0, 0); } while (0)
; #define PG8_LDA(dst, b, h) do { _Pragma("unroll") for (int m = 0; m < 4; ++m) _Pragma("unroll") for (int k = 0; k < 2; ++k) dst[m][k] = *(const PG8_LAS bf16x8*)(lds + PG8_SA(b, h) + aoff + m * 2048 + k * 1024); } while (0)
; template <class Epi, class Sched>
; __device__ __forceinline__ void gemm_phase(PG8_LAS unsigned char* lds, const Gemm g, const Sched& S, const Epi& E) {
;     ...
;             PG8_LDB(B0, 1, 0); PG8_SCHED; PG8_LDA(At, 1, 0); PG8_STAGE(PG8_SA(0, 1), a2 + hstep, voffA);
;             PG8_WAIT_L(8); PG8_BAR; PG8_WAIT_L(0); PG8_MMA(0, 0, At, B0); PG8_BAR; PG8_SCHED;
;             PG8_LDB(B1, 1, 1); PG8_STAGE(PG8_SB(1, 0), b3, voffB);
;             PG8_BAR; PG8_WAIT_L(0); PG8_MMA(0, 1, At, B1); PG8_BAR;
;             PG8_LDA(At, 1, 1); PG8_STAGE(PG8_SA(1, 0), a3, voffA);
;             PG8_BAR; PG8_WAIT_L(0); PG8_MMA(1, 0, At, B0); PG8_BAR; PG8_SCHED;
;             PG8_STAGE(PG8_SB(1, 1), b3 + hstep, voffB);
;             PG8_WAIT_V(6); PG8_BAR; PG8_MMA(1, 1, At, B1); PG8_BAR;
;         }
;         E(acc, cur, wr, wc, fr, fq); S.done(cur);
;     __device__ __forceinline__ void operator()(const AccT& acc, const pg8::Unit& u, int wr, int wc, int fr, int fq) const {
;         const int row0 = u.pm * 256 + wr * 64 + fr, col0 = u.pn * 256 + wc * 32 + 8 * fq;
;         const float* ga = mod + (u.pm >= 64 ? 12288 : 0) + 5 * 2048;
;         f32x4 gv[2][2], lg[2][2], lbv[2][2];
; #pragma unroll
;         for (int bj = 0; bj < 2; ++bj)
; #pragma unroll
;             for (int n = 0; n < 2; ++n) { const int c = col0 + bj * 128 + n * 4; gv[bj][n] = *(const f32x4*)(ga + c); lg[bj][n] = ALPHA * *(const f32x4*)(g1 + c); lbv[bj][n] = ALPHA * *(const f32x4*)(b1 + c); }
; #pragma unroll
;         for (int ai = 0; ai < 2; ++ai) {
;             u32x4 uraw[4][2]; f32x2 stv[4];
; #pragma unroll
;             for (int m = 0; m < 4; ++m) { const int row = row0 + ai * 128 + m * 16; const size_t off = (size_t)row * D + col0; stv[m] = *(const f32x2*)(stats + 2 * row);
; #pragma unroll
;                 for (int bj = 0; bj < 2; ++bj) uraw[m][bj] = *(const u32x4*)(U1 + off + bj * 128); }
	s_setprio 0
	ds_read_b128 v[144:147], v248 offset:49152
	ds_read_b128 v[148:151], v248 offset:50176
	ds_read_b128 v[152:155], v248 offset:51200
	ds_read_b128 v[156:159], v248 offset:52224
	ds_read_b128 v[160:163], v248 offset:53248
	ds_read_b128 v[164:167], v248 offset:54272
	ds_read_b128 v[168:171], v248 offset:55296
	ds_read_b128 v[172:175], v248 offset:56320
	s_add_i32 s30, 0, 0x1c000
	s_add_i32 s10, s33, s39
	v_lshl_add_u64 v[204:205], v[204:205], 0, s[18:19]
	s_mov_b32 m0, s10
	s_nop 0
	global_load_lds_dwordx4 v[204:205], off
	v_lshl_add_u64 v[204:205], v[206:207], 0, s[18:19]
	s_add_i32 m0, s10, 0x2000
	s_nop 0
	global_load_lds_dwordx4 v[204:205], off
	s_mov_b32 m0, s45
	v_lshl_add_u64 v[204:205], v[208:209], 0, s[18:19]
	global_load_lds_dwordx4 v[204:205], off
	v_lshl_add_u64 v[204:205], v[210:211], 0, s[18:19]
	s_mov_b32 m0, s46
	s_nop 0
	global_load_lds_dwordx4 v[204:205], off
	s_add_u32 s10, s28, 0x160080
	s_addc_u32 s11, s29, 0
	s_add_i32 s28, s30, s39
	v_lshl_add_u64 v[252:253], s[10:11], 0, v[178:179]
	s_mov_b32 m0, s28
	s_nop 0
	global_load_lds_dwordx4 v[252:253], off
	v_lshl_add_u64 v[252:253], s[10:11], 0, v[182:183]
	s_add_i32 m0, s28, 0x2000
	s_nop 0
	global_load_lds_dwordx4 v[252:253], off
	s_waitcnt vmcnt(8)
	s_waitcnt lgkmcnt(0)
	s_setprio 1
	s_barrier
	v_mfma_f32_16x16x32_bf16 v[60:63], v[108:111], v[144:147], v[60:63]
	v_mfma_f32_16x16x32_bf16 v[56:59], v[124:127], v[144:147], v[56:59]
	v_mfma_f32_16x16x32_bf16 v[44:47], v[108:111], v[152:155], v[44:47]
	v_mfma_f32_16x16x32_bf16 v[40:43], v[124:127], v[152:155], v[40:43]
	v_mfma_f32_16x16x32_bf16 v[28:31], v[108:111], v[160:163], v[28:31]
	v_mfma_f32_16x16x32_bf16 v[24:27], v[124:127], v[160:163], v[24:27]
	v_mfma_f32_16x16x32_bf16 v[12:15], v[108:111], v[168:171], v[12:15]
	v_mfma_f32_16x16x32_bf16 v[8:11], v[124:127], v[168:171], v[8:11]
	s_add_i32 s69, s69, 2
	s_add_u32 s26, s26, 0x100
	s_addc_u32 s27, s27, 0
	s_add_u32 s67, s67, 0x100
	s_addc_u32 s68, s68, 0
	s_cmpk_gt_u32 s69, 0x55
	v_mfma_f32_16x16x32_bf16 v[60:63], v[112:115], v[148:151], v[60:63]
	v_mfma_f32_16x16x32_bf16 v[56:59], v[128:131], v[148:151], v[56:59]
	v_mfma_f32_16x16x32_bf16 v[44:47], v[112:115], v[156:159], v[44:47]
	v_mfma_f32_16x16x32_bf16 v[40:43], v[128:131], v[156:159], v[40:43]
	v_mfma_f32_16x16x32_bf16 v[28:31], v[112:115], v[164:167], v[28:31]
	v_mfma_f32_16x16x32_bf16 v[24:27], v[128:131], v[164:167], v[24:27]
	v_mfma_f32_16x16x32_bf16 v[12:15], v[112:115], v[172:175], v[12:15]
	v_mfma_f32_16x16x32_bf16 v[8:11], v[128:131], v[172:175], v[8:11]
	v_mfma_f32_16x16x32_bf16 v[52:55], v[188:191], v[144:147], v[52:55]
	v_mfma_f32_16x16x32_bf16 v[48:51], v[196:199], v[144:147], v[48:51]
	v_mfma_f32_16x16x32_bf16 v[36:39], v[188:191], v[152:155], v[36:39]
	v_mfma_f32_16x16x32_bf16 v[32:35], v[196:199], v[152:155], v[32:35]
	v_mfma_f32_16x16x32_bf16 v[20:23], v[188:191], v[160:163], v[20:23]
	v_mfma_f32_16x16x32_bf16 v[16:19], v[196:199], v[160:163], v[16:19]
	v_mfma_f32_16x16x32_bf16 v[4:7], v[188:191], v[168:171], v[4:7]
	v_mfma_f32_16x16x32_bf16 v[0:3], v[196:199], v[168:171], v[0:3]
	v_mfma_f32_16x16x32_bf16 v[52:55], v[192:195], v[148:151], v[52:55]
	v_mfma_f32_16x16x32_bf16 v[48:51], v[200:203], v[148:151], v[48:51]
	v_mfma_f32_16x16x32_bf16 v[36:39], v[192:195], v[156:159], v[36:39]
	v_mfma_f32_16x16x32_bf16 v[32:35], v[200:203], v[156:159], v[32:35]
	v_mfma_f32_16x16x32_bf16 v[20:23], v[192:195], v[164:167], v[20:23]
	v_mfma_f32_16x16x32_bf16 v[16:19], v[200:203], v[164:167], v[16:19]
	v_mfma_f32_16x16x32_bf16 v[4:7], v[192:195], v[172:175], v[4:7]
	v_mfma_f32_16x16x32_bf16 v[0:3], v[200:203], v[172:175], v[0:3]
	s_barrier
	s_cbranch_scc0 .LBB0_882
	s_setprio 0
	s_cmp_gt_i32 s65, 63
	s_cselect_b32 s10, 0xc000, 0
	s_add_u32 s10, s58, s10
	v_lshl_or_b32 v156, s66, 8, v246
	s_addc_u32 s11, s59, 0
	s_add_u32 s10, s10, 0x6a0a000
	v_ashrrev_i32_e32 v157, 31, v156
	s_addc_u32 s11, s11, 0
	v_lshlrev_b64 v[144:145], 2, v[156:157]
	v_lshl_add_u64 v[108:109], s[10:11], 0, v[144:145]
	v_lshl_add_u64 v[148:149], s[22:23], 0, v[144:145]
	global_load_dwordx4 v[112:115], v[108:109], off offset:16
	global_load_dwordx4 v[128:131], v[108:109], off
	s_nop 0
	global_load_dwordx4 v[108:111], v[148:149], off offset:16
	global_load_dwordx4 v[124:127], v[148:149], off
	v_lshl_add_u64 v[152:153], s[24:25], 0, v[144:145]
	v_lshl_add_u32 v224, s65, 8, v244
	v_lshlrev_b64 v[220:221], 1, v[156:157]
	v_ashrrev_i32_e32 v225, 31, v224
	v_lshl_add_u64 v[222:223], s[6:7], 0, v[220:221]
	v_lshlrev_b64 v[240:241], 12, v[224:225]
	s_and_b64 vcc, exec, s[2:3]
	s_mov_b32 s66, s51
	s_mov_b32 s65, s64
	s_mov_b64 s[28:29], s[4:5]
	s_mov_b64 s[26:27], s[0:1]
	s_waitcnt vmcnt(0)
	v_pk_mul_f32 v[210:211], v[108:109], s[20:21] op_sel_hi:[1,0]
	v_pk_mul_f32 v[204:205], v[126:127], s[20:21] op_sel_hi:[1,0]
	v_pk_mul_f32 v[206:207], v[124:125], s[20:21] op_sel_hi:[1,0]
	global_load_dwordx4 v[124:127], v[152:153], off offset:16
	global_load_dwordx4 v[144:147], v[152:153], off
	v_or_b32_e32 v108, 0x80, v156
	v_ashrrev_i32_e32 v109, 31, v108
	v_pk_mul_f32 v[208:209], v[110:111], s[20:21] op_sel_hi:[1,0]
	v_or_b32_e32 v156, 48, v224
	v_ashrrev_i32_e32 v157, 31, v156
	v_lshlrev_b32_e32 v158, 1, v156
	v_ashrrev_i32_e32 v159, 31, v158
	v_lshlrev_b64 v[232:233], 12, v[156:157]
	v_lshl_add_u64 v[158:159], v[158:159], 2, s[8:9]
	v_lshl_add_u64 v[156:157], v[222:223], 0, v[232:233]
	s_waitcnt vmcnt(0)
;     __device__ __forceinline__ void operator()(const AccT& acc, const pg8::Unit& u, int wr, int wc, int fr, int fq) const {
;     ...
;         for (int ai = 0; ai < 2; ++ai) {
;             u32x4 uraw[4][2]; f32x2 stv[4];
; #pragma unroll
;             for (int m = 0; m < 4; ++m) { const int row = row0 + ai * 128 + m * 16; const size_t off = (size_t)row * D + col0; stv[m] = *(const f32x2*)(stats + 2 * row);
; #pragma unroll
;                 for (int bj = 0; bj < 2; ++bj) uraw[m][bj] = *(const u32x4*)(U1 + off + bj * 128); }
; #pragma unroll
;             for (int m = 0; m < 4; ++m) { const int row = row0 + ai * 128 + m * 16; const size_t off = (size_t)row * D + col0; const f32x2 st = stv[m];
; #pragma unroll
;                 for (int bj = 0; bj < 2; ++bj) { float uf[8]; unpack_h8(uraw[m][bj], uf);
;                     const f32x4 ua = {uf[0], uf[1], uf[2], uf[3]}, ub = {uf[4], uf[5], uf[6], uf[7]};
;                     const f32x4 a = ((ua - st.x) * st.y) * lg[bj][0] + lbv[bj][0] + gv[bj][0] * acc[ai][bj][m][0], b = ((ub - st.x) * st.y) * lg[bj][1] + lbv[bj][1] + gv[bj][1] * acc[ai][bj][m][1];
;                     u32x4 w; w.x = pk_h2(a[0], a[1]); w.y = pk_h2(a[2], a[3]); w.z = pk_h2(b[0], b[1]); w.w = pk_h2(b[2], b[3]);
;                     *(u32x4*)(U2 + off + bj * 128) = w; } }
	v_pk_mul_f32 v[214:215], v[124:125], s[20:21] op_sel_hi:[1,0]
	v_lshl_add_u64 v[124:125], v[108:109], 2, s[10:11]
	v_pk_mul_f32 v[216:217], v[146:147], s[20:21] op_sel_hi:[1,0]
	v_pk_mul_f32 v[218:219], v[144:145], s[20:21] op_sel_hi:[1,0]
	v_pk_mul_f32 v[212:213], v[126:127], s[20:21] op_sel_hi:[1,0]
	global_load_dwordx4 v[108:111], v[124:125], off offset:16
	s_nop 0
	global_load_dwordx4 v[124:127], v[124:125], off
	s_nop 0
	global_load_dwordx4 v[144:147], v[148:149], off offset:528
	s_nop 0
	global_load_dwordx4 v[148:151], v[148:149], off offset:512
	s_waitcnt vmcnt(0)
	v_pk_mul_f32 v[190:191], v[144:145], s[20:21] op_sel_hi:[1,0]
	v_pk_mul_f32 v[196:197], v[150:151], s[20:21] op_sel_hi:[1,0]
	v_pk_mul_f32 v[198:199], v[148:149], s[20:21] op_sel_hi:[1,0]
	global_load_dwordx4 v[148:151], v[152:153], off offset:528
	s_nop 0
	global_load_dwordx4 v[152:155], v[152:153], off offset:512
	v_lshlrev_b32_e32 v144, 1, v224
	v_ashrrev_i32_e32 v145, 31, v144
	v_lshl_add_u64 v[144:145], v[144:145], 2, s[8:9]
	global_load_dwordx2 v[234:235], v[144:145], off
	v_lshl_add_u64 v[144:145], v[222:223], 0, v[240:241]
	global_load_dwordx4 v[172:175], v[144:145], off
	global_load_dwordx4 v[160:163], v[144:145], off offset:256
	v_or_b32_e32 v144, 16, v224
	v_pk_mul_f32 v[188:189], v[146:147], s[20:21] op_sel_hi:[1,0]
	v_ashrrev_i32_e32 v145, 31, v144
	v_lshlrev_b32_e32 v146, 1, v144
	v_ashrrev_i32_e32 v147, 31, v146
	v_lshlrev_b64 v[238:239], 12, v[144:145]
	v_lshl_add_u64 v[146:147], v[146:147], 2, s[8:9]
	v_lshl_add_u64 v[144:145], v[222:223], 0, v[238:239]
	global_load_dwordx2 v[236:237], v[146:147], off
	s_waitcnt vmcnt(0)
	v_pk_mul_f32 v[192:193], v[150:151], s[20:21] op_sel_hi:[1,0]
	v_pk_mul_f32 v[194:195], v[148:149], s[20:21] op_sel_hi:[1,0]
	global_load_dwordx4 v[164:167], v[144:145], off
	global_load_dwordx4 v[148:151], v[144:145], off offset:256
	v_or_b32_e32 v144, 32, v224
	v_ashrrev_i32_e32 v145, 31, v144
	v_lshlrev_b32_e32 v146, 1, v144
	v_ashrrev_i32_e32 v147, 31, v146
	v_lshlrev_b64 v[230:231], 12, v[144:145]
	v_lshl_add_u64 v[146:147], v[146:147], 2, s[8:9]
	v_lshl_add_u64 v[144:145], v[222:223], 0, v[230:231]
	v_pk_mul_f32 v[200:201], v[154:155], s[20:21] op_sel_hi:[1,0]
	v_pk_mul_f32 v[202:203], v[152:153], s[20:21] op_sel_hi:[1,0]
	global_load_dwordx2 v[228:229], v[146:147], off
	global_load_dwordx4 v[152:155], v[144:145], off
	s_nop 0
	global_load_dwordx4 v[144:147], v[144:145], off offset:256
	v_cvt_f32_f16_sdwa v225, v172 dst_sel:DWORD dst_unused:UNUSED_PAD src0_sel:WORD_1
	global_load_dwordx2 v[226:227], v[158:159], off
	global_load_dwordx4 v[168:171], v[156:157], off
	s_nop 0
	global_load_dwordx4 v[156:159], v[156:157], off offset:256
	v_cvt_f32_f16_e32 v172, v172
	v_cvt_f32_f16_sdwa v250, v173 dst_sel:DWORD dst_unused:UNUSED_PAD src0_sel:WORD_1
	v_cvt_f32_f16_e32 v251, v173
	v_cvt_f32_f16_sdwa v252, v174 dst_sel:DWORD dst_unused:UNUSED_PAD src0_sel:WORD_1
	v_cvt_f32_f16_e32 v253, v174
	v_cvt_f32_f16_sdwa v254, v175 dst_sel:DWORD dst_unused:UNUSED_PAD src0_sel:WORD_1
	v_cvt_f32_f16_e32 v243, v175
	v_sub_f32_e32 v172, v172, v234
	v_sub_f32_e32 v173, v225, v234
	v_sub_f32_e32 v174, v251, v234
	v_sub_f32_e32 v175, v250, v234
	v_pk_mul_f32 v[174:175], v[234:235], v[174:175] op_sel:[1,0]
	v_pk_mul_f32 v[172:173], v[234:235], v[172:173] op_sel:[1,0]
	v_pk_fma_f32 v[174:175], v[204:205], v[174:175], v[216:217]
	v_pk_fma_f32 v[172:173], v[206:207], v[172:173], v[218:219]
	v_pk_fma_f32 v[142:143], v[142:143], v[130:131], v[174:175]
	v_pk_fma_f32 v[140:141], v[140:141], v[128:129], v[172:173]
	v_sub_f32_e32 v172, v253, v234
	v_sub_f32_e32 v173, v252, v234
	v_sub_f32_e32 v174, v243, v234
	v_sub_f32_e32 v175, v254, v234
	v_pk_mul_f32 v[174:175], v[234:235], v[174:175] op_sel:[1,0]
	v_pk_mul_f32 v[172:173], v[234:235], v[172:173] op_sel:[1,0]
	v_pk_fma_f32 v[174:175], v[208:209], v[174:175], v[212:213]
	v_pk_fma_f32 v[172:173], v[210:211], v[172:173], v[214:215]
	v_pk_fma_f32 v[174:175], v[138:139], v[114:115], v[174:175]
	v_pk_fma_f32 v[138:139], v[136:137], v[112:113], v[172:173]
	v_cvt_pk_f16_f32 v136, v140, v141
	v_lshl_add_u64 v[140:141], s[16:17], 0, v[240:241]
	v_cvt_pk_f16_f32 v137, v142, v143
	v_cvt_pk_f16_f32 v138, v138, v139
	v_cvt_pk_f16_f32 v139, v174, v175
	v_lshl_add_u64 v[140:141], v[140:141], 0, v[220:221]
	global_store_dwordx4 v[140:141], v[136:139], off
	v_cvt_f32_f16_sdwa v142, v162 dst_sel:DWORD dst_unused:UNUSED_PAD src0_sel:WORD_1
	v_cvt_f32_f16_e32 v143, v162
	v_cvt_f32_f16_sdwa v137, v160 dst_sel:DWORD dst_unused:UNUSED_PAD src0_sel:WORD_1
	v_cvt_f32_f16_e32 v136, v160
	v_cvt_f32_f16_sdwa v139, v161 dst_sel:DWORD dst_unused:UNUSED_PAD src0_sel:WORD_1
	v_cvt_f32_f16_e32 v138, v161
	v_cvt_f32_f16_sdwa v160, v163 dst_sel:DWORD dst_unused:UNUSED_PAD src0_sel:WORD_1
	v_cvt_f32_f16_e32 v161, v163
	v_sub_f32_e32 v136, v136, v234
	v_sub_f32_e32 v137, v137, v234
	v_sub_f32_e32 v138, v138, v234
	v_sub_f32_e32 v139, v139, v234
	v_pk_mul_f32 v[138:139], v[234:235], v[138:139] op_sel:[1,0]
	v_pk_mul_f32 v[136:137], v[234:235], v[136:137] op_sel:[1,0]
	v_pk_fma_f32 v[138:139], v[196:197], v[138:139], v[200:201]
	v_pk_fma_f32 v[136:137], v[198:199], v[136:137], v[202:203]
	v_pk_fma_f32 v[134:135], v[134:135], v[126:127], v[138:139]
	v_pk_fma_f32 v[132:133], v[132:133], v[124:125], v[136:137]
	v_sub_f32_e32 v136, v143, v234
	v_sub_f32_e32 v137, v142, v234
	v_sub_f32_e32 v138, v161, v234
	v_sub_f32_e32 v139, v160, v234
	v_pk_mul_f32 v[138:139], v[234:235], v[138:139] op_sel:[1,0]
	v_pk_mul_f32 v[136:137], v[234:235], v[136:137] op_sel:[1,0]
	v_pk_fma_f32 v[138:139], v[188:189], v[138:139], v[192:193]
	v_pk_fma_f32 v[136:137], v[190:191], v[136:137], v[194:195]
	v_pk_fma_f32 v[138:139], v[122:123], v[110:111], v[138:139]
	v_pk_fma_f32 v[122:123], v[120:121], v[108:109], v[136:137]
	v_cvt_pk_f16_f32 v120, v132, v133
	v_cvt_pk_f16_f32 v121, v134, v135
	v_cvt_pk_f16_f32 v122, v122, v123
	v_cvt_pk_f16_f32 v123, v138, v139
	global_store_dwordx4 v[140:141], v[120:123], off offset:256
	s_waitcnt vmcnt(0)
;     __device__ __forceinline__ void operator()(const AccT& acc, const pg8::Unit& u, int wr, int wc, int fr, int fq) const {
;     ...
;             for (int m = 0; m < 4; ++m) { const int row = row0 + ai * 128 + m * 16; const size_t off = (size_t)row * D + col0; const f32x2 st = stv[m];
; #pragma unroll
;                 for (int bj = 0; bj < 2; ++bj) { float uf[8]; unpack_h8(uraw[m][bj], uf);
;                     const f32x4 ua = {uf[0], uf[1], uf[2], uf[3]}, ub = {uf[4], uf[5], uf[6], uf[7]};
;                     const f32x4 a = ((ua - st.x) * st.y) * lg[bj][0] + lbv[bj][0] + gv[bj][0] * acc[ai][bj][m][0], b = ((ub - st.x) * st.y) * lg[bj][1] + lbv[bj][1] + gv[bj][1] * acc[ai][bj][m][1];
;                     u32x4 w; w.x = pk_h2(a[0], a[1]); w.y = pk_h2(a[2], a[3]); w.z = pk_h2(b[0], b[1]); w.w = pk_h2(b[2], b[3]);
;                     *(u32x4*)(U2 + off + bj * 128) = w; } }
	v_cvt_f32_f16_sdwa v132, v166 dst_sel:DWORD dst_unused:UNUSED_PAD src0_sel:WORD_1
	v_cvt_f32_f16_e32 v133, v166
	v_cvt_f32_f16_sdwa v121, v164 dst_sel:DWORD dst_unused:UNUSED_PAD src0_sel:WORD_1
	v_cvt_f32_f16_e32 v120, v164
	v_cvt_f32_f16_sdwa v123, v165 dst_sel:DWORD dst_unused:UNUSED_PAD src0_sel:WORD_1
	v_cvt_f32_f16_e32 v122, v165
	v_cvt_f32_f16_sdwa v134, v167 dst_sel:DWORD dst_unused:UNUSED_PAD src0_sel:WORD_1
	v_cvt_f32_f16_e32 v135, v167
	v_sub_f32_e32 v120, v120, v236
	v_sub_f32_e32 v121, v121, v236
	v_sub_f32_e32 v122, v122, v236
	v_sub_f32_e32 v123, v123, v236
	v_pk_mul_f32 v[122:123], v[236:237], v[122:123] op_sel:[1,0]
	v_pk_mul_f32 v[120:121], v[236:237], v[120:121] op_sel:[1,0]
	v_pk_fma_f32 v[122:123], v[204:205], v[122:123], v[216:217]
	v_pk_fma_f32 v[120:121], v[206:207], v[120:121], v[218:219]
	v_pk_fma_f32 v[118:119], v[118:119], v[130:131], v[122:123]
	v_pk_fma_f32 v[116:117], v[116:117], v[128:129], v[120:121]
	v_sub_f32_e32 v120, v133, v236
	v_sub_f32_e32 v121, v132, v236
	v_sub_f32_e32 v122, v135, v236
	v_sub_f32_e32 v123, v134, v236
	v_pk_mul_f32 v[122:123], v[236:237], v[122:123] op_sel:[1,0]
	v_pk_mul_f32 v[120:121], v[236:237], v[120:121] op_sel:[1,0]
	v_pk_fma_f32 v[122:123], v[208:209], v[122:123], v[212:213]
	v_pk_fma_f32 v[120:121], v[210:211], v[120:121], v[214:215]
	v_pk_fma_f32 v[122:123], v[106:107], v[114:115], v[122:123]
	v_pk_fma_f32 v[106:107], v[104:105], v[112:113], v[120:121]
	v_cvt_pk_f16_f32 v104, v116, v117
	v_lshl_add_u64 v[116:117], s[16:17], 0, v[238:239]
	v_cvt_pk_f16_f32 v105, v118, v119
	v_cvt_pk_f16_f32 v106, v106, v107
	v_cvt_pk_f16_f32 v107, v122, v123
	v_lshl_add_u64 v[116:117], v[116:117], 0, v[220:221]
	global_store_dwordx4 v[116:117], v[104:107], off
	v_cvt_f32_f16_sdwa v118, v150 dst_sel:DWORD dst_unused:UNUSED_PAD src0_sel:WORD_1
	v_cvt_f32_f16_e32 v119, v150
	v_cvt_f32_f16_sdwa v105, v148 dst_sel:DWORD dst_unused:UNUSED_PAD src0_sel:WORD_1
	v_cvt_f32_f16_e32 v104, v148
	v_cvt_f32_f16_sdwa v107, v149 dst_sel:DWORD dst_unused:UNUSED_PAD src0_sel:WORD_1
	v_cvt_f32_f16_e32 v106, v149
	v_cvt_f32_f16_sdwa v120, v151 dst_sel:DWORD dst_unused:UNUSED_PAD src0_sel:WORD_1
	v_cvt_f32_f16_e32 v121, v151
	v_sub_f32_e32 v104, v104, v236
	v_sub_f32_e32 v105, v105, v236
	v_sub_f32_e32 v106, v106, v236
	v_sub_f32_e32 v107, v107, v236
	v_pk_mul_f32 v[106:107], v[236:237], v[106:107] op_sel:[1,0]
	v_pk_mul_f32 v[104:105], v[236:237], v[104:105] op_sel:[1,0]
	v_pk_fma_f32 v[106:107], v[196:197], v[106:107], v[200:201]
	v_pk_fma_f32 v[104:105], v[198:199], v[104:105], v[202:203]
	v_pk_fma_f32 v[102:103], v[102:103], v[126:127], v[106:107]
	v_pk_fma_f32 v[100:101], v[100:101], v[124:125], v[104:105]
	v_sub_f32_e32 v104, v119, v236
	v_sub_f32_e32 v105, v118, v236
	v_sub_f32_e32 v106, v121, v236
	v_sub_f32_e32 v107, v120, v236
	v_pk_mul_f32 v[106:107], v[236:237], v[106:107] op_sel:[1,0]
	v_pk_mul_f32 v[104:105], v[236:237], v[104:105] op_sel:[1,0]
	v_pk_fma_f32 v[106:107], v[188:189], v[106:107], v[192:193]
	v_pk_fma_f32 v[104:105], v[190:191], v[104:105], v[194:195]
	v_pk_fma_f32 v[106:107], v[98:99], v[110:111], v[106:107]
	v_pk_fma_f32 v[98:99], v[96:97], v[108:109], v[104:105]
	v_cvt_pk_f16_f32 v96, v100, v101
	v_cvt_pk_f16_f32 v97, v102, v103
	v_cvt_pk_f16_f32 v98, v98, v99
	v_cvt_pk_f16_f32 v99, v106, v107
	global_store_dwordx4 v[116:117], v[96:99], off offset:256
	v_cvt_f32_f16_sdwa v100, v154 dst_sel:DWORD dst_unused:UNUSED_PAD src0_sel:WORD_1
	v_cvt_f32_f16_e32 v101, v154
	v_cvt_f32_f16_sdwa v97, v152 dst_sel:DWORD dst_unused:UNUSED_PAD src0_sel:WORD_1
	v_cvt_f32_f16_e32 v96, v152
	v_cvt_f32_f16_sdwa v99, v153 dst_sel:DWORD dst_unused:UNUSED_PAD src0_sel:WORD_1
	v_cvt_f32_f16_e32 v98, v153
	v_cvt_f32_f16_sdwa v102, v155 dst_sel:DWORD dst_unused:UNUSED_PAD src0_sel:WORD_1
	v_cvt_f32_f16_e32 v103, v155
	v_sub_f32_e32 v96, v96, v228
	v_sub_f32_e32 v97, v97, v228
	v_sub_f32_e32 v98, v98, v228
	v_sub_f32_e32 v99, v99, v228
	v_pk_mul_f32 v[98:99], v[228:229], v[98:99] op_sel:[1,0]
	v_pk_mul_f32 v[96:97], v[228:229], v[96:97] op_sel:[1,0]
	v_pk_fma_f32 v[98:99], v[204:205], v[98:99], v[216:217]
	v_pk_fma_f32 v[96:97], v[206:207], v[96:97], v[218:219]
	v_pk_fma_f32 v[94:95], v[94:95], v[130:131], v[98:99]
	v_pk_fma_f32 v[92:93], v[92:93], v[128:129], v[96:97]
	v_sub_f32_e32 v96, v101, v228
	v_sub_f32_e32 v97, v100, v228
	v_sub_f32_e32 v98, v103, v228
	v_sub_f32_e32 v99, v102, v228
	v_pk_mul_f32 v[98:99], v[228:229], v[98:99] op_sel:[1,0]
	v_pk_mul_f32 v[96:97], v[228:229], v[96:97] op_sel:[1,0]
	v_pk_fma_f32 v[98:99], v[208:209], v[98:99], v[212:213]
	v_pk_fma_f32 v[96:97], v[210:211], v[96:97], v[214:215]
	v_pk_fma_f32 v[98:99], v[90:91], v[114:115], v[98:99]
	v_pk_fma_f32 v[90:91], v[88:89], v[112:113], v[96:97]
	v_cvt_pk_f16_f32 v88, v92, v93
	v_lshl_add_u64 v[92:93], s[16:17], 0, v[230:231]
	v_cvt_pk_f16_f32 v89, v94, v95
	v_cvt_pk_f16_f32 v90, v90, v91
	v_cvt_pk_f16_f32 v91, v98, v99
	v_lshl_add_u64 v[92:93], v[92:93], 0, v[220:221]
	global_store_dwordx4 v[92:93], v[88:91], off
	v_cvt_f32_f16_sdwa v94, v146 dst_sel:DWORD dst_unused:UNUSED_PAD src0_sel:WORD_1
	v_cvt_f32_f16_e32 v95, v146
	v_cvt_f32_f16_sdwa v89, v144 dst_sel:DWORD dst_unused:UNUSED_PAD src0_sel:WORD_1
	v_cvt_f32_f16_e32 v88, v144
	v_cvt_f32_f16_sdwa v91, v145 dst_sel:DWORD dst_unused:UNUSED_PAD src0_sel:WORD_1
	v_cvt_f32_f16_e32 v90, v145
	v_cvt_f32_f16_sdwa v96, v147 dst_sel:DWORD dst_unused:UNUSED_PAD src0_sel:WORD_1
	v_cvt_f32_f16_e32 v97, v147
	v_sub_f32_e32 v88, v88, v228
	v_sub_f32_e32 v89, v89, v228
	v_sub_f32_e32 v90, v90, v228
	v_sub_f32_e32 v91, v91, v228
	v_pk_mul_f32 v[90:91], v[228:229], v[90:91] op_sel:[1,0]
;     __device__ __forceinline__ void operator()(const AccT& acc, const pg8::Unit& u, int wr, int wc, int fr, int fq) const {
;     ...
; #pragma unroll
;         for (int ai = 0; ai < 2; ++ai) {
;             u32x4 uraw[4][2]; f32x2 stv[4];
; #pragma unroll
;             for (int m = 0; m < 4; ++m) { const int row = row0 + ai * 128 + m * 16; const size_t off = (size_t)row * D + col0; stv[m] = *(const f32x2*)(stats + 2 * row);
; #pragma unroll
;                 for (int bj = 0; bj < 2; ++bj) uraw[m][bj] = *(const u32x4*)(U1 + off + bj * 128); }
; #pragma unroll
;             for (int m = 0; m < 4; ++m) { const int row = row0 + ai * 128 + m * 16; const size_t off = (size_t)row * D + col0; const f32x2 st = stv[m];
; #pragma unroll
;                 for (int bj = 0; bj < 2; ++bj) { float uf[8]; unpack_h8(uraw[m][bj], uf);
;                     const f32x4 ua = {uf[0], uf[1], uf[2], uf[3]}, ub = {uf[4], uf[5], uf[6], uf[7]};
;                     const f32x4 a = ((ua - st.x) * st.y) * lg[bj][0] + lbv[bj][0] + gv[bj][0] * acc[ai][bj][m][0], b = ((ub - st.x) * st.y) * lg[bj][1] + lbv[bj][1] + gv[bj][1] * acc[ai][bj][m][1];
;                     u32x4 w; w.x = pk_h2(a[0], a[1]); w.y = pk_h2(a[2], a[3]); w.z = pk_h2(b[0], b[1]); w.w = pk_h2(b[2], b[3]);
;                     *(u32x4*)(U2 + off + bj * 128) = w; } }
;         }
	v_pk_mul_f32 v[88:89], v[228:229], v[88:89] op_sel:[1,0]
	v_pk_fma_f32 v[90:91], v[196:197], v[90:91], v[200:201]
	v_pk_fma_f32 v[88:89], v[198:199], v[88:89], v[202:203]
	v_pk_fma_f32 v[86:87], v[86:87], v[126:127], v[90:91]
	v_pk_fma_f32 v[84:85], v[84:85], v[124:125], v[88:89]
	v_sub_f32_e32 v88, v95, v228
	v_sub_f32_e32 v89, v94, v228
	v_sub_f32_e32 v90, v97, v228
	v_sub_f32_e32 v91, v96, v228
	v_pk_mul_f32 v[90:91], v[228:229], v[90:91] op_sel:[1,0]
	v_pk_mul_f32 v[88:89], v[228:229], v[88:89] op_sel:[1,0]
	v_pk_fma_f32 v[90:91], v[188:189], v[90:91], v[192:193]
	v_pk_fma_f32 v[88:89], v[190:191], v[88:89], v[194:195]
	v_pk_fma_f32 v[90:91], v[82:83], v[110:111], v[90:91]
	v_pk_fma_f32 v[82:83], v[80:81], v[108:109], v[88:89]
	v_cvt_pk_f16_f32 v80, v84, v85
	v_cvt_pk_f16_f32 v81, v86, v87
	v_cvt_pk_f16_f32 v82, v82, v83
	v_cvt_pk_f16_f32 v83, v90, v91
	global_store_dwordx4 v[92:93], v[80:83], off offset:256
	v_cvt_f32_f16_sdwa v84, v170 dst_sel:DWORD dst_unused:UNUSED_PAD src0_sel:WORD_1
	v_cvt_f32_f16_e32 v85, v170
	v_cvt_f32_f16_sdwa v81, v168 dst_sel:DWORD dst_unused:UNUSED_PAD src0_sel:WORD_1
	v_cvt_f32_f16_e32 v80, v168
	v_cvt_f32_f16_sdwa v83, v169 dst_sel:DWORD dst_unused:UNUSED_PAD src0_sel:WORD_1
	v_cvt_f32_f16_e32 v82, v169
	v_cvt_f32_f16_sdwa v86, v171 dst_sel:DWORD dst_unused:UNUSED_PAD src0_sel:WORD_1
	v_cvt_f32_f16_e32 v87, v171
	v_sub_f32_e32 v80, v80, v226
	v_sub_f32_e32 v81, v81, v226
	v_sub_f32_e32 v82, v82, v226
	v_sub_f32_e32 v83, v83, v226
	v_pk_mul_f32 v[82:83], v[226:227], v[82:83] op_sel:[1,0]
	v_pk_mul_f32 v[80:81], v[226:227], v[80:81] op_sel:[1,0]
	v_pk_fma_f32 v[82:83], v[204:205], v[82:83], v[216:217]
	v_pk_fma_f32 v[80:81], v[206:207], v[80:81], v[218:219]
	v_pk_fma_f32 v[78:79], v[78:79], v[130:131], v[82:83]
	v_pk_fma_f32 v[76:77], v[76:77], v[128:129], v[80:81]
	v_sub_f32_e32 v80, v85, v226
	v_sub_f32_e32 v81, v84, v226
	v_sub_f32_e32 v82, v87, v226
	v_sub_f32_e32 v83, v86, v226
	v_pk_mul_f32 v[82:83], v[226:227], v[82:83] op_sel:[1,0]
	v_pk_mul_f32 v[80:81], v[226:227], v[80:81] op_sel:[1,0]
	v_pk_fma_f32 v[82:83], v[208:209], v[82:83], v[212:213]
	v_pk_fma_f32 v[80:81], v[210:211], v[80:81], v[214:215]
	v_pk_fma_f32 v[82:83], v[74:75], v[114:115], v[82:83]
	v_pk_fma_f32 v[74:75], v[72:73], v[112:113], v[80:81]
	v_cvt_pk_f16_f32 v72, v76, v77
	v_lshl_add_u64 v[76:77], s[16:17], 0, v[232:233]
	v_cvt_pk_f16_f32 v73, v78, v79
	v_cvt_pk_f16_f32 v74, v74, v75
	v_cvt_pk_f16_f32 v75, v82, v83
	v_lshl_add_u64 v[76:77], v[76:77], 0, v[220:221]
	global_store_dwordx4 v[76:77], v[72:75], off
	v_cvt_f32_f16_sdwa v78, v158 dst_sel:DWORD dst_unused:UNUSED_PAD src0_sel:WORD_1
	v_cvt_f32_f16_e32 v79, v158
	v_cvt_f32_f16_sdwa v73, v156 dst_sel:DWORD dst_unused:UNUSED_PAD src0_sel:WORD_1
	v_cvt_f32_f16_e32 v72, v156
	v_cvt_f32_f16_sdwa v75, v157 dst_sel:DWORD dst_unused:UNUSED_PAD src0_sel:WORD_1
	v_cvt_f32_f16_e32 v74, v157
	v_cvt_f32_f16_sdwa v80, v159 dst_sel:DWORD dst_unused:UNUSED_PAD src0_sel:WORD_1
	v_cvt_f32_f16_e32 v81, v159
	v_sub_f32_e32 v72, v72, v226
	v_sub_f32_e32 v73, v73, v226
	v_sub_f32_e32 v74, v74, v226
	v_sub_f32_e32 v75, v75, v226
	v_pk_mul_f32 v[74:75], v[226:227], v[74:75] op_sel:[1,0]
	v_pk_mul_f32 v[72:73], v[226:227], v[72:73] op_sel:[1,0]
	v_pk_fma_f32 v[74:75], v[196:197], v[74:75], v[200:201]
	v_pk_fma_f32 v[72:73], v[198:199], v[72:73], v[202:203]
	v_pk_fma_f32 v[70:71], v[70:71], v[126:127], v[74:75]
	v_pk_fma_f32 v[68:69], v[68:69], v[124:125], v[72:73]
	v_sub_f32_e32 v72, v79, v226
	v_sub_f32_e32 v73, v78, v226
	v_sub_f32_e32 v74, v81, v226
	v_sub_f32_e32 v75, v80, v226
	v_pk_mul_f32 v[74:75], v[226:227], v[74:75] op_sel:[1,0]
	v_pk_mul_f32 v[72:73], v[226:227], v[72:73] op_sel:[1,0]
	v_pk_fma_f32 v[74:75], v[188:189], v[74:75], v[192:193]
	v_pk_fma_f32 v[72:73], v[190:191], v[72:73], v[194:195]
	v_pk_fma_f32 v[74:75], v[66:67], v[110:111], v[74:75]
	v_pk_fma_f32 v[66:67], v[64:65], v[108:109], v[72:73]
	v_cvt_pk_f16_f32 v64, v68, v69
	v_cvt_pk_f16_f32 v65, v70, v71
	v_cvt_pk_f16_f32 v66, v66, v67
	v_cvt_pk_f16_f32 v67, v74, v75
	global_store_dwordx4 v[76:77], v[64:67], off offset:256
	s_nop 1
	v_add_u32_e32 v64, 0x80, v224
	v_ashrrev_i32_e32 v65, 31, v64
	v_lshlrev_b32_e32 v66, 1, v64
	v_ashrrev_i32_e32 v67, 31, v66
	v_lshlrev_b64 v[106:107], 12, v[64:65]
	v_lshl_add_u64 v[66:67], v[66:67], 2, s[8:9]
	v_lshl_add_u64 v[64:65], v[222:223], 0, v[106:107]
	global_load_dwordx2 v[104:105], v[66:67], off
	global_load_dwordx4 v[84:87], v[64:65], off
	global_load_dwordx4 v[88:91], v[64:65], off offset:256
	v_add_u32_e32 v64, 0x90, v224
	v_ashrrev_i32_e32 v65, 31, v64
	v_lshlrev_b32_e32 v66, 1, v64
	v_ashrrev_i32_e32 v67, 31, v66
	v_lshlrev_b64 v[118:119], 12, v[64:65]
	v_lshl_add_u64 v[66:67], v[66:67], 2, s[8:9]
	v_lshl_add_u64 v[64:65], v[222:223], 0, v[118:119]
	global_load_dwordx2 v[116:117], v[66:67], off
	global_load_dwordx4 v[92:95], v[64:65], off
	global_load_dwordx4 v[96:99], v[64:65], off offset:256
	v_add_u32_e32 v64, 0xa0, v224
	v_ashrrev_i32_e32 v65, 31, v64
	v_lshlrev_b32_e32 v66, 1, v64
	v_ashrrev_i32_e32 v67, 31, v66
	v_lshlrev_b64 v[82:83], 12, v[64:65]
	v_lshl_add_u64 v[66:67], v[66:67], 2, s[8:9]
	v_lshl_add_u64 v[64:65], v[222:223], 0, v[82:83]
	global_load_dwordx2 v[80:81], v[66:67], off
	global_load_dwordx4 v[100:103], v[64:65], off
	global_load_dwordx4 v[72:75], v[64:65], off offset:256
	v_add_u32_e32 v64, 0xb0, v224
	v_ashrrev_i32_e32 v65, 31, v64
	v_lshlrev_b32_e32 v66, 1, v64
	v_ashrrev_i32_e32 v67, 31, v66
	v_lshlrev_b64 v[78:79], 12, v[64:65]
	v_lshl_add_u64 v[66:67], v[66:67], 2, s[8:9]
	v_lshl_add_u64 v[64:65], v[222:223], 0, v[78:79]
	global_load_dwordx2 v[76:77], v[66:67], off
	global_load_dwordx4 v[68:71], v[64:65], off
	s_nop 0
	global_load_dwordx4 v[64:67], v[64:65], off offset:256
	s_waitcnt vmcnt(0)
;     __device__ __forceinline__ void operator()(const AccT& acc, const pg8::Unit& u, int wr, int wc, int fr, int fq) const {
;     ...
; #pragma unroll
;         for (int ai = 0; ai < 2; ++ai) {
;             u32x4 uraw[4][2]; f32x2 stv[4];
; #pragma unroll
;             for (int m = 0; m < 4; ++m) { const int row = row0 + ai * 128 + m * 16; const size_t off = (size_t)row * D + col0; stv[m] = *(const f32x2*)(stats + 2 * row);
; #pragma unroll
;                 for (int bj = 0; bj < 2; ++bj) uraw[m][bj] = *(const u32x4*)(U1 + off + bj * 128); }
; #pragma unroll
;             for (int m = 0; m < 4; ++m) { const int row = row0 + ai * 128 + m * 16; const size_t off = (size_t)row * D + col0; const f32x2 st = stv[m];
; #pragma unroll
;                 for (int bj = 0; bj < 2; ++bj) { float uf[8]; unpack_h8(uraw[m][bj], uf);
;                     const f32x4 ua = {uf[0], uf[1], uf[2], uf[3]}, ub = {uf[4], uf[5], uf[6], uf[7]};
;                     const f32x4 a = ((ua - st.x) * st.y) * lg[bj][0] + lbv[bj][0] + gv[bj][0] * acc[ai][bj][m][0], b = ((ub - st.x) * st.y) * lg[bj][1] + lbv[bj][1] + gv[bj][1] * acc[ai][bj][m][1];
;                     u32x4 w; w.x = pk_h2(a[0], a[1]); w.y = pk_h2(a[2], a[3]); w.z = pk_h2(b[0], b[1]); w.w = pk_h2(b[2], b[3]);
;                     *(u32x4*)(U2 + off + bj * 128) = w; } }
;         }
	v_cvt_f32_f16_e32 v120, v84
	v_cvt_f32_f16_sdwa v84, v84 dst_sel:DWORD dst_unused:UNUSED_PAD src0_sel:WORD_1
	v_cvt_f32_f16_e32 v121, v85
	v_cvt_f32_f16_sdwa v122, v85 dst_sel:DWORD dst_unused:UNUSED_PAD src0_sel:WORD_1
	v_cvt_f32_f16_e32 v123, v86
	v_cvt_f32_f16_sdwa v132, v86 dst_sel:DWORD dst_unused:UNUSED_PAD src0_sel:WORD_1
	v_cvt_f32_f16_e32 v133, v87
	v_cvt_f32_f16_sdwa v134, v87 dst_sel:DWORD dst_unused:UNUSED_PAD src0_sel:WORD_1
	v_sub_f32_e32 v85, v84, v104
	v_sub_f32_e32 v84, v120, v104
	v_sub_f32_e32 v87, v122, v104
	v_sub_f32_e32 v86, v121, v104
	v_pk_mul_f32 v[86:87], v[104:105], v[86:87] op_sel:[1,0]
	v_pk_mul_f32 v[84:85], v[104:105], v[84:85] op_sel:[1,0]
	v_pk_fma_f32 v[86:87], v[204:205], v[86:87], v[216:217]
	v_pk_fma_f32 v[84:85], v[206:207], v[84:85], v[218:219]
	v_pk_fma_f32 v[62:63], v[62:63], v[130:131], v[86:87]
	v_pk_fma_f32 v[60:61], v[60:61], v[128:129], v[84:85]
	v_sub_f32_e32 v85, v132, v104
	v_sub_f32_e32 v84, v123, v104
	v_sub_f32_e32 v87, v134, v104
	v_sub_f32_e32 v86, v133, v104
	v_pk_mul_f32 v[86:87], v[104:105], v[86:87] op_sel:[1,0]
	v_pk_mul_f32 v[84:85], v[104:105], v[84:85] op_sel:[1,0]
	v_pk_fma_f32 v[86:87], v[208:209], v[86:87], v[212:213]
	v_pk_fma_f32 v[84:85], v[210:211], v[84:85], v[214:215]
	v_pk_fma_f32 v[86:87], v[58:59], v[114:115], v[86:87]
	v_pk_fma_f32 v[58:59], v[56:57], v[112:113], v[84:85]
	v_cvt_pk_f16_f32 v56, v60, v61
	v_lshl_add_u64 v[60:61], s[16:17], 0, v[106:107]
	v_cvt_pk_f16_f32 v57, v62, v63
	v_cvt_pk_f16_f32 v58, v58, v59
	v_cvt_pk_f16_f32 v59, v86, v87
	v_lshl_add_u64 v[60:61], v[60:61], 0, v[220:221]
	global_store_dwordx4 v[60:61], v[56:59], off
	v_cvt_f32_f16_e32 v62, v90
	v_cvt_f32_f16_sdwa v63, v90 dst_sel:DWORD dst_unused:UNUSED_PAD src0_sel:WORD_1
	v_cvt_f32_f16_e32 v56, v88
	v_cvt_f32_f16_sdwa v57, v88 dst_sel:DWORD dst_unused:UNUSED_PAD src0_sel:WORD_1
	v_cvt_f32_f16_e32 v58, v89
	v_cvt_f32_f16_sdwa v59, v89 dst_sel:DWORD dst_unused:UNUSED_PAD src0_sel:WORD_1
	v_cvt_f32_f16_e32 v84, v91
	v_cvt_f32_f16_sdwa v85, v91 dst_sel:DWORD dst_unused:UNUSED_PAD src0_sel:WORD_1
	v_sub_f32_e32 v57, v57, v104
	v_sub_f32_e32 v56, v56, v104
	v_sub_f32_e32 v59, v59, v104
	v_sub_f32_e32 v58, v58, v104
	v_pk_mul_f32 v[58:59], v[104:105], v[58:59] op_sel:[1,0]
	v_pk_mul_f32 v[56:57], v[104:105], v[56:57] op_sel:[1,0]
	v_pk_fma_f32 v[58:59], v[196:197], v[58:59], v[200:201]
	v_pk_fma_f32 v[56:57], v[198:199], v[56:57], v[202:203]
	v_pk_fma_f32 v[54:55], v[54:55], v[126:127], v[58:59]
	v_pk_fma_f32 v[52:53], v[52:53], v[124:125], v[56:57]
	v_sub_f32_e32 v57, v63, v104
	v_sub_f32_e32 v56, v62, v104
	v_sub_f32_e32 v59, v85, v104
	v_sub_f32_e32 v58, v84, v104
	v_pk_mul_f32 v[58:59], v[104:105], v[58:59] op_sel:[1,0]
	v_pk_mul_f32 v[56:57], v[104:105], v[56:57] op_sel:[1,0]
	v_pk_fma_f32 v[58:59], v[188:189], v[58:59], v[192:193]
	v_pk_fma_f32 v[56:57], v[190:191], v[56:57], v[194:195]
	v_pk_fma_f32 v[58:59], v[50:51], v[110:111], v[58:59]
	v_pk_fma_f32 v[50:51], v[48:49], v[108:109], v[56:57]
	v_cvt_pk_f16_f32 v48, v52, v53
	v_cvt_pk_f16_f32 v49, v54, v55
	v_cvt_pk_f16_f32 v50, v50, v51
	v_cvt_pk_f16_f32 v51, v58, v59
	global_store_dwordx4 v[60:61], v[48:51], off offset:256
	v_cvt_f32_f16_e32 v52, v94
	v_cvt_f32_f16_sdwa v53, v94 dst_sel:DWORD dst_unused:UNUSED_PAD src0_sel:WORD_1
	v_cvt_f32_f16_e32 v48, v92
	v_cvt_f32_f16_sdwa v49, v92 dst_sel:DWORD dst_unused:UNUSED_PAD src0_sel:WORD_1
	v_cvt_f32_f16_e32 v50, v93
	v_cvt_f32_f16_sdwa v51, v93 dst_sel:DWORD dst_unused:UNUSED_PAD src0_sel:WORD_1
	v_cvt_f32_f16_e32 v54, v95
	v_cvt_f32_f16_sdwa v55, v95 dst_sel:DWORD dst_unused:UNUSED_PAD src0_sel:WORD_1
	v_sub_f32_e32 v49, v49, v116
	v_sub_f32_e32 v48, v48, v116
	v_sub_f32_e32 v51, v51, v116
	v_sub_f32_e32 v50, v50, v116
	v_pk_mul_f32 v[50:51], v[116:117], v[50:51] op_sel:[1,0]
	v_pk_mul_f32 v[48:49], v[116:117], v[48:49] op_sel:[1,0]
	v_pk_fma_f32 v[50:51], v[204:205], v[50:51], v[216:217]
	v_pk_fma_f32 v[48:49], v[206:207], v[48:49], v[218:219]
	v_pk_fma_f32 v[46:47], v[46:47], v[130:131], v[50:51]
	v_pk_fma_f32 v[44:45], v[44:45], v[128:129], v[48:49]
	v_sub_f32_e32 v49, v53, v116
	v_sub_f32_e32 v48, v52, v116
	v_sub_f32_e32 v51, v55, v116
	v_sub_f32_e32 v50, v54, v116
	v_pk_mul_f32 v[50:51], v[116:117], v[50:51] op_sel:[1,0]
	v_pk_mul_f32 v[48:49], v[116:117], v[48:49] op_sel:[1,0]
	v_pk_fma_f32 v[50:51], v[208:209], v[50:51], v[212:213]
	v_pk_fma_f32 v[48:49], v[210:211], v[48:49], v[214:215]
	v_pk_fma_f32 v[50:51], v[42:43], v[114:115], v[50:51]
	v_pk_fma_f32 v[42:43], v[40:41], v[112:113], v[48:49]
	v_cvt_pk_f16_f32 v40, v44, v45
	v_lshl_add_u64 v[44:45], s[16:17], 0, v[118:119]
	v_cvt_pk_f16_f32 v41, v46, v47
	v_cvt_pk_f16_f32 v42, v42, v43
	v_cvt_pk_f16_f32 v43, v50, v51
	v_lshl_add_u64 v[44:45], v[44:45], 0, v[220:221]
	global_store_dwordx4 v[44:45], v[40:43], off
	v_cvt_f32_f16_e32 v46, v98
	v_cvt_f32_f16_sdwa v47, v98 dst_sel:DWORD dst_unused:UNUSED_PAD src0_sel:WORD_1
	v_cvt_f32_f16_e32 v40, v96
	v_cvt_f32_f16_sdwa v41, v96 dst_sel:DWORD dst_unused:UNUSED_PAD src0_sel:WORD_1
	v_cvt_f32_f16_e32 v42, v97
	v_cvt_f32_f16_sdwa v43, v97 dst_sel:DWORD dst_unused:UNUSED_PAD src0_sel:WORD_1
	v_cvt_f32_f16_e32 v48, v99
	v_cvt_f32_f16_sdwa v49, v99 dst_sel:DWORD dst_unused:UNUSED_PAD src0_sel:WORD_1
	v_sub_f32_e32 v41, v41, v116
	v_sub_f32_e32 v40, v40, v116
	v_sub_f32_e32 v43, v43, v116
	v_sub_f32_e32 v42, v42, v116
	v_pk_mul_f32 v[42:43], v[116:117], v[42:43] op_sel:[1,0]
	v_pk_mul_f32 v[40:41], v[116:117], v[40:41] op_sel:[1,0]
	v_pk_fma_f32 v[42:43], v[196:197], v[42:43], v[200:201]
	v_pk_fma_f32 v[40:41], v[198:199], v[40:41], v[202:203]
	v_pk_fma_f32 v[38:39], v[38:39], v[126:127], v[42:43]
; #define PG8_WAIT_V(n) asm volatile("s_waitcnt vmcnt(" #n ")" ::: "memory")
; #define PG8_BAR __builtin_amdgcn_s_barrier()
; template <class Epi, class Sched>
; __device__ __forceinline__ void gemm_phase(PG8_LAS unsigned char* lds, const Gemm g, const Sched& S, const Epi& E) {
;     ...
;         cur = nxt; cA = nA; cB = nB; ++ui;
;     }
;     PG8_WAIT_V(0);
;     if (wr == 0) PG8_BAR;
;     PG8_BAR;
;     __device__ __forceinline__ void operator()(const AccT& acc, const pg8::Unit& u, int wr, int wc, int fr, int fq) const {
;     ...
;             for (int m = 0; m < 4; ++m) { const int row = row0 + ai * 128 + m * 16; const size_t off = (size_t)row * D + col0; const f32x2 st = stv[m];
; #pragma unroll
;                 for (int bj = 0; bj < 2; ++bj) { float uf[8]; unpack_h8(uraw[m][bj], uf);
;                     const f32x4 ua = {uf[0], uf[1], uf[2], uf[3]}, ub = {uf[4], uf[5], uf[6], uf[7]};
;                     const f32x4 a = ((ua - st.x) * st.y) * lg[bj][0] + lbv[bj][0] + gv[bj][0] * acc[ai][bj][m][0], b = ((ub - st.x) * st.y) * lg[bj][1] + lbv[bj][1] + gv[bj][1] * acc[ai][bj][m][1];
;                     u32x4 w; w.x = pk_h2(a[0], a[1]); w.y = pk_h2(a[2], a[3]); w.z = pk_h2(b[0], b[1]); w.w = pk_h2(b[2], b[3]);
;                     *(u32x4*)(U2 + off + bj * 128) = w; } }
;         }
	v_pk_fma_f32 v[36:37], v[36:37], v[124:125], v[40:41]
	v_sub_f32_e32 v41, v47, v116
	v_sub_f32_e32 v40, v46, v116
	v_sub_f32_e32 v43, v49, v116
	v_sub_f32_e32 v42, v48, v116
	v_pk_mul_f32 v[42:43], v[116:117], v[42:43] op_sel:[1,0]
	v_pk_mul_f32 v[40:41], v[116:117], v[40:41] op_sel:[1,0]
	v_pk_fma_f32 v[42:43], v[188:189], v[42:43], v[192:193]
	v_pk_fma_f32 v[40:41], v[190:191], v[40:41], v[194:195]
	v_pk_fma_f32 v[42:43], v[34:35], v[110:111], v[42:43]
	v_pk_fma_f32 v[34:35], v[32:33], v[108:109], v[40:41]
	v_cvt_pk_f16_f32 v32, v36, v37
	v_cvt_pk_f16_f32 v33, v38, v39
	v_cvt_pk_f16_f32 v34, v34, v35
	v_cvt_pk_f16_f32 v35, v42, v43
	global_store_dwordx4 v[44:45], v[32:35], off offset:256
	v_cvt_f32_f16_e32 v36, v102
	v_cvt_f32_f16_sdwa v37, v102 dst_sel:DWORD dst_unused:UNUSED_PAD src0_sel:WORD_1
	v_cvt_f32_f16_e32 v32, v100
	v_cvt_f32_f16_sdwa v33, v100 dst_sel:DWORD dst_unused:UNUSED_PAD src0_sel:WORD_1
	v_cvt_f32_f16_e32 v34, v101
	v_cvt_f32_f16_sdwa v35, v101 dst_sel:DWORD dst_unused:UNUSED_PAD src0_sel:WORD_1
	v_cvt_f32_f16_e32 v38, v103
	v_cvt_f32_f16_sdwa v39, v103 dst_sel:DWORD dst_unused:UNUSED_PAD src0_sel:WORD_1
	v_sub_f32_e32 v33, v33, v80
	v_sub_f32_e32 v32, v32, v80
	v_sub_f32_e32 v35, v35, v80
	v_sub_f32_e32 v34, v34, v80
	v_pk_mul_f32 v[34:35], v[80:81], v[34:35] op_sel:[1,0]
	v_pk_mul_f32 v[32:33], v[80:81], v[32:33] op_sel:[1,0]
	v_pk_fma_f32 v[34:35], v[204:205], v[34:35], v[216:217]
	v_pk_fma_f32 v[32:33], v[206:207], v[32:33], v[218:219]
	v_pk_fma_f32 v[30:31], v[30:31], v[130:131], v[34:35]
	v_pk_fma_f32 v[28:29], v[28:29], v[128:129], v[32:33]
	v_sub_f32_e32 v33, v37, v80
	v_sub_f32_e32 v32, v36, v80
	v_sub_f32_e32 v35, v39, v80
	v_sub_f32_e32 v34, v38, v80
	v_pk_mul_f32 v[34:35], v[80:81], v[34:35] op_sel:[1,0]
	v_pk_mul_f32 v[32:33], v[80:81], v[32:33] op_sel:[1,0]
	v_pk_fma_f32 v[34:35], v[208:209], v[34:35], v[212:213]
	v_pk_fma_f32 v[32:33], v[210:211], v[32:33], v[214:215]
	v_pk_fma_f32 v[34:35], v[26:27], v[114:115], v[34:35]
	v_pk_fma_f32 v[26:27], v[24:25], v[112:113], v[32:33]
	v_cvt_pk_f16_f32 v24, v28, v29
	v_lshl_add_u64 v[28:29], s[16:17], 0, v[82:83]
	v_cvt_pk_f16_f32 v25, v30, v31
	v_cvt_pk_f16_f32 v26, v26, v27
	v_cvt_pk_f16_f32 v27, v34, v35
	v_lshl_add_u64 v[28:29], v[28:29], 0, v[220:221]
	global_store_dwordx4 v[28:29], v[24:27], off
	v_cvt_f32_f16_e32 v30, v74
	v_cvt_f32_f16_sdwa v31, v74 dst_sel:DWORD dst_unused:UNUSED_PAD src0_sel:WORD_1
	v_cvt_f32_f16_e32 v24, v72
	v_cvt_f32_f16_sdwa v25, v72 dst_sel:DWORD dst_unused:UNUSED_PAD src0_sel:WORD_1
	v_cvt_f32_f16_e32 v26, v73
	v_cvt_f32_f16_sdwa v27, v73 dst_sel:DWORD dst_unused:UNUSED_PAD src0_sel:WORD_1
	v_cvt_f32_f16_e32 v32, v75
	v_cvt_f32_f16_sdwa v33, v75 dst_sel:DWORD dst_unused:UNUSED_PAD src0_sel:WORD_1
	v_sub_f32_e32 v25, v25, v80
	v_sub_f32_e32 v24, v24, v80
	v_sub_f32_e32 v27, v27, v80
	v_sub_f32_e32 v26, v26, v80
	v_pk_mul_f32 v[26:27], v[80:81], v[26:27] op_sel:[1,0]
	v_pk_mul_f32 v[24:25], v[80:81], v[24:25] op_sel:[1,0]
	v_pk_fma_f32 v[26:27], v[196:197], v[26:27], v[200:201]
	v_pk_fma_f32 v[24:25], v[198:199], v[24:25], v[202:203]
	v_pk_fma_f32 v[22:23], v[22:23], v[126:127], v[26:27]
	v_pk_fma_f32 v[20:21], v[20:21], v[124:125], v[24:25]
	v_sub_f32_e32 v25, v31, v80
	v_sub_f32_e32 v24, v30, v80
	v_sub_f32_e32 v27, v33, v80
	v_sub_f32_e32 v26, v32, v80
	v_pk_mul_f32 v[26:27], v[80:81], v[26:27] op_sel:[1,0]
	v_pk_mul_f32 v[24:25], v[80:81], v[24:25] op_sel:[1,0]
	v_pk_fma_f32 v[26:27], v[188:189], v[26:27], v[192:193]
	v_pk_fma_f32 v[24:25], v[190:191], v[24:25], v[194:195]
	v_pk_fma_f32 v[26:27], v[18:19], v[110:111], v[26:27]
	v_pk_fma_f32 v[18:19], v[16:17], v[108:109], v[24:25]
	v_cvt_pk_f16_f32 v16, v20, v21
	v_cvt_pk_f16_f32 v17, v22, v23
	v_cvt_pk_f16_f32 v18, v18, v19
	v_cvt_pk_f16_f32 v19, v26, v27
	global_store_dwordx4 v[28:29], v[16:19], off offset:256
	v_cvt_f32_f16_e32 v20, v70
	v_cvt_f32_f16_sdwa v21, v70 dst_sel:DWORD dst_unused:UNUSED_PAD src0_sel:WORD_1
	v_cvt_f32_f16_e32 v16, v68
	v_cvt_f32_f16_sdwa v17, v68 dst_sel:DWORD dst_unused:UNUSED_PAD src0_sel:WORD_1
	v_cvt_f32_f16_e32 v18, v69
	v_cvt_f32_f16_sdwa v19, v69 dst_sel:DWORD dst_unused:UNUSED_PAD src0_sel:WORD_1
	v_cvt_f32_f16_e32 v22, v71
	v_cvt_f32_f16_sdwa v23, v71 dst_sel:DWORD dst_unused:UNUSED_PAD src0_sel:WORD_1
	v_sub_f32_e32 v17, v17, v76
	v_sub_f32_e32 v16, v16, v76
	v_sub_f32_e32 v19, v19, v76
	v_sub_f32_e32 v18, v18, v76
	v_pk_mul_f32 v[18:19], v[76:77], v[18:19] op_sel:[1,0]
	v_pk_mul_f32 v[16:17], v[76:77], v[16:17] op_sel:[1,0]
	v_pk_fma_f32 v[18:19], v[204:205], v[18:19], v[216:217]
	v_pk_fma_f32 v[16:17], v[206:207], v[16:17], v[218:219]
	v_pk_fma_f32 v[14:15], v[14:15], v[130:131], v[18:19]
	v_pk_fma_f32 v[12:13], v[12:13], v[128:129], v[16:17]
	v_sub_f32_e32 v17, v21, v76
	v_sub_f32_e32 v16, v20, v76
	v_sub_f32_e32 v19, v23, v76
	v_sub_f32_e32 v18, v22, v76
	v_pk_mul_f32 v[18:19], v[76:77], v[18:19] op_sel:[1,0]
	v_pk_mul_f32 v[16:17], v[76:77], v[16:17] op_sel:[1,0]
	v_pk_fma_f32 v[18:19], v[208:209], v[18:19], v[212:213]
	v_pk_fma_f32 v[16:17], v[210:211], v[16:17], v[214:215]
	v_pk_fma_f32 v[18:19], v[10:11], v[114:115], v[18:19]
	v_pk_fma_f32 v[10:11], v[8:9], v[112:113], v[16:17]
	v_cvt_pk_f16_f32 v8, v12, v13
	v_lshl_add_u64 v[12:13], s[16:17], 0, v[78:79]
	v_cvt_pk_f16_f32 v9, v14, v15
	v_cvt_pk_f16_f32 v10, v10, v11
	v_cvt_pk_f16_f32 v11, v18, v19
	v_lshl_add_u64 v[12:13], v[12:13], 0, v[220:221]
	global_store_dwordx4 v[12:13], v[8:11], off
	v_cvt_f32_f16_e32 v14, v66
	v_cvt_f32_f16_sdwa v15, v66 dst_sel:DWORD dst_unused:UNUSED_PAD src0_sel:WORD_1
	v_cvt_f32_f16_e32 v8, v64
	v_cvt_f32_f16_sdwa v9, v64 dst_sel:DWORD dst_unused:UNUSED_PAD src0_sel:WORD_1
	v_cvt_f32_f16_e32 v10, v65
	v_cvt_f32_f16_sdwa v11, v65 dst_sel:DWORD dst_unused:UNUSED_PAD src0_sel:WORD_1
	v_cvt_f32_f16_e32 v16, v67
	v_cvt_f32_f16_sdwa v17, v67 dst_sel:DWORD dst_unused:UNUSED_PAD src0_sel:WORD_1
	v_sub_f32_e32 v9, v9, v76
	v_sub_f32_e32 v8, v8, v76
	v_sub_f32_e32 v11, v11, v76
	v_sub_f32_e32 v10, v10, v76
	v_pk_mul_f32 v[10:11], v[76:77], v[10:11] op_sel:[1,0]
	v_pk_mul_f32 v[8:9], v[76:77], v[8:9] op_sel:[1,0]
	v_pk_fma_f32 v[10:11], v[196:197], v[10:11], v[200:201]
	v_pk_fma_f32 v[8:9], v[198:199], v[8:9], v[202:203]
	v_pk_fma_f32 v[6:7], v[6:7], v[126:127], v[10:11]
	v_pk_fma_f32 v[4:5], v[4:5], v[124:125], v[8:9]
	v_sub_f32_e32 v9, v15, v76
	v_sub_f32_e32 v8, v14, v76
	v_sub_f32_e32 v11, v17, v76
	v_sub_f32_e32 v10, v16, v76
	v_pk_mul_f32 v[10:11], v[76:77], v[10:11] op_sel:[1,0]
	v_pk_mul_f32 v[8:9], v[76:77], v[8:9] op_sel:[1,0]
	v_pk_fma_f32 v[10:11], v[188:189], v[10:11], v[192:193]
	v_pk_fma_f32 v[8:9], v[190:191], v[8:9], v[194:195]
	v_pk_fma_f32 v[10:11], v[2:3], v[110:111], v[10:11]
	v_pk_fma_f32 v[2:3], v[0:1], v[108:109], v[8:9]
	v_cvt_pk_f16_f32 v0, v4, v5
	v_cvt_pk_f16_f32 v1, v6, v7
	v_cvt_pk_f16_f32 v2, v2, v3
	v_cvt_pk_f16_f32 v3, v10, v11
	global_store_dwordx4 v[12:13], v[0:3], off offset:256
	s_cbranch_vccz .LBB0_871
	s_waitcnt vmcnt(0)
	s_cmpk_gt_u32 s21, 0xff
	s_cbranch_scc1 .LBB0_886
	s_barrier
